# v25 plus: in every K-loop MFMA block the s_setprio 1 is issued before the opening barrier and the s_setprio 0 after the closing barrier (the barrier-bounded segment starts and ends with MFMAs)
# baseline (speedup 1.0000x reference)
.LBB0_131:
	s_add_u32 s60, s57, 0xffffff80
	s_addc_u32 s61, s58, -1
	s_cmp_eq_u32 s59, 60
	s_cselect_b32 s36, s17, s57
	s_cselect_b32 s37, s7, s58
	s_cselect_b32 s39, s21, s56
	s_cselect_b32 s38, s33, s55
	s_add_u32 s30, s36, 0x80
	s_addc_u32 s31, s37, 0
	s_add_u32 s34, s38, 0x80
	s_addc_u32 s35, s39, 0
	s_add_i32 s62, 0, 0x10000
	s_add_i32 s63, 0, 0x14000
	v_add_u32_e32 v152, s62, v1
	v_add_u32_e32 v168, s63, v1
	ds_read_b128 v[140:143], v152
	ds_read_b128 v[144:147], v152 offset:1024
	ds_read_b128 v[148:151], v152 offset:2048
	ds_read_b128 v[152:155], v152 offset:3072
	ds_read_b128 v[156:159], v168
	ds_read_b128 v[160:163], v168 offset:1024
	ds_read_b128 v[164:167], v168 offset:2048
	ds_read_b128 v[168:171], v168 offset:3072
	s_add_u32 s60, s60, 0x100000
	s_addc_u32 s61, s61, 0
	v_lshl_add_u64 v[204:205], s[60:61], 0, v[2:3]
	s_add_i32 m0, s29, 0xc000
	ds_read_b128 v[172:175], v5
	ds_read_b128 v[176:179], v5 offset:1024
	ds_read_b128 v[180:183], v5 offset:2048
	ds_read_b128 v[184:187], v5 offset:3072
	ds_read_b128 v[188:191], v5 offset:4096
	ds_read_b128 v[192:195], v5 offset:5120
	ds_read_b128 v[196:199], v5 offset:6144
	ds_read_b128 v[200:203], v5 offset:7168
	global_load_lds_dwordx4 v[204:205], off
	v_lshl_add_u64 v[204:205], s[60:61], 0, v[136:137]
	s_add_i32 m0, s29, 0xe000
	s_nop 0
	global_load_lds_dwordx4 v[204:205], off
	s_waitcnt vmcnt(8)
	s_waitcnt lgkmcnt(0)
	s_setprio 1
	s_barrier
	v_mfma_f32_16x16x32_bf16 v[130:133], v[140:143], v[172:175], v[130:133]
	v_mfma_f32_16x16x32_bf16 v[126:129], v[148:151], v[172:175], v[126:129]
	v_mfma_f32_16x16x32_bf16 v[114:117], v[140:143], v[180:183], v[114:117]
	v_mfma_f32_16x16x32_bf16 v[110:113], v[148:151], v[180:183], v[110:113]
	v_mfma_f32_16x16x32_bf16 v[98:101], v[140:143], v[188:191], v[98:101]
	v_mfma_f32_16x16x32_bf16 v[94:97], v[148:151], v[188:191], v[94:97]
	v_mfma_f32_16x16x32_bf16 v[82:85], v[140:143], v[196:199], v[82:85]
	v_mfma_f32_16x16x32_bf16 v[78:81], v[148:151], v[196:199], v[78:81]
	v_mfma_f32_16x16x32_bf16 v[130:133], v[144:147], v[176:179], v[130:133]
	v_mfma_f32_16x16x32_bf16 v[126:129], v[152:155], v[176:179], v[126:129]
	v_mfma_f32_16x16x32_bf16 v[114:117], v[144:147], v[184:187], v[114:117]
	v_mfma_f32_16x16x32_bf16 v[110:113], v[152:155], v[184:187], v[110:113]
	v_mfma_f32_16x16x32_bf16 v[98:101], v[144:147], v[192:195], v[98:101]
	v_mfma_f32_16x16x32_bf16 v[94:97], v[152:155], v[192:195], v[94:97]
	v_mfma_f32_16x16x32_bf16 v[82:85], v[144:147], v[200:203], v[82:85]
	v_mfma_f32_16x16x32_bf16 v[78:81], v[152:155], v[200:203], v[78:81]
	s_setprio 0
	s_setprio 1
	v_mfma_f32_16x16x32_bf16 v[122:125], v[156:159], v[172:175], v[122:125]
	v_mfma_f32_16x16x32_bf16 v[118:121], v[164:167], v[172:175], v[118:121]
	v_mfma_f32_16x16x32_bf16 v[106:109], v[156:159], v[180:183], v[106:109]
	v_mfma_f32_16x16x32_bf16 v[102:105], v[164:167], v[180:183], v[102:105]
	v_mfma_f32_16x16x32_bf16 v[90:93], v[156:159], v[188:191], v[90:93]
	v_mfma_f32_16x16x32_bf16 v[86:89], v[164:167], v[188:191], v[86:89]
	v_mfma_f32_16x16x32_bf16 v[74:77], v[156:159], v[196:199], v[74:77]
	v_mfma_f32_16x16x32_bf16 v[70:73], v[164:167], v[196:199], v[70:73]
	v_mfma_f32_16x16x32_bf16 v[122:125], v[160:163], v[176:179], v[122:125]
	v_mfma_f32_16x16x32_bf16 v[118:121], v[168:171], v[176:179], v[118:121]
	v_mfma_f32_16x16x32_bf16 v[106:109], v[160:163], v[184:187], v[106:109]
	v_mfma_f32_16x16x32_bf16 v[102:105], v[168:171], v[184:187], v[102:105]
	v_mfma_f32_16x16x32_bf16 v[90:93], v[160:163], v[192:195], v[90:93]
	v_mfma_f32_16x16x32_bf16 v[86:89], v[168:171], v[192:195], v[86:89]
	v_mfma_f32_16x16x32_bf16 v[74:77], v[160:163], v[200:203], v[74:77]
	v_mfma_f32_16x16x32_bf16 v[70:73], v[168:171], v[200:203], v[70:73]
	s_barrier
	s_setprio 0
	s_add_i32 s60, s62, s42
	v_lshl_add_u64 v[204:205], s[38:39], 0, v[134:135]
	s_mov_b32 m0, s60
	ds_read_b128 v[172:175], v5 offset:16384
	ds_read_b128 v[176:179], v5 offset:17408
	ds_read_b128 v[180:183], v5 offset:18432
	ds_read_b128 v[184:187], v5 offset:19456
	ds_read_b128 v[188:191], v5 offset:20480
	ds_read_b128 v[192:195], v5 offset:21504
	ds_read_b128 v[196:199], v5 offset:22528
	ds_read_b128 v[200:203], v5 offset:23552
	global_load_lds_dwordx4 v[204:205], off
	s_add_i32 m0, s60, 0x2000
	v_lshl_add_u64 v[204:205], s[38:39], 0, v[138:139]
	s_add_u32 s38, s38, 0x100000
	s_addc_u32 s39, s39, 0
	s_add_i32 s60, s63, s42
	global_load_lds_dwordx4 v[204:205], off
	v_lshl_add_u64 v[204:205], s[38:39], 0, v[134:135]
	s_mov_b32 m0, s60
	s_nop 0
	global_load_lds_dwordx4 v[204:205], off
	v_lshl_add_u64 v[204:205], s[38:39], 0, v[138:139]
	s_add_i32 m0, s60, 0x2000
	s_nop 0
	global_load_lds_dwordx4 v[204:205], off
	v_lshl_add_u64 v[204:205], s[36:37], 0, v[2:3]
	s_mov_b32 m0, s29
	s_nop 0
	global_load_lds_dwordx4 v[204:205], off
	v_lshl_add_u64 v[204:205], s[36:37], 0, v[136:137]
	s_mov_b32 m0, s43
	s_nop 0
	global_load_lds_dwordx4 v[204:205], off
	s_waitcnt vmcnt(8)
	s_waitcnt lgkmcnt(0)
	s_setprio 1
	s_barrier
	v_mfma_f32_16x16x32_bf16 v[66:69], v[140:143], v[172:175], v[66:69]
	v_mfma_f32_16x16x32_bf16 v[62:65], v[148:151], v[172:175], v[62:65]
	v_mfma_f32_16x16x32_bf16 v[50:53], v[140:143], v[180:183], v[50:53]
	v_mfma_f32_16x16x32_bf16 v[46:49], v[148:151], v[180:183], v[46:49]
	v_mfma_f32_16x16x32_bf16 v[34:37], v[140:143], v[188:191], v[34:37]
	v_mfma_f32_16x16x32_bf16 v[30:33], v[148:151], v[188:191], v[30:33]
	v_mfma_f32_16x16x32_bf16 v[18:21], v[140:143], v[196:199], v[18:21]
	v_mfma_f32_16x16x32_bf16 v[14:17], v[148:151], v[196:199], v[14:17]
	v_mfma_f32_16x16x32_bf16 v[66:69], v[144:147], v[176:179], v[66:69]
	v_mfma_f32_16x16x32_bf16 v[62:65], v[152:155], v[176:179], v[62:65]
	v_mfma_f32_16x16x32_bf16 v[50:53], v[144:147], v[184:187], v[50:53]
	v_mfma_f32_16x16x32_bf16 v[46:49], v[152:155], v[184:187], v[46:49]
	v_mfma_f32_16x16x32_bf16 v[34:37], v[144:147], v[192:195], v[34:37]
	v_mfma_f32_16x16x32_bf16 v[30:33], v[152:155], v[192:195], v[30:33]
	v_mfma_f32_16x16x32_bf16 v[18:21], v[144:147], v[200:203], v[18:21]
	v_mfma_f32_16x16x32_bf16 v[14:17], v[152:155], v[200:203], v[14:17]
	s_setprio 0
	s_setprio 1
	v_mfma_f32_16x16x32_bf16 v[58:61], v[156:159], v[172:175], v[58:61]
	v_mfma_f32_16x16x32_bf16 v[54:57], v[164:167], v[172:175], v[54:57]
	v_mfma_f32_16x16x32_bf16 v[42:45], v[156:159], v[180:183], v[42:45]
	v_mfma_f32_16x16x32_bf16 v[38:41], v[164:167], v[180:183], v[38:41]
	v_mfma_f32_16x16x32_bf16 v[26:29], v[156:159], v[188:191], v[26:29]
	v_mfma_f32_16x16x32_bf16 v[22:25], v[164:167], v[188:191], v[22:25]
	v_mfma_f32_16x16x32_bf16 v[10:13], v[156:159], v[196:199], v[10:13]
	v_mfma_f32_16x16x32_bf16 v[6:9], v[164:167], v[196:199], v[6:9]
	v_mfma_f32_16x16x32_bf16 v[58:61], v[160:163], v[176:179], v[58:61]
	v_mfma_f32_16x16x32_bf16 v[54:57], v[168:171], v[176:179], v[54:57]
	v_mfma_f32_16x16x32_bf16 v[42:45], v[160:163], v[184:187], v[42:45]
	v_mfma_f32_16x16x32_bf16 v[38:41], v[168:171], v[184:187], v[38:41]
	v_mfma_f32_16x16x32_bf16 v[26:29], v[160:163], v[192:195], v[26:29]
	v_mfma_f32_16x16x32_bf16 v[22:25], v[168:171], v[192:195], v[22:25]
	v_mfma_f32_16x16x32_bf16 v[10:13], v[160:163], v[200:203], v[10:13]
	v_mfma_f32_16x16x32_bf16 v[6:9], v[168:171], v[200:203], v[6:9]
	s_barrier
	s_setprio 0
	s_add_i32 s38, 0, 0x18000
	s_add_i32 s39, 0, 0x1c000
	v_add_u32_e32 v152, s38, v1
	v_add_u32_e32 v168, s39, v1
	ds_read_b128 v[140:143], v152
	ds_read_b128 v[144:147], v152 offset:1024
	ds_read_b128 v[148:151], v152 offset:2048
	ds_read_b128 v[152:155], v152 offset:3072
	ds_read_b128 v[156:159], v168
	ds_read_b128 v[160:163], v168 offset:1024
	ds_read_b128 v[164:167], v168 offset:2048
	ds_read_b128 v[168:171], v168 offset:3072
	s_add_u32 s36, s36, 0x100000
	s_addc_u32 s37, s37, 0
	s_mov_b32 m0, s48
	v_lshl_add_u64 v[204:205], s[36:37], 0, v[2:3]
	ds_read_b128 v[172:175], v5 offset:32768
	ds_read_b128 v[176:179], v5 offset:33792
	ds_read_b128 v[180:183], v5 offset:34816
	ds_read_b128 v[184:187], v5 offset:35840
	ds_read_b128 v[188:191], v5 offset:36864
	ds_read_b128 v[192:195], v5 offset:37888
	ds_read_b128 v[196:199], v5 offset:38912
	ds_read_b128 v[200:203], v5 offset:39936
	global_load_lds_dwordx4 v[204:205], off
	v_lshl_add_u64 v[204:205], s[36:37], 0, v[136:137]
	s_mov_b32 m0, s49
	s_nop 0
	global_load_lds_dwordx4 v[204:205], off
	s_waitcnt vmcnt(8)
	s_waitcnt lgkmcnt(0)
	s_setprio 1
	s_barrier
	v_mfma_f32_16x16x32_bf16 v[130:133], v[140:143], v[172:175], v[130:133]
	v_mfma_f32_16x16x32_bf16 v[126:129], v[148:151], v[172:175], v[126:129]
	v_mfma_f32_16x16x32_bf16 v[114:117], v[140:143], v[180:183], v[114:117]
	v_mfma_f32_16x16x32_bf16 v[110:113], v[148:151], v[180:183], v[110:113]
	v_mfma_f32_16x16x32_bf16 v[98:101], v[140:143], v[188:191], v[98:101]
	v_mfma_f32_16x16x32_bf16 v[94:97], v[148:151], v[188:191], v[94:97]
	v_mfma_f32_16x16x32_bf16 v[82:85], v[140:143], v[196:199], v[82:85]
	v_mfma_f32_16x16x32_bf16 v[78:81], v[148:151], v[196:199], v[78:81]
	v_mfma_f32_16x16x32_bf16 v[130:133], v[144:147], v[176:179], v[130:133]
	v_mfma_f32_16x16x32_bf16 v[126:129], v[152:155], v[176:179], v[126:129]
	v_mfma_f32_16x16x32_bf16 v[114:117], v[144:147], v[184:187], v[114:117]
	v_mfma_f32_16x16x32_bf16 v[110:113], v[152:155], v[184:187], v[110:113]
	v_mfma_f32_16x16x32_bf16 v[98:101], v[144:147], v[192:195], v[98:101]
	v_mfma_f32_16x16x32_bf16 v[94:97], v[152:155], v[192:195], v[94:97]
	v_mfma_f32_16x16x32_bf16 v[82:85], v[144:147], v[200:203], v[82:85]
	v_mfma_f32_16x16x32_bf16 v[78:81], v[152:155], v[200:203], v[78:81]
	s_setprio 0
	s_setprio 1
	v_mfma_f32_16x16x32_bf16 v[122:125], v[156:159], v[172:175], v[122:125]
	v_mfma_f32_16x16x32_bf16 v[118:121], v[164:167], v[172:175], v[118:121]
	v_mfma_f32_16x16x32_bf16 v[106:109], v[156:159], v[180:183], v[106:109]
	v_mfma_f32_16x16x32_bf16 v[102:105], v[164:167], v[180:183], v[102:105]
	v_mfma_f32_16x16x32_bf16 v[90:93], v[156:159], v[188:191], v[90:93]
	v_mfma_f32_16x16x32_bf16 v[86:89], v[164:167], v[188:191], v[86:89]
	v_mfma_f32_16x16x32_bf16 v[74:77], v[156:159], v[196:199], v[74:77]
	v_mfma_f32_16x16x32_bf16 v[70:73], v[164:167], v[196:199], v[70:73]
	v_mfma_f32_16x16x32_bf16 v[122:125], v[160:163], v[176:179], v[122:125]
	v_mfma_f32_16x16x32_bf16 v[118:121], v[168:171], v[176:179], v[118:121]
	v_mfma_f32_16x16x32_bf16 v[106:109], v[160:163], v[184:187], v[106:109]
	v_mfma_f32_16x16x32_bf16 v[102:105], v[168:171], v[184:187], v[102:105]
	v_mfma_f32_16x16x32_bf16 v[90:93], v[160:163], v[192:195], v[90:93]
	v_mfma_f32_16x16x32_bf16 v[86:89], v[168:171], v[192:195], v[86:89]
	v_mfma_f32_16x16x32_bf16 v[74:77], v[160:163], v[200:203], v[74:77]
	v_mfma_f32_16x16x32_bf16 v[70:73], v[168:171], v[200:203], v[70:73]
	s_barrier
	s_setprio 0
	s_add_i32 s36, s38, s42
	v_lshl_add_u64 v[204:205], s[34:35], 0, v[134:135]
	s_mov_b32 m0, s36
	ds_read_b128 v[172:175], v5 offset:49152
	ds_read_b128 v[176:179], v5 offset:50176
	ds_read_b128 v[180:183], v5 offset:51200
	ds_read_b128 v[184:187], v5 offset:52224
	ds_read_b128 v[188:191], v5 offset:53248
	ds_read_b128 v[192:195], v5 offset:54272
	ds_read_b128 v[196:199], v5 offset:55296
	ds_read_b128 v[200:203], v5 offset:56320
	global_load_lds_dwordx4 v[204:205], off
	s_add_i32 m0, s36, 0x2000
	v_lshl_add_u64 v[204:205], s[34:35], 0, v[138:139]
	s_add_u32 s34, s34, 0x100000
	s_addc_u32 s35, s35, 0
	s_add_i32 s36, s39, s42
	global_load_lds_dwordx4 v[204:205], off
	v_lshl_add_u64 v[204:205], s[34:35], 0, v[134:135]
	s_mov_b32 m0, s36
	s_nop 0
	global_load_lds_dwordx4 v[204:205], off
	v_lshl_add_u64 v[204:205], s[34:35], 0, v[138:139]
	s_add_i32 m0, s36, 0x2000
	s_nop 0
	global_load_lds_dwordx4 v[204:205], off
	v_lshl_add_u64 v[204:205], s[30:31], 0, v[2:3]
	s_mov_b32 m0, s52
	s_nop 0
	global_load_lds_dwordx4 v[204:205], off
	v_lshl_add_u64 v[204:205], s[30:31], 0, v[136:137]
	s_mov_b32 m0, s53
	s_nop 0
	global_load_lds_dwordx4 v[204:205], off
	s_waitcnt vmcnt(8)
	s_waitcnt lgkmcnt(0)
	s_setprio 1
	s_barrier
	v_mfma_f32_16x16x32_bf16 v[66:69], v[140:143], v[172:175], v[66:69]
	v_mfma_f32_16x16x32_bf16 v[62:65], v[148:151], v[172:175], v[62:65]
	v_mfma_f32_16x16x32_bf16 v[50:53], v[140:143], v[180:183], v[50:53]
	v_mfma_f32_16x16x32_bf16 v[46:49], v[148:151], v[180:183], v[46:49]
	v_mfma_f32_16x16x32_bf16 v[34:37], v[140:143], v[188:191], v[34:37]
	v_mfma_f32_16x16x32_bf16 v[30:33], v[148:151], v[188:191], v[30:33]
	v_mfma_f32_16x16x32_bf16 v[18:21], v[140:143], v[196:199], v[18:21]
	v_mfma_f32_16x16x32_bf16 v[14:17], v[148:151], v[196:199], v[14:17]
	v_mfma_f32_16x16x32_bf16 v[66:69], v[144:147], v[176:179], v[66:69]
	v_mfma_f32_16x16x32_bf16 v[62:65], v[152:155], v[176:179], v[62:65]
	v_mfma_f32_16x16x32_bf16 v[50:53], v[144:147], v[184:187], v[50:53]
	v_mfma_f32_16x16x32_bf16 v[46:49], v[152:155], v[184:187], v[46:49]
	v_mfma_f32_16x16x32_bf16 v[34:37], v[144:147], v[192:195], v[34:37]
	v_mfma_f32_16x16x32_bf16 v[30:33], v[152:155], v[192:195], v[30:33]
	v_mfma_f32_16x16x32_bf16 v[18:21], v[144:147], v[200:203], v[18:21]
	v_mfma_f32_16x16x32_bf16 v[14:17], v[152:155], v[200:203], v[14:17]
	s_setprio 0
	s_setprio 1
	v_mfma_f32_16x16x32_bf16 v[58:61], v[156:159], v[172:175], v[58:61]
	v_mfma_f32_16x16x32_bf16 v[54:57], v[164:167], v[172:175], v[54:57]
	v_mfma_f32_16x16x32_bf16 v[42:45], v[156:159], v[180:183], v[42:45]
	v_mfma_f32_16x16x32_bf16 v[38:41], v[164:167], v[180:183], v[38:41]
	v_mfma_f32_16x16x32_bf16 v[26:29], v[156:159], v[188:191], v[26:29]
	v_mfma_f32_16x16x32_bf16 v[22:25], v[164:167], v[188:191], v[22:25]
	v_mfma_f32_16x16x32_bf16 v[10:13], v[156:159], v[196:199], v[10:13]
	v_mfma_f32_16x16x32_bf16 v[6:9], v[164:167], v[196:199], v[6:9]
	v_mfma_f32_16x16x32_bf16 v[58:61], v[160:163], v[176:179], v[58:61]
	v_mfma_f32_16x16x32_bf16 v[54:57], v[168:171], v[176:179], v[54:57]
	v_mfma_f32_16x16x32_bf16 v[42:45], v[160:163], v[184:187], v[42:45]
	v_mfma_f32_16x16x32_bf16 v[38:41], v[168:171], v[184:187], v[38:41]
	v_mfma_f32_16x16x32_bf16 v[26:29], v[160:163], v[192:195], v[26:29]
	v_mfma_f32_16x16x32_bf16 v[22:25], v[168:171], v[192:195], v[22:25]
	v_mfma_f32_16x16x32_bf16 v[10:13], v[160:163], v[200:203], v[10:13]
	v_mfma_f32_16x16x32_bf16 v[6:9], v[168:171], v[200:203], v[6:9]
	s_barrier
	s_setprio 0
	s_add_i32 s59, s59, 2
	s_add_u32 s55, s55, 0x100
	s_addc_u32 s56, s56, 0
	s_add_u32 s57, s57, 0x100
	s_addc_u32 s58, s58, 0
	s_cmp_gt_u32 s59, 61
	s_cbranch_scc0 .LBB0_131
	s_and_b64 vcc, exec, s[8:9]
	s_cbranch_vccz .LBB0_134
	s_barrier

.LBB0_251:
	s_add_u32 s56, s52, 0xffffff80
	s_addc_u32 s57, s53, -1
	s_cmp_eq_u32 s54, 60
	s_cselect_b32 s28, s2, s52
	s_cselect_b32 s29, s1, s53
	s_cselect_b32 s31, s11, s33
	s_cselect_b32 s30, s15, s19
	s_add_u32 s24, s28, 0x80
	s_addc_u32 s25, s29, 0
	s_add_u32 s26, s30, 0x80
	s_addc_u32 s27, s31, 0
	s_add_i32 s55, 0, 0x10000
	s_add_i32 s58, 0, 0x14000
	v_add_u32_e32 v152, s55, v1
	v_add_u32_e32 v168, s58, v1
	ds_read_b128 v[140:143], v152
	ds_read_b128 v[144:147], v152 offset:1024
	ds_read_b128 v[148:151], v152 offset:2048
	ds_read_b128 v[152:155], v152 offset:3072
	ds_read_b128 v[156:159], v168
	ds_read_b128 v[160:163], v168 offset:1024
	ds_read_b128 v[164:167], v168 offset:2048
	ds_read_b128 v[168:171], v168 offset:3072
	s_add_u32 s56, s56, 0x100000
	s_addc_u32 s57, s57, 0
	v_lshl_add_u64 v[204:205], s[56:57], 0, v[138:139]
	s_add_i32 m0, s23, 0xc000
	ds_read_b128 v[172:175], v5
	ds_read_b128 v[176:179], v5 offset:1024
	ds_read_b128 v[180:183], v5 offset:2048
	ds_read_b128 v[184:187], v5 offset:3072
	ds_read_b128 v[188:191], v5 offset:4096
	ds_read_b128 v[192:195], v5 offset:5120
	ds_read_b128 v[196:199], v5 offset:6144
	ds_read_b128 v[200:203], v5 offset:7168
	global_load_lds_dwordx4 v[204:205], off
	v_lshl_add_u64 v[204:205], s[56:57], 0, v[134:135]
	s_add_i32 m0, s23, 0xe000
	s_nop 0
	global_load_lds_dwordx4 v[204:205], off
	s_waitcnt vmcnt(8)
	s_waitcnt lgkmcnt(0)
	s_setprio 1
	s_barrier
	v_mfma_f32_16x16x32_bf16 v[6:9], v[140:143], v[172:175], v[6:9]
	v_mfma_f32_16x16x32_bf16 v[10:13], v[148:151], v[172:175], v[10:13]
	v_mfma_f32_16x16x32_bf16 v[22:25], v[140:143], v[180:183], v[22:25]
	v_mfma_f32_16x16x32_bf16 v[26:29], v[148:151], v[180:183], v[26:29]
	v_mfma_f32_16x16x32_bf16 v[38:41], v[140:143], v[188:191], v[38:41]
	v_mfma_f32_16x16x32_bf16 v[42:45], v[148:151], v[188:191], v[42:45]
	v_mfma_f32_16x16x32_bf16 v[54:57], v[140:143], v[196:199], v[54:57]
	v_mfma_f32_16x16x32_bf16 v[58:61], v[148:151], v[196:199], v[58:61]
	v_mfma_f32_16x16x32_bf16 v[6:9], v[144:147], v[176:179], v[6:9]
	v_mfma_f32_16x16x32_bf16 v[10:13], v[152:155], v[176:179], v[10:13]
	v_mfma_f32_16x16x32_bf16 v[22:25], v[144:147], v[184:187], v[22:25]
	v_mfma_f32_16x16x32_bf16 v[26:29], v[152:155], v[184:187], v[26:29]
	v_mfma_f32_16x16x32_bf16 v[38:41], v[144:147], v[192:195], v[38:41]
	v_mfma_f32_16x16x32_bf16 v[42:45], v[152:155], v[192:195], v[42:45]
	v_mfma_f32_16x16x32_bf16 v[54:57], v[144:147], v[200:203], v[54:57]
	v_mfma_f32_16x16x32_bf16 v[58:61], v[152:155], v[200:203], v[58:61]
	s_setprio 0
	s_setprio 1
	v_mfma_f32_16x16x32_bf16 v[14:17], v[156:159], v[172:175], v[14:17]
	v_mfma_f32_16x16x32_bf16 v[18:21], v[164:167], v[172:175], v[18:21]
	v_mfma_f32_16x16x32_bf16 v[30:33], v[156:159], v[180:183], v[30:33]
	v_mfma_f32_16x16x32_bf16 v[34:37], v[164:167], v[180:183], v[34:37]
	v_mfma_f32_16x16x32_bf16 v[46:49], v[156:159], v[188:191], v[46:49]
	v_mfma_f32_16x16x32_bf16 v[50:53], v[164:167], v[188:191], v[50:53]
	v_mfma_f32_16x16x32_bf16 v[62:65], v[156:159], v[196:199], v[62:65]
	v_mfma_f32_16x16x32_bf16 v[66:69], v[164:167], v[196:199], v[66:69]
	v_mfma_f32_16x16x32_bf16 v[14:17], v[160:163], v[176:179], v[14:17]
	v_mfma_f32_16x16x32_bf16 v[18:21], v[168:171], v[176:179], v[18:21]
	v_mfma_f32_16x16x32_bf16 v[30:33], v[160:163], v[184:187], v[30:33]
	v_mfma_f32_16x16x32_bf16 v[34:37], v[168:171], v[184:187], v[34:37]
	v_mfma_f32_16x16x32_bf16 v[46:49], v[160:163], v[192:195], v[46:49]
	v_mfma_f32_16x16x32_bf16 v[50:53], v[168:171], v[192:195], v[50:53]
	v_mfma_f32_16x16x32_bf16 v[62:65], v[160:163], v[200:203], v[62:65]
	v_mfma_f32_16x16x32_bf16 v[66:69], v[168:171], v[200:203], v[66:69]
	s_barrier
	s_setprio 0
	s_add_i32 s55, s55, s37
	v_lshl_add_u64 v[204:205], s[30:31], 0, v[136:137]
	s_mov_b32 m0, s55
	ds_read_b128 v[172:175], v5 offset:16384
	ds_read_b128 v[176:179], v5 offset:17408
	ds_read_b128 v[180:183], v5 offset:18432
	ds_read_b128 v[184:187], v5 offset:19456
	ds_read_b128 v[188:191], v5 offset:20480
	ds_read_b128 v[192:195], v5 offset:21504
	ds_read_b128 v[196:199], v5 offset:22528
	ds_read_b128 v[200:203], v5 offset:23552
	global_load_lds_dwordx4 v[204:205], off
	s_add_i32 m0, s55, 0x2000
	v_lshl_add_u64 v[204:205], s[30:31], 0, v[2:3]
	s_add_u32 s30, s30, 0x100000
	s_addc_u32 s31, s31, 0
	s_add_i32 s55, s58, s37
	global_load_lds_dwordx4 v[204:205], off
	v_lshl_add_u64 v[204:205], s[30:31], 0, v[136:137]
	s_mov_b32 m0, s55
	s_nop 0
	global_load_lds_dwordx4 v[204:205], off
	v_lshl_add_u64 v[204:205], s[30:31], 0, v[2:3]
	s_add_i32 m0, s55, 0x2000
	s_nop 0
	global_load_lds_dwordx4 v[204:205], off
	v_lshl_add_u64 v[204:205], s[28:29], 0, v[138:139]
	s_mov_b32 m0, s23
	s_nop 0
	global_load_lds_dwordx4 v[204:205], off
	v_lshl_add_u64 v[204:205], s[28:29], 0, v[134:135]
	s_mov_b32 m0, s40
	s_nop 0
	global_load_lds_dwordx4 v[204:205], off
	s_waitcnt vmcnt(8)
	s_waitcnt lgkmcnt(0)
	s_setprio 1
	s_barrier
	v_mfma_f32_16x16x32_bf16 v[70:73], v[140:143], v[172:175], v[70:73]
	v_mfma_f32_16x16x32_bf16 v[74:77], v[148:151], v[172:175], v[74:77]
	v_mfma_f32_16x16x32_bf16 v[86:89], v[140:143], v[180:183], v[86:89]
	v_mfma_f32_16x16x32_bf16 v[90:93], v[148:151], v[180:183], v[90:93]
	v_mfma_f32_16x16x32_bf16 v[102:105], v[140:143], v[188:191], v[102:105]
	v_mfma_f32_16x16x32_bf16 v[106:109], v[148:151], v[188:191], v[106:109]
	v_mfma_f32_16x16x32_bf16 v[130:133], v[140:143], v[196:199], v[130:133]
	v_mfma_f32_16x16x32_bf16 v[126:129], v[148:151], v[196:199], v[126:129]
	v_mfma_f32_16x16x32_bf16 v[70:73], v[144:147], v[176:179], v[70:73]
	v_mfma_f32_16x16x32_bf16 v[74:77], v[152:155], v[176:179], v[74:77]
	v_mfma_f32_16x16x32_bf16 v[86:89], v[144:147], v[184:187], v[86:89]
	v_mfma_f32_16x16x32_bf16 v[90:93], v[152:155], v[184:187], v[90:93]
	v_mfma_f32_16x16x32_bf16 v[102:105], v[144:147], v[192:195], v[102:105]
	v_mfma_f32_16x16x32_bf16 v[106:109], v[152:155], v[192:195], v[106:109]
	v_mfma_f32_16x16x32_bf16 v[130:133], v[144:147], v[200:203], v[130:133]
	v_mfma_f32_16x16x32_bf16 v[126:129], v[152:155], v[200:203], v[126:129]
	s_setprio 0
	s_setprio 1
	v_mfma_f32_16x16x32_bf16 v[78:81], v[156:159], v[172:175], v[78:81]
	v_mfma_f32_16x16x32_bf16 v[82:85], v[164:167], v[172:175], v[82:85]
	v_mfma_f32_16x16x32_bf16 v[94:97], v[156:159], v[180:183], v[94:97]
	v_mfma_f32_16x16x32_bf16 v[98:101], v[164:167], v[180:183], v[98:101]
	v_mfma_f32_16x16x32_bf16 v[110:113], v[156:159], v[188:191], v[110:113]
	v_mfma_f32_16x16x32_bf16 v[114:117], v[164:167], v[188:191], v[114:117]
	v_mfma_f32_16x16x32_bf16 v[122:125], v[156:159], v[196:199], v[122:125]
	v_mfma_f32_16x16x32_bf16 v[118:121], v[164:167], v[196:199], v[118:121]
	v_mfma_f32_16x16x32_bf16 v[78:81], v[160:163], v[176:179], v[78:81]
	v_mfma_f32_16x16x32_bf16 v[82:85], v[168:171], v[176:179], v[82:85]
	v_mfma_f32_16x16x32_bf16 v[94:97], v[160:163], v[184:187], v[94:97]
	v_mfma_f32_16x16x32_bf16 v[98:101], v[168:171], v[184:187], v[98:101]
	v_mfma_f32_16x16x32_bf16 v[110:113], v[160:163], v[192:195], v[110:113]
	v_mfma_f32_16x16x32_bf16 v[114:117], v[168:171], v[192:195], v[114:117]
	v_mfma_f32_16x16x32_bf16 v[122:125], v[160:163], v[200:203], v[122:125]
	v_mfma_f32_16x16x32_bf16 v[118:121], v[168:171], v[200:203], v[118:121]
	s_barrier
	s_setprio 0
	s_add_i32 s30, 0, 0x18000
	s_add_i32 s31, 0, 0x1c000
	v_add_u32_e32 v152, s30, v1
	v_add_u32_e32 v168, s31, v1
	ds_read_b128 v[140:143], v152
	ds_read_b128 v[144:147], v152 offset:1024
	ds_read_b128 v[148:151], v152 offset:2048
	ds_read_b128 v[152:155], v152 offset:3072
	ds_read_b128 v[156:159], v168
	ds_read_b128 v[160:163], v168 offset:1024
	ds_read_b128 v[164:167], v168 offset:2048
	ds_read_b128 v[168:171], v168 offset:3072
	s_add_u32 s28, s28, 0x100000
	s_addc_u32 s29, s29, 0
	s_mov_b32 m0, s41
	v_lshl_add_u64 v[204:205], s[28:29], 0, v[138:139]
	ds_read_b128 v[172:175], v5 offset:32768
	ds_read_b128 v[176:179], v5 offset:33792
	ds_read_b128 v[180:183], v5 offset:34816
	ds_read_b128 v[184:187], v5 offset:35840
	ds_read_b128 v[188:191], v5 offset:36864
	ds_read_b128 v[192:195], v5 offset:37888
	ds_read_b128 v[196:199], v5 offset:38912
	ds_read_b128 v[200:203], v5 offset:39936
	global_load_lds_dwordx4 v[204:205], off
	v_lshl_add_u64 v[204:205], s[28:29], 0, v[134:135]
	s_mov_b32 m0, s42
	s_nop 0
	global_load_lds_dwordx4 v[204:205], off
	s_waitcnt vmcnt(8)
	s_waitcnt lgkmcnt(0)
	s_setprio 1
	s_barrier
	v_mfma_f32_16x16x32_bf16 v[6:9], v[140:143], v[172:175], v[6:9]
	v_mfma_f32_16x16x32_bf16 v[10:13], v[148:151], v[172:175], v[10:13]
	v_mfma_f32_16x16x32_bf16 v[22:25], v[140:143], v[180:183], v[22:25]
	v_mfma_f32_16x16x32_bf16 v[26:29], v[148:151], v[180:183], v[26:29]
	v_mfma_f32_16x16x32_bf16 v[38:41], v[140:143], v[188:191], v[38:41]
	v_mfma_f32_16x16x32_bf16 v[42:45], v[148:151], v[188:191], v[42:45]
	v_mfma_f32_16x16x32_bf16 v[54:57], v[140:143], v[196:199], v[54:57]
	v_mfma_f32_16x16x32_bf16 v[58:61], v[148:151], v[196:199], v[58:61]
	v_mfma_f32_16x16x32_bf16 v[6:9], v[144:147], v[176:179], v[6:9]
	v_mfma_f32_16x16x32_bf16 v[10:13], v[152:155], v[176:179], v[10:13]
	v_mfma_f32_16x16x32_bf16 v[22:25], v[144:147], v[184:187], v[22:25]
	v_mfma_f32_16x16x32_bf16 v[26:29], v[152:155], v[184:187], v[26:29]
	v_mfma_f32_16x16x32_bf16 v[38:41], v[144:147], v[192:195], v[38:41]
	v_mfma_f32_16x16x32_bf16 v[42:45], v[152:155], v[192:195], v[42:45]
	v_mfma_f32_16x16x32_bf16 v[54:57], v[144:147], v[200:203], v[54:57]
	v_mfma_f32_16x16x32_bf16 v[58:61], v[152:155], v[200:203], v[58:61]
	s_setprio 0
	s_setprio 1
	v_mfma_f32_16x16x32_bf16 v[14:17], v[156:159], v[172:175], v[14:17]
	v_mfma_f32_16x16x32_bf16 v[18:21], v[164:167], v[172:175], v[18:21]
	v_mfma_f32_16x16x32_bf16 v[30:33], v[156:159], v[180:183], v[30:33]
	v_mfma_f32_16x16x32_bf16 v[34:37], v[164:167], v[180:183], v[34:37]
	v_mfma_f32_16x16x32_bf16 v[46:49], v[156:159], v[188:191], v[46:49]
	v_mfma_f32_16x16x32_bf16 v[50:53], v[164:167], v[188:191], v[50:53]
	v_mfma_f32_16x16x32_bf16 v[62:65], v[156:159], v[196:199], v[62:65]
	v_mfma_f32_16x16x32_bf16 v[66:69], v[164:167], v[196:199], v[66:69]
	v_mfma_f32_16x16x32_bf16 v[14:17], v[160:163], v[176:179], v[14:17]
	v_mfma_f32_16x16x32_bf16 v[18:21], v[168:171], v[176:179], v[18:21]
	v_mfma_f32_16x16x32_bf16 v[30:33], v[160:163], v[184:187], v[30:33]
	v_mfma_f32_16x16x32_bf16 v[34:37], v[168:171], v[184:187], v[34:37]
	v_mfma_f32_16x16x32_bf16 v[46:49], v[160:163], v[192:195], v[46:49]
	v_mfma_f32_16x16x32_bf16 v[50:53], v[168:171], v[192:195], v[50:53]
	v_mfma_f32_16x16x32_bf16 v[62:65], v[160:163], v[200:203], v[62:65]
	v_mfma_f32_16x16x32_bf16 v[66:69], v[168:171], v[200:203], v[66:69]
	s_barrier
	s_setprio 0
	s_add_i32 s28, s30, s37
	v_lshl_add_u64 v[204:205], s[26:27], 0, v[136:137]
	s_mov_b32 m0, s28
	ds_read_b128 v[172:175], v5 offset:49152
	ds_read_b128 v[176:179], v5 offset:50176
	ds_read_b128 v[180:183], v5 offset:51200
	ds_read_b128 v[184:187], v5 offset:52224
	ds_read_b128 v[188:191], v5 offset:53248
	ds_read_b128 v[192:195], v5 offset:54272
	ds_read_b128 v[196:199], v5 offset:55296
	ds_read_b128 v[200:203], v5 offset:56320
	global_load_lds_dwordx4 v[204:205], off
	s_add_i32 m0, s28, 0x2000
	v_lshl_add_u64 v[204:205], s[26:27], 0, v[2:3]
	s_add_u32 s26, s26, 0x100000
	s_addc_u32 s27, s27, 0
	s_add_i32 s28, s31, s37
	global_load_lds_dwordx4 v[204:205], off
	v_lshl_add_u64 v[204:205], s[26:27], 0, v[136:137]
	s_mov_b32 m0, s28
	s_nop 0
	global_load_lds_dwordx4 v[204:205], off
	v_lshl_add_u64 v[204:205], s[26:27], 0, v[2:3]
	s_add_i32 m0, s28, 0x2000
	s_nop 0
	global_load_lds_dwordx4 v[204:205], off
	v_lshl_add_u64 v[204:205], s[24:25], 0, v[138:139]
	s_mov_b32 m0, s49
	s_nop 0
	global_load_lds_dwordx4 v[204:205], off
	v_lshl_add_u64 v[204:205], s[24:25], 0, v[134:135]
	s_mov_b32 m0, s50
	s_nop 0
	global_load_lds_dwordx4 v[204:205], off
	s_waitcnt vmcnt(8)
	s_waitcnt lgkmcnt(0)
	s_setprio 1
	s_barrier
	v_mfma_f32_16x16x32_bf16 v[70:73], v[140:143], v[172:175], v[70:73]
	v_mfma_f32_16x16x32_bf16 v[74:77], v[148:151], v[172:175], v[74:77]
	v_mfma_f32_16x16x32_bf16 v[86:89], v[140:143], v[180:183], v[86:89]
	v_mfma_f32_16x16x32_bf16 v[90:93], v[148:151], v[180:183], v[90:93]
	v_mfma_f32_16x16x32_bf16 v[102:105], v[140:143], v[188:191], v[102:105]
	v_mfma_f32_16x16x32_bf16 v[106:109], v[148:151], v[188:191], v[106:109]
	v_mfma_f32_16x16x32_bf16 v[130:133], v[140:143], v[196:199], v[130:133]
	v_mfma_f32_16x16x32_bf16 v[126:129], v[148:151], v[196:199], v[126:129]
	v_mfma_f32_16x16x32_bf16 v[70:73], v[144:147], v[176:179], v[70:73]
	v_mfma_f32_16x16x32_bf16 v[74:77], v[152:155], v[176:179], v[74:77]
	v_mfma_f32_16x16x32_bf16 v[86:89], v[144:147], v[184:187], v[86:89]
	v_mfma_f32_16x16x32_bf16 v[90:93], v[152:155], v[184:187], v[90:93]
	v_mfma_f32_16x16x32_bf16 v[102:105], v[144:147], v[192:195], v[102:105]
	v_mfma_f32_16x16x32_bf16 v[106:109], v[152:155], v[192:195], v[106:109]
	v_mfma_f32_16x16x32_bf16 v[130:133], v[144:147], v[200:203], v[130:133]
	v_mfma_f32_16x16x32_bf16 v[126:129], v[152:155], v[200:203], v[126:129]
	s_setprio 0
	s_setprio 1
	v_mfma_f32_16x16x32_bf16 v[78:81], v[156:159], v[172:175], v[78:81]
	v_mfma_f32_16x16x32_bf16 v[82:85], v[164:167], v[172:175], v[82:85]
	v_mfma_f32_16x16x32_bf16 v[94:97], v[156:159], v[180:183], v[94:97]
	v_mfma_f32_16x16x32_bf16 v[98:101], v[164:167], v[180:183], v[98:101]
	v_mfma_f32_16x16x32_bf16 v[110:113], v[156:159], v[188:191], v[110:113]
	v_mfma_f32_16x16x32_bf16 v[114:117], v[164:167], v[188:191], v[114:117]
	v_mfma_f32_16x16x32_bf16 v[122:125], v[156:159], v[196:199], v[122:125]
	v_mfma_f32_16x16x32_bf16 v[118:121], v[164:167], v[196:199], v[118:121]
	v_mfma_f32_16x16x32_bf16 v[78:81], v[160:163], v[176:179], v[78:81]
	v_mfma_f32_16x16x32_bf16 v[82:85], v[168:171], v[176:179], v[82:85]
	v_mfma_f32_16x16x32_bf16 v[94:97], v[160:163], v[184:187], v[94:97]
	v_mfma_f32_16x16x32_bf16 v[98:101], v[168:171], v[184:187], v[98:101]
	v_mfma_f32_16x16x32_bf16 v[110:113], v[160:163], v[192:195], v[110:113]
	v_mfma_f32_16x16x32_bf16 v[114:117], v[168:171], v[192:195], v[114:117]
	v_mfma_f32_16x16x32_bf16 v[122:125], v[160:163], v[200:203], v[122:125]
	v_mfma_f32_16x16x32_bf16 v[118:121], v[168:171], v[200:203], v[118:121]
	s_barrier
	s_setprio 0
	s_add_i32 s54, s54, 2
	s_add_u32 s19, s19, 0x100
	s_addc_u32 s33, s33, 0
	s_add_u32 s52, s52, 0x100
	s_addc_u32 s53, s53, 0
	s_cmp_gt_u32 s54, 61
	s_cbranch_scc0 .LBB0_251
	v_mov_b32_e32 v141, v0
	s_lshl_b32 s1, s0, 8
	s_mov_b64 s[24:25], s[84:85]
	s_add_i32 s1, s1, s43
	v_and_or_b32 v140, v141, 15, s1
	v_lshrrev_b32_e32 v141, 1, v141
	s_add_u32 s26, s24, s6
	v_and_or_b32 v148, v141, 24, s48
	s_addc_u32 s27, s25, s7
	v_ashrrev_i32_e32 v141, 31, v140
	v_lshl_add_u64 v[142:143], v[140:141], 2, s[26:27]
	s_mov_b64 s[26:27], 0x10000
	v_lshl_add_u64 v[144:145], v[142:143], 0, s[26:27]
	v_add_co_u32_e32 v142, vcc, s91, v142
	global_load_dword v146, v[144:145], off offset:512
	s_nop 0
	v_addc_co_u32_e32 v143, vcc, 0, v143, vcc
	global_load_dword v142, v[142:143], off
	s_cmp_lt_i32 s22, 8
	s_mov_b64 s[26:27], -1
	global_load_dword v205, v[144:145], off offset:64
	global_load_dword v204, v[144:145], off offset:128
	global_load_dword v203, v[144:145], off offset:192
	global_load_dword v202, v[144:145], off offset:576
	global_load_dword v201, v[144:145], off offset:640
	global_load_dword v200, v[144:145], off offset:704
	s_waitcnt vmcnt(0)
	v_fmamk_f32 v146, v146, 0x39800000, v246
	v_mul_f32_e32 v147, 0x4b800000, v146
	v_fmamk_f32 v142, v142, 0x39800000, v246
	v_cmp_gt_f32_e32 vcc, s95, v142
	v_mul_f32_e32 v143, 0x4b800000, v142
	s_nop 0
	v_cndmask_b32_e32 v142, v142, v143, vcc
	v_rsq_f32_e32 v142, v142
	s_nop 0
	v_mul_f32_e32 v143, 0x45800000, v142
	v_cndmask_b32_e32 v142, v142, v143, vcc
	v_pk_mul_f32 v[8:9], v[8:9], v[142:143] op_sel_hi:[1,0]
	v_pk_mul_f32 v[6:7], v[6:7], v[142:143] op_sel_hi:[1,0]
	v_pk_mul_f32 v[12:13], v[12:13], v[142:143] op_sel_hi:[1,0]
	v_pk_mul_f32 v[10:11], v[10:11], v[142:143] op_sel_hi:[1,0]
	v_pk_mul_f32 v[16:17], v[16:17], v[142:143] op_sel_hi:[1,0]
	v_pk_mul_f32 v[14:15], v[14:15], v[142:143] op_sel_hi:[1,0]
	v_pk_mul_f32 v[20:21], v[20:21], v[142:143] op_sel_hi:[1,0]
	v_pk_mul_f32 v[18:19], v[18:19], v[142:143] op_sel_hi:[1,0]
	s_waitcnt vmcnt(0)
	v_fmamk_f32 v142, v205, 0x39800000, v246
	v_cmp_gt_f32_e32 vcc, s95, v142
	v_mul_f32_e32 v143, 0x4b800000, v142
	s_nop 0
	v_cndmask_b32_e32 v142, v142, v143, vcc
	v_rsq_f32_e32 v142, v142
	s_nop 0
	v_mul_f32_e32 v143, 0x45800000, v142
	v_cndmask_b32_e32 v142, v142, v143, vcc
	v_pk_mul_f32 v[24:25], v[24:25], v[142:143] op_sel_hi:[1,0]
	v_pk_mul_f32 v[22:23], v[22:23], v[142:143] op_sel_hi:[1,0]
	v_pk_mul_f32 v[28:29], v[28:29], v[142:143] op_sel_hi:[1,0]
	v_pk_mul_f32 v[26:27], v[26:27], v[142:143] op_sel_hi:[1,0]
	v_pk_mul_f32 v[32:33], v[32:33], v[142:143] op_sel_hi:[1,0]
	v_pk_mul_f32 v[30:31], v[30:31], v[142:143] op_sel_hi:[1,0]
	v_pk_mul_f32 v[36:37], v[36:37], v[142:143] op_sel_hi:[1,0]
	v_pk_mul_f32 v[34:35], v[34:35], v[142:143] op_sel_hi:[1,0]
	s_waitcnt vmcnt(0)
	v_fmamk_f32 v142, v204, 0x39800000, v246
	v_cmp_gt_f32_e32 vcc, s95, v142
	v_mul_f32_e32 v143, 0x4b800000, v142
	s_nop 0
	v_cndmask_b32_e32 v142, v142, v143, vcc
	v_rsq_f32_e32 v142, v142
	s_nop 0
	v_mul_f32_e32 v143, 0x45800000, v142
	v_cndmask_b32_e32 v142, v142, v143, vcc
	v_pk_mul_f32 v[40:41], v[40:41], v[142:143] op_sel_hi:[1,0]
	v_pk_mul_f32 v[38:39], v[38:39], v[142:143] op_sel_hi:[1,0]
	v_pk_mul_f32 v[44:45], v[44:45], v[142:143] op_sel_hi:[1,0]
	v_pk_mul_f32 v[42:43], v[42:43], v[142:143] op_sel_hi:[1,0]
	v_pk_mul_f32 v[48:49], v[48:49], v[142:143] op_sel_hi:[1,0]
	v_pk_mul_f32 v[46:47], v[46:47], v[142:143] op_sel_hi:[1,0]
	v_pk_mul_f32 v[52:53], v[52:53], v[142:143] op_sel_hi:[1,0]
	v_pk_mul_f32 v[50:51], v[50:51], v[142:143] op_sel_hi:[1,0]
	s_waitcnt vmcnt(0)
	v_fmamk_f32 v142, v203, 0x39800000, v246
	v_cmp_gt_f32_e32 vcc, s95, v142
	v_mul_f32_e32 v143, 0x4b800000, v142
	s_nop 0
	v_cndmask_b32_e32 v142, v142, v143, vcc
	v_rsq_f32_e32 v142, v142
	s_nop 0
	v_mul_f32_e32 v143, 0x45800000, v142
	v_cndmask_b32_e32 v142, v142, v143, vcc
	v_cmp_gt_f32_e32 vcc, s95, v146
	v_pk_mul_f32 v[56:57], v[56:57], v[142:143] op_sel_hi:[1,0]
	v_pk_mul_f32 v[54:55], v[54:55], v[142:143] op_sel_hi:[1,0]
	v_cndmask_b32_e32 v146, v146, v147, vcc
	v_rsq_f32_e32 v146, v146
	v_pk_mul_f32 v[60:61], v[60:61], v[142:143] op_sel_hi:[1,0]
	v_pk_mul_f32 v[58:59], v[58:59], v[142:143] op_sel_hi:[1,0]
	v_pk_mul_f32 v[64:65], v[64:65], v[142:143] op_sel_hi:[1,0]
	v_mul_f32_e32 v147, 0x45800000, v146
	v_cndmask_b32_e32 v146, v146, v147, vcc
	v_pk_mul_f32 v[72:73], v[72:73], v[146:147] op_sel_hi:[1,0]
	v_pk_mul_f32 v[70:71], v[70:71], v[146:147] op_sel_hi:[1,0]
	v_pk_mul_f32 v[76:77], v[76:77], v[146:147] op_sel_hi:[1,0]
	v_pk_mul_f32 v[74:75], v[74:75], v[146:147] op_sel_hi:[1,0]
	v_pk_mul_f32 v[80:81], v[80:81], v[146:147] op_sel_hi:[1,0]
	v_pk_mul_f32 v[78:79], v[78:79], v[146:147] op_sel_hi:[1,0]
	v_pk_mul_f32 v[84:85], v[84:85], v[146:147] op_sel_hi:[1,0]
	v_pk_mul_f32 v[82:83], v[82:83], v[146:147] op_sel_hi:[1,0]
	v_pk_mul_f32 v[62:63], v[62:63], v[142:143] op_sel_hi:[1,0]
	v_pk_mul_f32 v[68:69], v[68:69], v[142:143] op_sel_hi:[1,0]
	v_pk_mul_f32 v[66:67], v[66:67], v[142:143] op_sel_hi:[1,0]
	v_add_u32_e32 v142, 0x80, v140
	v_ashrrev_i32_e32 v143, 31, v142
	s_waitcnt vmcnt(0)
	v_fmamk_f32 v146, v202, 0x39800000, v246
	v_cmp_gt_f32_e32 vcc, s95, v146
	v_mul_f32_e32 v147, 0x4b800000, v146
	s_nop 0
	v_cndmask_b32_e32 v146, v146, v147, vcc
	v_rsq_f32_e32 v146, v146
	s_nop 0
	v_mul_f32_e32 v147, 0x45800000, v146
	v_cndmask_b32_e32 v146, v146, v147, vcc
	v_pk_mul_f32 v[88:89], v[88:89], v[146:147] op_sel_hi:[1,0]
	v_pk_mul_f32 v[86:87], v[86:87], v[146:147] op_sel_hi:[1,0]
	v_pk_mul_f32 v[92:93], v[92:93], v[146:147] op_sel_hi:[1,0]
	v_pk_mul_f32 v[90:91], v[90:91], v[146:147] op_sel_hi:[1,0]
	v_pk_mul_f32 v[96:97], v[96:97], v[146:147] op_sel_hi:[1,0]
	v_pk_mul_f32 v[94:95], v[94:95], v[146:147] op_sel_hi:[1,0]
	v_pk_mul_f32 v[100:101], v[100:101], v[146:147] op_sel_hi:[1,0]
	v_pk_mul_f32 v[98:99], v[98:99], v[146:147] op_sel_hi:[1,0]
	s_waitcnt vmcnt(0)
	v_fmamk_f32 v146, v201, 0x39800000, v246
	v_cmp_gt_f32_e32 vcc, s95, v146
	v_mul_f32_e32 v147, 0x4b800000, v146
	s_waitcnt vmcnt(0)
	v_fmamk_f32 v144, v200, 0x39800000, v246
	v_cndmask_b32_e32 v146, v146, v147, vcc
	v_rsq_f32_e32 v146, v146
	v_mul_f32_e32 v145, 0x4b800000, v144
	v_mul_f32_e32 v147, 0x45800000, v146
	v_cndmask_b32_e32 v146, v146, v147, vcc
	v_cmp_gt_f32_e32 vcc, s95, v144
	v_pk_mul_f32 v[104:105], v[104:105], v[146:147] op_sel_hi:[1,0]
	v_pk_mul_f32 v[102:103], v[102:103], v[146:147] op_sel_hi:[1,0]
	v_cndmask_b32_e32 v144, v144, v145, vcc
	v_rsq_f32_e32 v144, v144
	v_pk_mul_f32 v[108:109], v[108:109], v[146:147] op_sel_hi:[1,0]
	v_pk_mul_f32 v[106:107], v[106:107], v[146:147] op_sel_hi:[1,0]
	v_pk_mul_f32 v[112:113], v[112:113], v[146:147] op_sel_hi:[1,0]
	v_mul_f32_e32 v145, 0x45800000, v144
	v_cndmask_b32_e32 v144, v144, v145, vcc
	v_pk_mul_f32 v[110:111], v[110:111], v[146:147] op_sel_hi:[1,0]
	v_pk_mul_f32 v[116:117], v[116:117], v[146:147] op_sel_hi:[1,0]
	v_pk_mul_f32 v[114:115], v[114:115], v[146:147] op_sel_hi:[1,0]
	v_pk_mul_f32 v[132:133], v[132:133], v[144:145] op_sel_hi:[1,0]
	v_pk_mul_f32 v[130:131], v[130:131], v[144:145] op_sel_hi:[1,0]
	v_pk_mul_f32 v[128:129], v[128:129], v[144:145] op_sel_hi:[1,0]
	v_pk_mul_f32 v[126:127], v[126:127], v[144:145] op_sel_hi:[1,0]
	v_pk_mul_f32 v[124:125], v[124:125], v[144:145] op_sel_hi:[1,0]
	v_pk_mul_f32 v[122:123], v[122:123], v[144:145] op_sel_hi:[1,0]
	v_pk_mul_f32 v[120:121], v[120:121], v[144:145] op_sel_hi:[1,0]
	v_pk_mul_f32 v[118:119], v[118:119], v[144:145] op_sel_hi:[1,0]
	s_cbranch_scc1 .LBB0_254
	v_mul_f32_e32 v145, 0xbfb8aa3b, v7
	v_mul_f32_e32 v146, 0xbfb8aa3b, v8
	v_exp_f32_e32 v145, v145
	v_exp_f32_e32 v146, v146
	v_mul_f32_e32 v144, 0xbfb8aa3b, v6
	v_exp_f32_e32 v144, v144
	v_add_f32_e32 v145, 1.0, v145
	v_add_f32_e32 v146, 1.0, v146
	v_rcp_f32_e32 v145, v145
	v_rcp_f32_e32 v149, v146
	v_add_f32_e32 v144, 1.0, v144
	v_mul_f32_e32 v146, 0xbfb8aa3b, v9
	v_mul_f32_e32 v147, v7, v145
	v_mul_f32_e32 v195, v8, v149
	v_mul_f32_e32 v145, 0xbfb8aa3b, v10
	v_mul_f32_e32 v149, 0xbfb8aa3b, v11
	v_rcp_f32_e32 v144, v144
	v_exp_f32_e32 v150, v146
	v_exp_f32_e32 v145, v145
	v_exp_f32_e32 v149, v149
	v_mul_f32_e32 v146, v6, v144
	v_add_f32_e32 v144, 1.0, v150
	v_add_f32_e32 v145, 1.0, v145
	v_add_f32_e32 v149, 1.0, v149
	v_mul_f32_e32 v150, 0xbfb8aa3b, v12
	v_rcp_f32_e32 v144, v144
	v_rcp_f32_e32 v145, v145
	v_rcp_f32_e32 v149, v149
	v_exp_f32_e32 v150, v150
	v_mul_f32_e32 v209, v9, v144
	v_mul_f32_e32 v144, v10, v145
	v_mul_f32_e32 v145, v11, v149
	v_add_f32_e32 v149, 1.0, v150
	v_mul_f32_e32 v150, 0xbfb8aa3b, v13
	v_exp_f32_e32 v150, v150
	v_mul_f32_e32 v151, 0xbfb8aa3b, v14
	v_exp_f32_e32 v151, v151
	v_mul_f32_e32 v240, 0xbfb8aa3b, v99
	v_add_f32_e32 v150, 1.0, v150
	v_rcp_f32_e32 v150, v150
	v_add_f32_e32 v151, 1.0, v151
	v_rcp_f32_e32 v151, v151
	v_exp_f32_e32 v240, v240
	v_mul_f32_e32 v206, v13, v150
	v_mul_f32_e32 v150, 0xbfb8aa3b, v16
	v_mul_f32_e32 v194, v14, v151
	v_exp_f32_e32 v150, v150
	v_mul_f32_e32 v151, 0xbfb8aa3b, v17
	v_exp_f32_e32 v151, v151
	v_mul_f32_e32 v152, 0xbfb8aa3b, v15
	v_rcp_f32_e32 v149, v149
	v_exp_f32_e32 v152, v152
	v_add_f32_e32 v150, 1.0, v150
	v_rcp_f32_e32 v150, v150
	v_add_f32_e32 v151, 1.0, v151
	v_add_f32_e32 v242, 1.0, v240
	v_cvt_pk_bf16_f32 v240, v146, v147
	v_mul_f32_e32 v146, 0xbfb8aa3b, v100
	v_rcp_f32_e32 v151, v151
	v_exp_f32_e32 v146, v146
	v_mul_f32_e32 v147, 0xbfb8aa3b, v101
	v_exp_f32_e32 v147, v147
	v_mul_f32_e32 v205, v12, v149
	v_add_f32_e32 v149, 1.0, v152
	v_mul_f32_e32 v152, 0xbfb8aa3b, v18
	s_lshl_b32 s1, s22, 8
	v_rcp_f32_e32 v149, v149
	v_exp_f32_e32 v152, v152
	v_mul_f32_e32 v203, v16, v150
	v_mul_f32_e32 v150, 0xbfb8aa3b, v19
	v_cvt_pk_bf16_f32 v241, v195, v209
	v_rcp_f32_e32 v195, v242
	s_addk_i32 s1, 0xf800
	v_cvt_pk_bf16_f32 v242, v144, v145
	v_cvt_pk_bf16_f32 v243, v205, v206
	v_mul_f32_e32 v205, 0xbfb8aa3b, v102
	v_mul_f32_e32 v204, v17, v151
	v_exp_f32_e32 v150, v150
	v_mul_f32_e32 v151, 0xbfb8aa3b, v20
	v_add_f32_e32 v146, 1.0, v146
	v_or_b32_e32 v144, s1, v148
	v_mov_b32_e32 v145, v4
	v_exp_f32_e32 v205, v205
	v_exp_f32_e32 v151, v151
	v_rcp_f32_e32 v209, v146
	v_add_f32_e32 v146, 1.0, v147
	v_lshl_add_u64 v[144:145], v[144:145], 1, s[24:25]
	s_mov_b64 s[26:27], 0x1b480000
	v_rcp_f32_e32 v244, v146
	v_lshl_add_u64 v[146:147], v[144:145], 0, s[26:27]
	v_lshlrev_b64 v[144:145], 13, v[140:141]
	v_mul_f32_e32 v202, v15, v149
	v_add_f32_e32 v149, 1.0, v152
	v_lshl_add_u64 v[144:145], v[146:147], 0, v[144:145]
	v_rcp_f32_e32 v149, v149
	v_add_f32_e32 v150, 1.0, v150
	global_store_dwordx4 v[144:145], v[240:243], off nt
	v_add_f32_e32 v205, 1.0, v205
	v_rcp_f32_e32 v150, v150
	v_mul_f32_e32 v240, 0xbfb8aa3b, v103
	v_add_f32_e32 v151, 1.0, v151
	v_exp_f32_e32 v240, v240
	v_cvt_pk_bf16_f32 v202, v194, v202
	v_cvt_pk_bf16_f32 v203, v203, v204
	v_rcp_f32_e32 v204, v205
	v_rcp_f32_e32 v151, v151
	v_mul_f32_e32 v152, 0xbfb8aa3b, v21
	v_mul_f32_e32 v200, v18, v149
	v_exp_f32_e32 v152, v152
	v_mul_f32_e32 v201, v19, v150
	v_add_f32_e32 v205, 1.0, v240
	v_mul_f32_e32 v240, 0xbfb8aa3b, v105
	v_mul_f32_e32 v241, v102, v204
	v_cvt_pk_bf16_f32 v204, v200, v201
	v_mul_f32_e32 v200, 0xbfb8aa3b, v106
	v_mul_f32_e32 v192, v20, v151
	v_mul_f32_e32 v151, 0xbfb8aa3b, v23
	v_rcp_f32_e32 v205, v205
	v_exp_f32_e32 v240, v240
	v_exp_f32_e32 v200, v200
	v_exp_f32_e32 v151, v151
	v_mul_f32_e32 v150, 0xbfb8aa3b, v22
	v_add_f32_e32 v149, 1.0, v152
	v_exp_f32_e32 v150, v150
	v_rcp_f32_e32 v149, v149
	v_mul_f32_e32 v242, v103, v205
	v_add_f32_e32 v205, 1.0, v240
	v_mul_f32_e32 v201, 0xbfb8aa3b, v107
	v_add_f32_e32 v200, 1.0, v200
	v_add_f32_e32 v151, 1.0, v151
	v_exp_f32_e32 v201, v201
	v_rcp_f32_e32 v240, v205
	v_rcp_f32_e32 v200, v200
	v_rcp_f32_e32 v151, v151
	v_add_f32_e32 v150, 1.0, v150
	v_rcp_f32_e32 v150, v150
	v_mul_f32_e32 v197, v21, v149
	v_mul_f32_e32 v152, 0xbfb8aa3b, v24
	v_add_f32_e32 v201, 1.0, v201
	v_cvt_pk_bf16_f32 v205, v192, v197
	v_mul_f32_e32 v197, v105, v240
	v_mul_f32_e32 v240, v106, v200
	v_mul_f32_e32 v200, 0xbfb8aa3b, v109
	v_exp_f32_e32 v152, v152
	v_mul_f32_e32 v181, v23, v151
	v_mul_f32_e32 v151, 0xbfb8aa3b, v26
	v_rcp_f32_e32 v201, v201
	v_exp_f32_e32 v200, v200
	v_exp_f32_e32 v151, v151
	v_mul_f32_e32 v179, v22, v150
	v_mul_f32_e32 v150, 0xbfb8aa3b, v25
	v_exp_f32_e32 v150, v150
	v_add_f32_e32 v149, 1.0, v152
	v_mul_f32_e32 v152, 0xbfb8aa3b, v27
	v_mul_f32_e32 v243, v107, v201
	v_mul_f32_e32 v201, 0xbfb8aa3b, v110
	v_add_f32_e32 v200, 1.0, v200
	v_rcp_f32_e32 v149, v149
	v_add_f32_e32 v151, 1.0, v151
	v_exp_f32_e32 v152, v152
	v_exp_f32_e32 v201, v201
	v_rcp_f32_e32 v200, v200
	v_rcp_f32_e32 v151, v151
	v_add_f32_e32 v150, 1.0, v150
	v_rcp_f32_e32 v150, v150
	global_store_dwordx4 v[144:145], v[202:205], off offset:256 nt
	v_mul_f32_e32 v188, v24, v149
	v_add_f32_e32 v149, 1.0, v152
	v_mul_f32_e32 v202, 0xbfb8aa3b, v111
	v_add_f32_e32 v201, 1.0, v201
	v_exp_f32_e32 v202, v202
	v_mul_f32_e32 v204, v109, v200
	v_cvt_pk_bf16_f32 v200, v179, v181
	v_mul_f32_e32 v181, 0xbfb8aa3b, v113
	v_mul_f32_e32 v178, v26, v151
	v_mul_f32_e32 v151, 0xbfb8aa3b, v29
	v_rcp_f32_e32 v149, v149
	v_rcp_f32_e32 v201, v201
	v_exp_f32_e32 v181, v181
	v_exp_f32_e32 v151, v151
	v_mul_f32_e32 v179, 0xbfb8aa3b, v112
	v_mul_f32_e32 v189, v25, v150
	v_mul_f32_e32 v150, 0xbfb8aa3b, v28
	v_exp_f32_e32 v179, v179
	v_exp_f32_e32 v150, v150
	v_add_f32_e32 v202, 1.0, v202
	v_mul_f32_e32 v187, v27, v149
	v_mul_f32_e32 v205, v110, v201
	v_cvt_pk_bf16_f32 v201, v188, v189
	v_rcp_f32_e32 v188, v202
	v_add_f32_e32 v181, 1.0, v181
	v_cvt_pk_bf16_f32 v202, v178, v187
	v_mul_f32_e32 v178, 0xbfb8aa3b, v114
	v_add_f32_e32 v151, 1.0, v151
	v_rcp_f32_e32 v181, v181
	v_exp_f32_e32 v178, v178
	v_rcp_f32_e32 v151, v151
	v_add_f32_e32 v179, 1.0, v179
	v_add_f32_e32 v150, 1.0, v150
	v_rcp_f32_e32 v179, v179
	v_rcp_f32_e32 v150, v150
	v_mul_f32_e32 v245, v113, v181
	v_add_f32_e32 v181, 1.0, v178
	v_mul_f32_e32 v178, 0xbfb8aa3b, v115
	v_mul_f32_e32 v182, v29, v151
	v_mul_f32_e32 v151, 0xbfb8aa3b, v32
	v_exp_f32_e32 v248, v178
	v_or_b32_e32 v178, 16, v140
	v_exp_f32_e32 v151, v151
	v_mul_f32_e32 v206, v100, v209
	v_mul_f32_e32 v209, v101, v244
	v_mul_f32_e32 v244, v112, v179
	v_ashrrev_i32_e32 v179, 31, v178
	v_mul_f32_e32 v152, 0xbfb8aa3b, v30
	v_mul_f32_e32 v180, v28, v150
	v_mul_f32_e32 v150, 0xbfb8aa3b, v31
	v_lshlrev_b64 v[178:179], 13, v[178:179]
	v_exp_f32_e32 v152, v152
	v_exp_f32_e32 v150, v150
	v_mul_f32_e32 v187, v111, v188
	v_lshl_add_u64 v[188:189], v[146:147], 0, v[178:179]
	v_mul_f32_e32 v178, 0xbfb8aa3b, v116
	v_exp_f32_e32 v178, v178
	v_add_f32_e32 v151, 1.0, v151
	v_rcp_f32_e32 v151, v151
	v_add_f32_e32 v149, 1.0, v152
	v_add_f32_e32 v150, 1.0, v150
	v_rcp_f32_e32 v149, v149
	v_rcp_f32_e32 v150, v150
	v_add_f32_e32 v178, 1.0, v178
	v_rcp_f32_e32 v178, v178
	v_mul_f32_e32 v173, v32, v151
	v_mul_f32_e32 v151, 0xbfb8aa3b, v35
	v_exp_f32_e32 v151, v151
	v_mul_f32_e32 v152, 0xbfb8aa3b, v33
	v_mul_f32_e32 v170, v30, v149
	v_mul_f32_e32 v172, v31, v150
	v_mul_f32_e32 v150, 0xbfb8aa3b, v34
	v_exp_f32_e32 v152, v152
	v_exp_f32_e32 v150, v150
	v_cvt_pk_bf16_f32 v203, v180, v182
	global_store_dwordx4 v[188:189], v[200:203], off nt
	v_add_f32_e32 v151, 1.0, v151
	v_rcp_f32_e32 v151, v151
	v_mul_f32_e32 v201, v116, v178
	v_cvt_pk_bf16_f32 v178, v170, v172
	v_mul_f32_e32 v170, 0xbfb8aa3b, v130
	v_exp_f32_e32 v170, v170
	v_add_f32_e32 v149, 1.0, v152
	v_add_f32_e32 v150, 1.0, v150
	v_rcp_f32_e32 v149, v149
	v_rcp_f32_e32 v150, v150
	v_add_f32_e32 v170, 1.0, v170
	v_rcp_f32_e32 v179, v181
	v_rcp_f32_e32 v170, v170
	v_mul_f32_e32 v152, 0xbfb8aa3b, v36
	v_mul_f32_e32 v169, v35, v151
	v_mul_f32_e32 v151, 0xbfb8aa3b, v38
	v_exp_f32_e32 v152, v152
	v_exp_f32_e32 v151, v151
	v_add_f32_e32 v180, 1.0, v248
	v_mul_f32_e32 v181, 0xbfb8aa3b, v117
	v_mul_f32_e32 v183, v33, v149
	v_mul_f32_e32 v168, v34, v150
	v_mul_f32_e32 v150, 0xbfb8aa3b, v37
	v_rcp_f32_e32 v180, v180
	v_exp_f32_e32 v181, v181
	v_exp_f32_e32 v150, v150
	v_mul_f32_e32 v182, v114, v179
	v_cvt_pk_bf16_f32 v179, v173, v183
	v_mul_f32_e32 v183, v130, v170
	v_mul_f32_e32 v170, 0xbfb8aa3b, v126
	v_exp_f32_e32 v170, v170
	v_add_f32_e32 v149, 1.0, v152
	v_add_f32_e32 v151, 1.0, v151
	v_rcp_f32_e32 v149, v149
	v_rcp_f32_e32 v151, v151
	v_mul_f32_e32 v200, v115, v180
	v_add_f32_e32 v180, 1.0, v181
	v_add_f32_e32 v150, 1.0, v150
	v_rcp_f32_e32 v173, v180
	v_cvt_pk_bf16_f32 v180, v168, v169
	v_mul_f32_e32 v168, 0xbfb8aa3b, v132
	v_mul_f32_e32 v169, 0xbfb8aa3b, v133
	v_rcp_f32_e32 v150, v150
	v_exp_f32_e32 v168, v168
	v_exp_f32_e32 v169, v169
	v_add_f32_e32 v170, 1.0, v170
	v_rcp_f32_e32 v170, v170
	v_mul_f32_e32 v171, v36, v149
	v_mul_f32_e32 v149, v38, v151
	v_mul_f32_e32 v151, 0xbfb8aa3b, v40
	v_mul_f32_e32 v152, 0xbfb8aa3b, v39
	v_exp_f32_e32 v151, v151
	v_exp_f32_e32 v152, v152
	v_mul_f32_e32 v174, v37, v150
	v_add_f32_e32 v168, 1.0, v168
	v_cvt_pk_bf16_f32 v181, v171, v174
	v_add_f32_e32 v169, 1.0, v169
	v_mul_f32_e32 v171, 0xbfb8aa3b, v127
	v_rcp_f32_e32 v168, v168
	v_rcp_f32_e32 v169, v169
	v_exp_f32_e32 v171, v171
	v_mul_f32_e32 v203, v126, v170
	v_mul_f32_e32 v170, 0xbfb8aa3b, v129
	v_exp_f32_e32 v170, v170
	v_add_f32_e32 v151, 1.0, v151
	v_add_f32_e32 v150, 1.0, v152
	v_mul_f32_e32 v152, 0xbfb8aa3b, v41
	v_rcp_f32_e32 v151, v151
	v_exp_f32_e32 v152, v152
	v_mul_f32_e32 v174, v132, v168
	v_mul_f32_e32 v202, v133, v169
	v_add_f32_e32 v168, 1.0, v171
	v_mul_f32_e32 v169, 0xbfb8aa3b, v128
	v_exp_f32_e32 v169, v169
	v_rcp_f32_e32 v168, v168
	v_add_f32_e32 v170, 1.0, v170
	v_mul_f32_e32 v171, 0xbfb8aa3b, v122
	v_rcp_f32_e32 v170, v170
	v_exp_f32_e32 v171, v171
	v_mul_f32_e32 v153, 0xbfb8aa3b, v42
	v_mul_f32_e32 v154, v40, v151
	v_mul_f32_e32 v151, 0xbfb8aa3b, v43
	v_rcp_f32_e32 v150, v150
	v_add_f32_e32 v152, 1.0, v152
	v_exp_f32_e32 v156, v153
	v_exp_f32_e32 v151, v151
	v_rcp_f32_e32 v152, v152
	global_store_dwordx4 v[188:189], v[178:181], off offset:256 nt
	v_add_f32_e32 v169, 1.0, v169
	v_rcp_f32_e32 v169, v169
	v_mul_f32_e32 v178, v127, v168
	v_mul_f32_e32 v168, 0xbfb8aa3b, v123
	v_mul_f32_e32 v180, v129, v170
	v_add_f32_e32 v170, 1.0, v171
	v_exp_f32_e32 v171, v168
	v_mul_f32_e32 v153, v39, v150
	v_add_f32_e32 v150, 1.0, v156
	v_add_f32_e32 v151, 1.0, v151
	v_mul_f32_e32 v156, 0xbfb8aa3b, v45
	v_mul_f32_e32 v155, v41, v152
	v_mul_f32_e32 v152, 0xbfb8aa3b, v44
	v_rcp_f32_e32 v150, v150
	v_rcp_f32_e32 v151, v151
	v_exp_f32_e32 v158, v156
	v_exp_f32_e32 v152, v152
	v_mul_f32_e32 v179, v128, v169
	v_cvt_pk_bf16_f32 v168, v149, v153
	v_cvt_pk_bf16_f32 v169, v154, v155
	v_add_f32_e32 v154, 1.0, v171
	v_mul_f32_e32 v155, 0xbfb8aa3b, v125
	v_rcp_f32_e32 v153, v170
	v_rcp_f32_e32 v154, v154
	v_exp_f32_e32 v155, v155
	v_mul_f32_e32 v156, v42, v150
	v_mul_f32_e32 v157, v43, v151
	v_add_f32_e32 v150, 1.0, v158
	v_mul_f32_e32 v151, 0xbfb8aa3b, v46
	v_mul_f32_e32 v158, 0xbfb8aa3b, v47
	v_add_f32_e32 v152, 1.0, v152
	v_exp_f32_e32 v151, v151
	v_exp_f32_e32 v158, v158
	v_rcp_f32_e32 v152, v152
	v_mul_f32_e32 v185, 0xbfb8aa3b, v61
	v_mul_f32_e32 v181, v122, v153
	v_mul_f32_e32 v188, v123, v154
	v_add_f32_e32 v153, 1.0, v155
	v_mul_f32_e32 v154, 0xbfb8aa3b, v118
	v_rcp_f32_e32 v150, v150
	v_exp_f32_e32 v185, v185
	v_mul_f32_e32 v186, 0xbfb8aa3b, v62
	v_rcp_f32_e32 v153, v153
	v_exp_f32_e32 v154, v154
	v_mul_f32_e32 v184, 0xbfb8aa3b, v60
	v_exp_f32_e32 v186, v186
	v_add_f32_e32 v151, 1.0, v151
	v_add_f32_e32 v158, 1.0, v158
	v_mul_f32_e32 v159, 0xbfb8aa3b, v48
	v_exp_f32_e32 v184, v184
	v_mul_f32_e32 v210, 0xbfb8aa3b, v71
	v_mul_f32_e32 v155, 0xbfb8aa3b, v119
	v_mul_f32_e32 v152, v44, v152
	v_rcp_f32_e32 v151, v151
	v_rcp_f32_e32 v158, v158
	v_exp_f32_e32 v159, v159
	v_mul_f32_e32 v207, 0xbfb8aa3b, v69
	v_mul_f32_e32 v208, 0xbfb8aa3b, v70
	v_exp_f32_e32 v210, v210
	v_mul_f32_e32 v226, 0xbfb8aa3b, v85
	v_exp_f32_e32 v155, v155
	v_mul_f32_e32 v161, v45, v150
	v_add_f32_e32 v185, 1.0, v185
	v_exp_f32_e32 v207, v207
	v_exp_f32_e32 v208, v208
	v_exp_f32_e32 v226, v226
	v_mul_f32_e32 v227, 0xbfb8aa3b, v86
	v_cvt_pk_bf16_f32 v170, v156, v157
	v_mul_f32_e32 v156, v125, v153
	v_add_f32_e32 v153, 1.0, v154
	v_cvt_pk_bf16_f32 v171, v152, v161
	v_or_b32_e32 v152, 32, v140
	v_rcp_f32_e32 v190, v185
	v_add_f32_e32 v185, 1.0, v186
	v_mul_f32_e32 v225, 0xbfb8aa3b, v84
	v_exp_f32_e32 v227, v227
	v_mul_f32_e32 v236, 0xbfb8aa3b, v95
	v_rcp_f32_e32 v157, v153
	v_ashrrev_i32_e32 v153, 31, v152
	v_add_f32_e32 v184, 1.0, v184
	v_rcp_f32_e32 v191, v185
	v_mul_f32_e32 v185, 0xbfb8aa3b, v63
	v_exp_f32_e32 v225, v225
	v_mul_f32_e32 v234, 0xbfb8aa3b, v93
	v_mul_f32_e32 v235, 0xbfb8aa3b, v94
	v_exp_f32_e32 v236, v236
	v_lshlrev_b64 v[152:153], 13, v[152:153]
	v_mul_f32_e32 v150, v46, v151
	v_mul_f32_e32 v151, v47, v158
	v_add_f32_e32 v158, 1.0, v159
	v_mul_f32_e32 v159, 0xbfb8aa3b, v49
	v_mul_f32_e32 v160, 0xbfb8aa3b, v50
	v_mul_f32_e32 v162, 0xbfb8aa3b, v51
	v_mul_f32_e32 v163, 0xbfb8aa3b, v52
	v_mul_f32_e32 v164, 0xbfb8aa3b, v53
	v_rcp_f32_e32 v184, v184
	v_exp_f32_e32 v193, v185
	v_add_f32_e32 v210, 1.0, v210
	v_exp_f32_e32 v234, v234
	v_exp_f32_e32 v235, v235
	v_add_f32_e32 v189, 1.0, v155
	v_lshl_add_u64 v[154:155], v[146:147], 0, v[152:153]
	v_mul_f32_e32 v152, 0xbfb8aa3b, v120
	v_mul_f32_e32 v153, 0xbfb8aa3b, v121
	v_exp_f32_e32 v159, v159
	v_exp_f32_e32 v160, v160
	v_exp_f32_e32 v162, v162
	v_exp_f32_e32 v163, v163
	v_exp_f32_e32 v164, v164
	v_add_f32_e32 v207, 1.0, v207
	v_add_f32_e32 v208, 1.0, v208
	v_rcp_f32_e32 v211, v210
	v_mul_f32_e32 v210, 0xbfb8aa3b, v72
	v_add_f32_e32 v226, 1.0, v226
	v_exp_f32_e32 v152, v152
	v_exp_f32_e32 v153, v153
	v_rcp_f32_e32 v207, v207
	v_rcp_f32_e32 v208, v208
	v_exp_f32_e32 v212, v210
	v_rcp_f32_e32 v228, v226
	v_add_f32_e32 v226, 1.0, v227
	v_mul_f32_e32 v165, 0xbfb8aa3b, v54
	v_mul_f32_e32 v166, 0xbfb8aa3b, v55
	v_mul_f32_e32 v167, 0xbfb8aa3b, v56
	v_mul_f32_e32 v175, 0xbfb8aa3b, v57
	v_add_f32_e32 v225, 1.0, v225
	v_rcp_f32_e32 v229, v226
	v_mul_f32_e32 v226, 0xbfb8aa3b, v87
	v_add_f32_e32 v236, 1.0, v236
	v_exp_f32_e32 v165, v165
	v_exp_f32_e32 v166, v166
	v_exp_f32_e32 v167, v167
	v_exp_f32_e32 v175, v175
	v_mul_f32_e32 v176, 0xbfb8aa3b, v58
	v_mul_f32_e32 v177, 0xbfb8aa3b, v59
	v_mul_f32_e32 v185, v60, v184
	v_mul_f32_e32 v186, v61, v190
	v_mul_f32_e32 v184, v62, v191
	v_add_f32_e32 v190, 1.0, v193
	v_mul_f32_e32 v191, 0xbfb8aa3b, v64
	v_mul_f32_e32 v193, 0xbfb8aa3b, v65
	v_rcp_f32_e32 v225, v225
	v_exp_f32_e32 v230, v226
	v_add_f32_e32 v234, 1.0, v234
	v_add_f32_e32 v235, 1.0, v235
	v_rcp_f32_e32 v237, v236
	v_mul_f32_e32 v236, 0xbfb8aa3b, v96
	v_add_f32_e32 v159, 1.0, v159
	v_add_f32_e32 v160, 1.0, v160
	v_add_f32_e32 v162, 1.0, v162
	v_add_f32_e32 v163, 1.0, v163
	v_add_f32_e32 v164, 1.0, v164
	v_exp_f32_e32 v176, v176
	v_exp_f32_e32 v177, v177
	v_exp_f32_e32 v191, v191
	v_exp_f32_e32 v193, v193
	v_mul_f32_e32 v196, 0xbfb8aa3b, v66
	v_mul_f32_e32 v198, 0xbfb8aa3b, v67
	v_mul_f32_e32 v199, 0xbfb8aa3b, v68
	v_rcp_f32_e32 v234, v234
	v_rcp_f32_e32 v235, v235
	v_exp_f32_e32 v238, v236
	v_add_f32_e32 v152, 1.0, v152
	v_add_f32_e32 v153, 1.0, v153
	v_rcp_f32_e32 v158, v158
	v_rcp_f32_e32 v159, v159
	v_rcp_f32_e32 v160, v160
	v_rcp_f32_e32 v162, v162
	v_rcp_f32_e32 v163, v163
	v_rcp_f32_e32 v164, v164
	v_exp_f32_e32 v196, v196
	v_exp_f32_e32 v198, v198
	v_exp_f32_e32 v199, v199
	v_mul_f32_e32 v210, v69, v207
	v_mul_f32_e32 v207, v70, v208
	v_mul_f32_e32 v208, v71, v211
	v_add_f32_e32 v211, 1.0, v212
	v_mul_f32_e32 v212, 0xbfb8aa3b, v73
	v_mul_f32_e32 v213, 0xbfb8aa3b, v74
	v_mul_f32_e32 v216, 0xbfb8aa3b, v75
	v_mul_f32_e32 v217, 0xbfb8aa3b, v76
	v_mul_f32_e32 v218, 0xbfb8aa3b, v77
	v_rcp_f32_e32 v152, v152
	v_rcp_f32_e32 v153, v153
	v_exp_f32_e32 v212, v212
	v_exp_f32_e32 v213, v213
	v_exp_f32_e32 v216, v216
	v_exp_f32_e32 v217, v217
	v_exp_f32_e32 v218, v218
	v_mul_f32_e32 v219, 0xbfb8aa3b, v78
	v_mul_f32_e32 v220, 0xbfb8aa3b, v79
	v_mul_f32_e32 v221, 0xbfb8aa3b, v80
	v_mul_f32_e32 v222, 0xbfb8aa3b, v81
	v_mul_f32_e32 v223, 0xbfb8aa3b, v82
	v_mul_f32_e32 v224, 0xbfb8aa3b, v83
	v_add_f32_e32 v165, 1.0, v165
	v_add_f32_e32 v166, 1.0, v166
	v_add_f32_e32 v167, 1.0, v167
	v_add_f32_e32 v175, 1.0, v175
	v_exp_f32_e32 v219, v219
	v_exp_f32_e32 v220, v220
	v_exp_f32_e32 v221, v221
	v_exp_f32_e32 v222, v222
	v_exp_f32_e32 v223, v223
	v_exp_f32_e32 v224, v224
	v_mul_f32_e32 v226, v84, v225
	v_mul_f32_e32 v227, v85, v228
	v_mul_f32_e32 v225, v86, v229
	v_add_f32_e32 v228, 1.0, v230
	v_mul_f32_e32 v229, 0xbfb8aa3b, v88
	v_mul_f32_e32 v230, 0xbfb8aa3b, v89
	v_mul_f32_e32 v231, 0xbfb8aa3b, v90
	v_mul_f32_e32 v232, 0xbfb8aa3b, v91
	v_mul_f32_e32 v233, 0xbfb8aa3b, v92
	v_rcp_f32_e32 v165, v165
	v_rcp_f32_e32 v166, v166
	v_rcp_f32_e32 v167, v167
	v_rcp_f32_e32 v175, v175
	v_add_f32_e32 v176, 1.0, v176
	v_add_f32_e32 v177, 1.0, v177
	v_add_f32_e32 v191, 1.0, v191
	v_add_f32_e32 v193, 1.0, v193
	v_exp_f32_e32 v229, v229
	v_exp_f32_e32 v230, v230
	v_exp_f32_e32 v231, v231
	v_exp_f32_e32 v232, v232
	v_exp_f32_e32 v233, v233
	v_mul_f32_e32 v236, v93, v234
	v_mul_f32_e32 v234, v94, v235
	v_mul_f32_e32 v235, v95, v237
	v_add_f32_e32 v237, 1.0, v238
	v_mul_f32_e32 v238, 0xbfb8aa3b, v97
	v_mul_f32_e32 v239, 0xbfb8aa3b, v98
	global_store_dwordx4 v[154:155], v[168:171], off nt
	v_cvt_pk_bf16_f32 v150, v150, v151
	v_mul_f32_e32 v158, v48, v158
	v_mul_f32_e32 v159, v49, v159
	v_mul_f32_e32 v160, v50, v160
	v_mul_f32_e32 v162, v51, v162
	v_mul_f32_e32 v163, v52, v163
	v_mul_f32_e32 v164, v53, v164
	v_rcp_f32_e32 v176, v176
	v_rcp_f32_e32 v177, v177
	v_rcp_f32_e32 v190, v190
	v_rcp_f32_e32 v191, v191
	v_rcp_f32_e32 v193, v193
	v_add_f32_e32 v196, 1.0, v196
	v_add_f32_e32 v198, 1.0, v198
	v_add_f32_e32 v199, 1.0, v199
	v_exp_f32_e32 v238, v238
	v_exp_f32_e32 v239, v239
	v_mul_f32_e32 v194, 0xbfb8aa3b, v104
	v_mul_f32_e32 v192, 0xbfb8aa3b, v108
	v_mul_f32_e32 v168, v120, v152
	v_mul_f32_e32 v169, v121, v153
	v_cvt_pk_bf16_f32 v151, v158, v159
	v_cvt_pk_bf16_f32 v152, v160, v162
	v_cvt_pk_bf16_f32 v153, v163, v164
	global_store_dwordx4 v[154:155], v[150:153], off offset:256 nt
	v_rcp_f32_e32 v196, v196
	v_rcp_f32_e32 v198, v198
	v_or_b32_e32 v150, 48, v140
	v_rcp_f32_e32 v199, v199
	v_add_f32_e32 v212, 1.0, v212
	v_add_f32_e32 v213, 1.0, v213
	v_add_f32_e32 v216, 1.0, v216
	v_add_f32_e32 v217, 1.0, v217
	v_add_f32_e32 v218, 1.0, v218
	v_exp_f32_e32 v194, v194
	v_exp_f32_e32 v192, v192
	v_ashrrev_i32_e32 v151, 31, v150
	v_rcp_f32_e32 v211, v211
	v_rcp_f32_e32 v212, v212
	v_rcp_f32_e32 v213, v213
	v_rcp_f32_e32 v216, v216
	v_rcp_f32_e32 v217, v217
	v_rcp_f32_e32 v218, v218
	v_add_f32_e32 v219, 1.0, v219
	v_add_f32_e32 v220, 1.0, v220
	v_add_f32_e32 v221, 1.0, v221
	v_add_f32_e32 v222, 1.0, v222
	v_add_f32_e32 v223, 1.0, v223
	v_add_f32_e32 v224, 1.0, v224
	v_mul_f32_e32 v172, 0xbfb8aa3b, v131
	v_mul_f32_e32 v149, 0xbfb8aa3b, v124
	v_lshlrev_b64 v[150:151], 13, v[150:151]
	v_mul_f32_e32 v165, v54, v165
	v_mul_f32_e32 v166, v55, v166
	v_mul_f32_e32 v167, v56, v167
	v_mul_f32_e32 v175, v57, v175
	v_rcp_f32_e32 v219, v219
	v_rcp_f32_e32 v220, v220
	v_rcp_f32_e32 v221, v221
	v_rcp_f32_e32 v222, v222
	v_rcp_f32_e32 v223, v223
	v_rcp_f32_e32 v224, v224
	v_add_f32_e32 v229, 1.0, v229
	v_add_f32_e32 v230, 1.0, v230
	v_add_f32_e32 v231, 1.0, v231
	v_add_f32_e32 v232, 1.0, v232
	v_add_f32_e32 v233, 1.0, v233
	v_exp_f32_e32 v172, v172
	v_exp_f32_e32 v149, v149
	v_lshl_add_u64 v[154:155], v[146:147], 0, v[150:151]
	v_cvt_pk_bf16_f32 v150, v165, v166
	v_cvt_pk_bf16_f32 v151, v167, v175
	v_mul_f32_e32 v176, v58, v176
	v_mul_f32_e32 v177, v59, v177
	v_mul_f32_e32 v190, v63, v190
	v_mul_f32_e32 v191, v64, v191
	v_mul_f32_e32 v193, v65, v193
	v_rcp_f32_e32 v228, v228
	v_rcp_f32_e32 v229, v229
	v_rcp_f32_e32 v230, v230
	v_rcp_f32_e32 v231, v231
	v_rcp_f32_e32 v232, v232
	v_rcp_f32_e32 v233, v233
	v_add_f32_e32 v238, 1.0, v238
	v_add_f32_e32 v239, 1.0, v239
	v_cvt_pk_bf16_f32 v152, v176, v177
	v_cvt_pk_bf16_f32 v153, v185, v186
	global_store_dwordx4 v[154:155], v[150:153], off nt
	v_mul_f32_e32 v196, v66, v196
	v_mul_f32_e32 v198, v67, v198
	v_cvt_pk_bf16_f32 v150, v184, v190
	v_cvt_pk_bf16_f32 v151, v191, v193
	v_mul_f32_e32 v199, v68, v199
	v_rcp_f32_e32 v237, v237
	v_rcp_f32_e32 v238, v238
	v_rcp_f32_e32 v239, v239
	v_add_f32_e32 v194, 1.0, v194
	v_add_f32_e32 v192, 1.0, v192
	v_cvt_pk_bf16_f32 v152, v196, v198
	v_cvt_pk_bf16_f32 v153, v199, v210
	global_store_dwordx4 v[154:155], v[150:153], off offset:256 nt
	v_mul_f32_e32 v211, v72, v211
	v_mul_f32_e32 v212, v73, v212
	v_lshlrev_b64 v[150:151], 13, v[142:143]
	v_mul_f32_e32 v213, v74, v213
	v_mul_f32_e32 v216, v75, v216
	v_mul_f32_e32 v217, v76, v217
	v_mul_f32_e32 v218, v77, v218
	v_rcp_f32_e32 v194, v194
	v_rcp_f32_e32 v192, v192
	v_lshl_add_u64 v[146:147], v[146:147], 0, v[150:151]
	v_cvt_pk_bf16_f32 v150, v207, v208
	v_cvt_pk_bf16_f32 v151, v211, v212
	v_cvt_pk_bf16_f32 v152, v213, v216
	v_cvt_pk_bf16_f32 v153, v217, v218
	v_add_co_u32_e32 v154, vcc, s72, v144
	v_mul_f32_e32 v219, v78, v219
	v_mul_f32_e32 v220, v79, v220
	v_mul_f32_e32 v221, v80, v221
	v_mul_f32_e32 v222, v81, v222
	v_mul_f32_e32 v223, v82, v223
	v_mul_f32_e32 v224, v83, v224
	v_add_f32_e32 v172, 1.0, v172
	v_add_f32_e32 v149, 1.0, v149
	global_store_dwordx4 v[146:147], v[150:153], off nt
	s_mov_b64 s[26:27], 0x120000
	v_addc_co_u32_e32 v155, vcc, 0, v145, vcc
	v_cvt_pk_bf16_f32 v150, v219, v220
	v_cvt_pk_bf16_f32 v151, v221, v222
	v_cvt_pk_bf16_f32 v152, v223, v224
	v_cvt_pk_bf16_f32 v153, v226, v227
	global_store_dwordx4 v[146:147], v[150:153], off offset:256 nt
	v_mul_f32_e32 v228, v87, v228
	v_mul_f32_e32 v229, v88, v229
	v_mul_f32_e32 v230, v89, v230
	v_mul_f32_e32 v231, v90, v231
	v_mul_f32_e32 v232, v91, v232
	v_mul_f32_e32 v233, v92, v233
	v_rcp_f32_e32 v172, v172
	v_rcp_f32_e32 v149, v149
	v_rcp_f32_e32 v161, v189
	v_lshl_add_u64 v[146:147], v[144:145], 0, s[26:27]
	v_cvt_pk_bf16_f32 v150, v225, v228
	v_cvt_pk_bf16_f32 v151, v229, v230
	v_cvt_pk_bf16_f32 v152, v231, v232
	v_cvt_pk_bf16_f32 v153, v233, v236
	global_store_dwordx4 v[154:155], v[150:153], off nt
	s_mov_b64 s[26:27], 0x140000
	v_add_co_u32_e32 v154, vcc, s73, v144
	v_mul_f32_e32 v237, v96, v237
	v_mul_f32_e32 v238, v97, v238
	v_mul_f32_e32 v239, v98, v239
	v_mul_f32_e32 v195, v99, v195
	v_cvt_pk_bf16_f32 v150, v234, v235
	v_cvt_pk_bf16_f32 v151, v237, v238
	v_cvt_pk_bf16_f32 v152, v239, v195
	v_cvt_pk_bf16_f32 v153, v206, v209
	global_store_dwordx4 v[146:147], v[150:153], off offset:256 nt
	v_lshl_add_u64 v[146:147], v[144:145], 0, s[26:27]
	v_addc_co_u32_e32 v155, vcc, 0, v145, vcc
	s_mov_b64 s[26:27], 0x160000
	v_mul_f32_e32 v194, v104, v194
	v_mul_f32_e32 v192, v108, v192
	v_cvt_pk_bf16_f32 v150, v241, v242
	v_cvt_pk_bf16_f32 v151, v194, v197
	v_cvt_pk_bf16_f32 v152, v240, v243
	v_cvt_pk_bf16_f32 v153, v192, v204
	global_store_dwordx4 v[154:155], v[150:153], off nt
	v_lshl_add_u64 v[154:155], v[144:145], 0, s[26:27]
	v_add_co_u32_e32 v144, vcc, 0x160000, v144
	v_mul_f32_e32 v173, v117, v173
	v_cvt_pk_bf16_f32 v150, v205, v187
	v_cvt_pk_bf16_f32 v151, v244, v245
	v_cvt_pk_bf16_f32 v152, v182, v200
	v_cvt_pk_bf16_f32 v153, v201, v173
	global_store_dwordx4 v[146:147], v[150:153], off offset:256 nt
	v_addc_co_u32_e32 v145, vcc, 0, v145, vcc
	v_mul_f32_e32 v172, v131, v172
	v_mul_f32_e32 v149, v124, v149
	v_mul_f32_e32 v157, v118, v157
	v_mul_f32_e32 v161, v119, v161
	v_cvt_pk_bf16_f32 v150, v183, v172
	v_cvt_pk_bf16_f32 v151, v174, v202
	v_cvt_pk_bf16_f32 v152, v203, v178
	v_cvt_pk_bf16_f32 v153, v179, v180
	global_store_dwordx4 v[144:145], v[150:153], off nt
	v_cvt_pk_bf16_f32 v144, v181, v188
	v_cvt_pk_bf16_f32 v145, v149, v156
	v_cvt_pk_bf16_f32 v146, v157, v161
	v_cvt_pk_bf16_f32 v147, v168, v169
	global_store_dwordx4 v[154:155], v[144:147], off offset:256 nt
	s_mov_b64 s[26:27], 0

.LBB0_346:
	s_add_u32 s54, s33, 0xffffff80
	s_addc_u32 s55, s52, -1
	s_cmp_eq_u32 s53, 60
	s_cselect_b32 s28, s2, s33
	s_cselect_b32 s29, s1, s52
	s_cselect_b32 s31, s11, s23
	s_cselect_b32 s30, s15, s19
	s_add_u32 s24, s28, 0x80
	s_addc_u32 s25, s29, 0
	s_add_u32 s26, s30, 0x80
	s_addc_u32 s27, s31, 0
	s_add_i32 s56, 0, 0x10000
	s_add_i32 s57, 0, 0x14000
	v_add_u32_e32 v152, s56, v1
	v_add_u32_e32 v168, s57, v1
	ds_read_b128 v[140:143], v152
	ds_read_b128 v[144:147], v152 offset:1024
	ds_read_b128 v[148:151], v152 offset:2048
	ds_read_b128 v[152:155], v152 offset:3072
	ds_read_b128 v[156:159], v168
	ds_read_b128 v[160:163], v168 offset:1024
	ds_read_b128 v[164:167], v168 offset:2048
	ds_read_b128 v[168:171], v168 offset:3072
	s_add_u32 s54, s54, 0x100000
	s_addc_u32 s55, s55, 0
	v_lshl_add_u64 v[204:205], s[54:55], 0, v[2:3]
	s_add_i32 m0, s41, 0xc000
	ds_read_b128 v[172:175], v5
	ds_read_b128 v[176:179], v5 offset:1024
	ds_read_b128 v[180:183], v5 offset:2048
	ds_read_b128 v[184:187], v5 offset:3072
	ds_read_b128 v[188:191], v5 offset:4096
	ds_read_b128 v[192:195], v5 offset:5120
	ds_read_b128 v[196:199], v5 offset:6144
	ds_read_b128 v[200:203], v5 offset:7168
	global_load_lds_dwordx4 v[204:205], off
	v_lshl_add_u64 v[204:205], s[54:55], 0, v[136:137]
	s_add_i32 m0, s41, 0xe000
	s_nop 0
	global_load_lds_dwordx4 v[204:205], off
	s_waitcnt vmcnt(8)
	s_waitcnt lgkmcnt(0)
	s_setprio 1
	s_barrier
	v_mfma_f32_16x16x32_bf16 v[130:133], v[140:143], v[172:175], v[130:133]
	v_mfma_f32_16x16x32_bf16 v[126:129], v[148:151], v[172:175], v[126:129]
	v_mfma_f32_16x16x32_bf16 v[114:117], v[140:143], v[180:183], v[114:117]
	v_mfma_f32_16x16x32_bf16 v[110:113], v[148:151], v[180:183], v[110:113]
	v_mfma_f32_16x16x32_bf16 v[98:101], v[140:143], v[188:191], v[98:101]
	v_mfma_f32_16x16x32_bf16 v[94:97], v[148:151], v[188:191], v[94:97]
	v_mfma_f32_16x16x32_bf16 v[82:85], v[140:143], v[196:199], v[82:85]
	v_mfma_f32_16x16x32_bf16 v[78:81], v[148:151], v[196:199], v[78:81]
	v_mfma_f32_16x16x32_bf16 v[130:133], v[144:147], v[176:179], v[130:133]
	v_mfma_f32_16x16x32_bf16 v[126:129], v[152:155], v[176:179], v[126:129]
	v_mfma_f32_16x16x32_bf16 v[114:117], v[144:147], v[184:187], v[114:117]
	v_mfma_f32_16x16x32_bf16 v[110:113], v[152:155], v[184:187], v[110:113]
	v_mfma_f32_16x16x32_bf16 v[98:101], v[144:147], v[192:195], v[98:101]
	v_mfma_f32_16x16x32_bf16 v[94:97], v[152:155], v[192:195], v[94:97]
	v_mfma_f32_16x16x32_bf16 v[82:85], v[144:147], v[200:203], v[82:85]
	v_mfma_f32_16x16x32_bf16 v[78:81], v[152:155], v[200:203], v[78:81]
	s_setprio 0
	s_setprio 1
	v_mfma_f32_16x16x32_bf16 v[122:125], v[156:159], v[172:175], v[122:125]
	v_mfma_f32_16x16x32_bf16 v[118:121], v[164:167], v[172:175], v[118:121]
	v_mfma_f32_16x16x32_bf16 v[106:109], v[156:159], v[180:183], v[106:109]
	v_mfma_f32_16x16x32_bf16 v[102:105], v[164:167], v[180:183], v[102:105]
	v_mfma_f32_16x16x32_bf16 v[90:93], v[156:159], v[188:191], v[90:93]
	v_mfma_f32_16x16x32_bf16 v[86:89], v[164:167], v[188:191], v[86:89]
	v_mfma_f32_16x16x32_bf16 v[74:77], v[156:159], v[196:199], v[74:77]
	v_mfma_f32_16x16x32_bf16 v[70:73], v[164:167], v[196:199], v[70:73]
	v_mfma_f32_16x16x32_bf16 v[122:125], v[160:163], v[176:179], v[122:125]
	v_mfma_f32_16x16x32_bf16 v[118:121], v[168:171], v[176:179], v[118:121]
	v_mfma_f32_16x16x32_bf16 v[106:109], v[160:163], v[184:187], v[106:109]
	v_mfma_f32_16x16x32_bf16 v[102:105], v[168:171], v[184:187], v[102:105]
	v_mfma_f32_16x16x32_bf16 v[90:93], v[160:163], v[192:195], v[90:93]
	v_mfma_f32_16x16x32_bf16 v[86:89], v[168:171], v[192:195], v[86:89]
	v_mfma_f32_16x16x32_bf16 v[74:77], v[160:163], v[200:203], v[74:77]
	v_mfma_f32_16x16x32_bf16 v[70:73], v[168:171], v[200:203], v[70:73]
	s_barrier
	s_setprio 0
	s_add_i32 s54, s56, s38
	v_lshl_add_u64 v[204:205], s[30:31], 0, v[134:135]
	s_mov_b32 m0, s54
	ds_read_b128 v[172:175], v5 offset:16384
	ds_read_b128 v[176:179], v5 offset:17408
	ds_read_b128 v[180:183], v5 offset:18432
	ds_read_b128 v[184:187], v5 offset:19456
	ds_read_b128 v[188:191], v5 offset:20480
	ds_read_b128 v[192:195], v5 offset:21504
	ds_read_b128 v[196:199], v5 offset:22528
	ds_read_b128 v[200:203], v5 offset:23552
	global_load_lds_dwordx4 v[204:205], off
	s_add_i32 m0, s54, 0x2000
	v_lshl_add_u64 v[204:205], s[30:31], 0, v[138:139]
	s_add_u32 s30, s30, 0x100000
	s_addc_u32 s31, s31, 0
	s_add_i32 s54, s57, s38
	global_load_lds_dwordx4 v[204:205], off
	v_lshl_add_u64 v[204:205], s[30:31], 0, v[134:135]
	s_mov_b32 m0, s54
	s_nop 0
	global_load_lds_dwordx4 v[204:205], off
	v_lshl_add_u64 v[204:205], s[30:31], 0, v[138:139]
	s_add_i32 m0, s54, 0x2000
	s_nop 0
	global_load_lds_dwordx4 v[204:205], off
	v_lshl_add_u64 v[204:205], s[28:29], 0, v[2:3]
	s_mov_b32 m0, s41
	s_nop 0
	global_load_lds_dwordx4 v[204:205], off
	v_lshl_add_u64 v[204:205], s[28:29], 0, v[136:137]
	s_mov_b32 m0, s3
	s_nop 0
	global_load_lds_dwordx4 v[204:205], off
	s_waitcnt vmcnt(8)
	s_waitcnt lgkmcnt(0)
	s_setprio 1
	s_barrier
	v_mfma_f32_16x16x32_bf16 v[66:69], v[140:143], v[172:175], v[66:69]
	v_mfma_f32_16x16x32_bf16 v[62:65], v[148:151], v[172:175], v[62:65]
	v_mfma_f32_16x16x32_bf16 v[50:53], v[140:143], v[180:183], v[50:53]
	v_mfma_f32_16x16x32_bf16 v[46:49], v[148:151], v[180:183], v[46:49]
	v_mfma_f32_16x16x32_bf16 v[34:37], v[140:143], v[188:191], v[34:37]
	v_mfma_f32_16x16x32_bf16 v[30:33], v[148:151], v[188:191], v[30:33]
	v_mfma_f32_16x16x32_bf16 v[18:21], v[140:143], v[196:199], v[18:21]
	v_mfma_f32_16x16x32_bf16 v[14:17], v[148:151], v[196:199], v[14:17]
	v_mfma_f32_16x16x32_bf16 v[66:69], v[144:147], v[176:179], v[66:69]
	v_mfma_f32_16x16x32_bf16 v[62:65], v[152:155], v[176:179], v[62:65]
	v_mfma_f32_16x16x32_bf16 v[50:53], v[144:147], v[184:187], v[50:53]
	v_mfma_f32_16x16x32_bf16 v[46:49], v[152:155], v[184:187], v[46:49]
	v_mfma_f32_16x16x32_bf16 v[34:37], v[144:147], v[192:195], v[34:37]
	v_mfma_f32_16x16x32_bf16 v[30:33], v[152:155], v[192:195], v[30:33]
	v_mfma_f32_16x16x32_bf16 v[18:21], v[144:147], v[200:203], v[18:21]
	v_mfma_f32_16x16x32_bf16 v[14:17], v[152:155], v[200:203], v[14:17]
	s_setprio 0
	s_setprio 1
	v_mfma_f32_16x16x32_bf16 v[58:61], v[156:159], v[172:175], v[58:61]
	v_mfma_f32_16x16x32_bf16 v[54:57], v[164:167], v[172:175], v[54:57]
	v_mfma_f32_16x16x32_bf16 v[42:45], v[156:159], v[180:183], v[42:45]
	v_mfma_f32_16x16x32_bf16 v[38:41], v[164:167], v[180:183], v[38:41]
	v_mfma_f32_16x16x32_bf16 v[26:29], v[156:159], v[188:191], v[26:29]
	v_mfma_f32_16x16x32_bf16 v[22:25], v[164:167], v[188:191], v[22:25]
	v_mfma_f32_16x16x32_bf16 v[10:13], v[156:159], v[196:199], v[10:13]
	v_mfma_f32_16x16x32_bf16 v[6:9], v[164:167], v[196:199], v[6:9]
	v_mfma_f32_16x16x32_bf16 v[58:61], v[160:163], v[176:179], v[58:61]
	v_mfma_f32_16x16x32_bf16 v[54:57], v[168:171], v[176:179], v[54:57]
	v_mfma_f32_16x16x32_bf16 v[42:45], v[160:163], v[184:187], v[42:45]
	v_mfma_f32_16x16x32_bf16 v[38:41], v[168:171], v[184:187], v[38:41]
	v_mfma_f32_16x16x32_bf16 v[26:29], v[160:163], v[192:195], v[26:29]
	v_mfma_f32_16x16x32_bf16 v[22:25], v[168:171], v[192:195], v[22:25]
	v_mfma_f32_16x16x32_bf16 v[10:13], v[160:163], v[200:203], v[10:13]
	v_mfma_f32_16x16x32_bf16 v[6:9], v[168:171], v[200:203], v[6:9]
	s_barrier
	s_setprio 0
	s_add_i32 s30, 0, 0x18000
	s_add_i32 s31, 0, 0x1c000
	v_add_u32_e32 v152, s30, v1
	v_add_u32_e32 v168, s31, v1
	ds_read_b128 v[140:143], v152
	ds_read_b128 v[144:147], v152 offset:1024
	ds_read_b128 v[148:151], v152 offset:2048
	ds_read_b128 v[152:155], v152 offset:3072
	ds_read_b128 v[156:159], v168
	ds_read_b128 v[160:163], v168 offset:1024
	ds_read_b128 v[164:167], v168 offset:2048
	ds_read_b128 v[168:171], v168 offset:3072
	s_add_u32 s28, s28, 0x100000
	s_addc_u32 s29, s29, 0
	s_mov_b32 m0, s43
	v_lshl_add_u64 v[204:205], s[28:29], 0, v[2:3]
	ds_read_b128 v[172:175], v5 offset:32768
	ds_read_b128 v[176:179], v5 offset:33792
	ds_read_b128 v[180:183], v5 offset:34816
	ds_read_b128 v[184:187], v5 offset:35840
	ds_read_b128 v[188:191], v5 offset:36864
	ds_read_b128 v[192:195], v5 offset:37888
	ds_read_b128 v[196:199], v5 offset:38912
	ds_read_b128 v[200:203], v5 offset:39936
	global_load_lds_dwordx4 v[204:205], off
	v_lshl_add_u64 v[204:205], s[28:29], 0, v[136:137]
	s_mov_b32 m0, s46
	s_nop 0
	global_load_lds_dwordx4 v[204:205], off
	s_waitcnt vmcnt(8)
	s_waitcnt lgkmcnt(0)
	s_setprio 1
	s_barrier
	v_mfma_f32_16x16x32_bf16 v[130:133], v[140:143], v[172:175], v[130:133]
	v_mfma_f32_16x16x32_bf16 v[126:129], v[148:151], v[172:175], v[126:129]
	v_mfma_f32_16x16x32_bf16 v[114:117], v[140:143], v[180:183], v[114:117]
	v_mfma_f32_16x16x32_bf16 v[110:113], v[148:151], v[180:183], v[110:113]
	v_mfma_f32_16x16x32_bf16 v[98:101], v[140:143], v[188:191], v[98:101]
	v_mfma_f32_16x16x32_bf16 v[94:97], v[148:151], v[188:191], v[94:97]
	v_mfma_f32_16x16x32_bf16 v[82:85], v[140:143], v[196:199], v[82:85]
	v_mfma_f32_16x16x32_bf16 v[78:81], v[148:151], v[196:199], v[78:81]
	v_mfma_f32_16x16x32_bf16 v[130:133], v[144:147], v[176:179], v[130:133]
	v_mfma_f32_16x16x32_bf16 v[126:129], v[152:155], v[176:179], v[126:129]
	v_mfma_f32_16x16x32_bf16 v[114:117], v[144:147], v[184:187], v[114:117]
	v_mfma_f32_16x16x32_bf16 v[110:113], v[152:155], v[184:187], v[110:113]
	v_mfma_f32_16x16x32_bf16 v[98:101], v[144:147], v[192:195], v[98:101]
	v_mfma_f32_16x16x32_bf16 v[94:97], v[152:155], v[192:195], v[94:97]
	v_mfma_f32_16x16x32_bf16 v[82:85], v[144:147], v[200:203], v[82:85]
	v_mfma_f32_16x16x32_bf16 v[78:81], v[152:155], v[200:203], v[78:81]
	s_setprio 0
	s_setprio 1
	v_mfma_f32_16x16x32_bf16 v[122:125], v[156:159], v[172:175], v[122:125]
	v_mfma_f32_16x16x32_bf16 v[118:121], v[164:167], v[172:175], v[118:121]
	v_mfma_f32_16x16x32_bf16 v[106:109], v[156:159], v[180:183], v[106:109]
	v_mfma_f32_16x16x32_bf16 v[102:105], v[164:167], v[180:183], v[102:105]
	v_mfma_f32_16x16x32_bf16 v[90:93], v[156:159], v[188:191], v[90:93]
	v_mfma_f32_16x16x32_bf16 v[86:89], v[164:167], v[188:191], v[86:89]
	v_mfma_f32_16x16x32_bf16 v[74:77], v[156:159], v[196:199], v[74:77]
	v_mfma_f32_16x16x32_bf16 v[70:73], v[164:167], v[196:199], v[70:73]
	v_mfma_f32_16x16x32_bf16 v[122:125], v[160:163], v[176:179], v[122:125]
	v_mfma_f32_16x16x32_bf16 v[118:121], v[168:171], v[176:179], v[118:121]
	v_mfma_f32_16x16x32_bf16 v[106:109], v[160:163], v[184:187], v[106:109]
	v_mfma_f32_16x16x32_bf16 v[102:105], v[168:171], v[184:187], v[102:105]
	v_mfma_f32_16x16x32_bf16 v[90:93], v[160:163], v[192:195], v[90:93]
	v_mfma_f32_16x16x32_bf16 v[86:89], v[168:171], v[192:195], v[86:89]
	v_mfma_f32_16x16x32_bf16 v[74:77], v[160:163], v[200:203], v[74:77]
	v_mfma_f32_16x16x32_bf16 v[70:73], v[168:171], v[200:203], v[70:73]
	s_barrier
	s_setprio 0
	s_add_i32 s28, s30, s38
	v_lshl_add_u64 v[204:205], s[26:27], 0, v[134:135]
	s_mov_b32 m0, s28
	ds_read_b128 v[172:175], v5 offset:49152
	ds_read_b128 v[176:179], v5 offset:50176
	ds_read_b128 v[180:183], v5 offset:51200
	ds_read_b128 v[184:187], v5 offset:52224
	ds_read_b128 v[188:191], v5 offset:53248
	ds_read_b128 v[192:195], v5 offset:54272
	ds_read_b128 v[196:199], v5 offset:55296
	ds_read_b128 v[200:203], v5 offset:56320
	global_load_lds_dwordx4 v[204:205], off
	s_add_i32 m0, s28, 0x2000
	v_lshl_add_u64 v[204:205], s[26:27], 0, v[138:139]
	s_add_u32 s26, s26, 0x100000
	s_addc_u32 s27, s27, 0
	s_add_i32 s28, s31, s38
	global_load_lds_dwordx4 v[204:205], off
	v_lshl_add_u64 v[204:205], s[26:27], 0, v[134:135]
	s_mov_b32 m0, s28
	s_nop 0
	global_load_lds_dwordx4 v[204:205], off
	v_lshl_add_u64 v[204:205], s[26:27], 0, v[138:139]
	s_add_i32 m0, s28, 0x2000
	s_nop 0
	global_load_lds_dwordx4 v[204:205], off
	v_lshl_add_u64 v[204:205], s[24:25], 0, v[2:3]
	s_mov_b32 m0, s49
	s_nop 0
	global_load_lds_dwordx4 v[204:205], off
	v_lshl_add_u64 v[204:205], s[24:25], 0, v[136:137]
	s_mov_b32 m0, s50
	s_nop 0
	global_load_lds_dwordx4 v[204:205], off
	s_waitcnt vmcnt(8)
	s_waitcnt lgkmcnt(0)
	s_setprio 1
	s_barrier
	v_mfma_f32_16x16x32_bf16 v[66:69], v[140:143], v[172:175], v[66:69]
	v_mfma_f32_16x16x32_bf16 v[62:65], v[148:151], v[172:175], v[62:65]
	v_mfma_f32_16x16x32_bf16 v[50:53], v[140:143], v[180:183], v[50:53]
	v_mfma_f32_16x16x32_bf16 v[46:49], v[148:151], v[180:183], v[46:49]
	v_mfma_f32_16x16x32_bf16 v[34:37], v[140:143], v[188:191], v[34:37]
	v_mfma_f32_16x16x32_bf16 v[30:33], v[148:151], v[188:191], v[30:33]
	v_mfma_f32_16x16x32_bf16 v[18:21], v[140:143], v[196:199], v[18:21]
	v_mfma_f32_16x16x32_bf16 v[14:17], v[148:151], v[196:199], v[14:17]
	v_mfma_f32_16x16x32_bf16 v[66:69], v[144:147], v[176:179], v[66:69]
	v_mfma_f32_16x16x32_bf16 v[62:65], v[152:155], v[176:179], v[62:65]
	v_mfma_f32_16x16x32_bf16 v[50:53], v[144:147], v[184:187], v[50:53]
	v_mfma_f32_16x16x32_bf16 v[46:49], v[152:155], v[184:187], v[46:49]
	v_mfma_f32_16x16x32_bf16 v[34:37], v[144:147], v[192:195], v[34:37]
	v_mfma_f32_16x16x32_bf16 v[30:33], v[152:155], v[192:195], v[30:33]
	v_mfma_f32_16x16x32_bf16 v[18:21], v[144:147], v[200:203], v[18:21]
	v_mfma_f32_16x16x32_bf16 v[14:17], v[152:155], v[200:203], v[14:17]
	s_setprio 0
	s_setprio 1
	v_mfma_f32_16x16x32_bf16 v[58:61], v[156:159], v[172:175], v[58:61]
	v_mfma_f32_16x16x32_bf16 v[54:57], v[164:167], v[172:175], v[54:57]
	v_mfma_f32_16x16x32_bf16 v[42:45], v[156:159], v[180:183], v[42:45]
	v_mfma_f32_16x16x32_bf16 v[38:41], v[164:167], v[180:183], v[38:41]
	v_mfma_f32_16x16x32_bf16 v[26:29], v[156:159], v[188:191], v[26:29]
	v_mfma_f32_16x16x32_bf16 v[22:25], v[164:167], v[188:191], v[22:25]
	v_mfma_f32_16x16x32_bf16 v[10:13], v[156:159], v[196:199], v[10:13]
	v_mfma_f32_16x16x32_bf16 v[6:9], v[164:167], v[196:199], v[6:9]
	v_mfma_f32_16x16x32_bf16 v[58:61], v[160:163], v[176:179], v[58:61]
	v_mfma_f32_16x16x32_bf16 v[54:57], v[168:171], v[176:179], v[54:57]
	v_mfma_f32_16x16x32_bf16 v[42:45], v[160:163], v[184:187], v[42:45]
	v_mfma_f32_16x16x32_bf16 v[38:41], v[168:171], v[184:187], v[38:41]
	v_mfma_f32_16x16x32_bf16 v[26:29], v[160:163], v[192:195], v[26:29]
	v_mfma_f32_16x16x32_bf16 v[22:25], v[168:171], v[192:195], v[22:25]
	v_mfma_f32_16x16x32_bf16 v[10:13], v[160:163], v[200:203], v[10:13]
	v_mfma_f32_16x16x32_bf16 v[6:9], v[168:171], v[200:203], v[6:9]
	s_barrier
	s_setprio 0
	s_add_i32 s53, s53, 2
	s_add_u32 s19, s19, 0x100
	s_addc_u32 s23, s23, 0
	s_add_u32 s33, s33, 0x100
	s_addc_u32 s52, s52, 0
	s_cmp_gt_u32 s53, 61
	s_cbranch_scc0 .LBB0_346
	v_mov_b32_e32 v140, v0
	s_lshl_b32 s1, s0, 8
	s_mov_b64 s[24:25], s[84:85]
	s_add_i32 s1, s1, s47
	v_bfe_u32 v210, v140, 4, 2
	v_and_or_b32 v140, v140, 15, s1
	s_add_u32 s26, s24, s6
	s_addc_u32 s27, s25, s7
	v_ashrrev_i32_e32 v141, 31, v140
	v_lshl_add_u64 v[142:143], v[140:141], 2, s[26:27]
	s_mov_b64 s[26:27], 0x10000
	v_lshl_add_u64 v[154:155], v[142:143], 0, s[26:27]
	v_add_co_u32_e32 v142, vcc, s91, v142
	s_cmp_gt_i32 s22, 3
	s_nop 0
	v_addc_co_u32_e32 v143, vcc, 0, v143, vcc
	global_load_dword v142, v[142:143], off
	s_cselect_b64 s[28:29], -1, 0
	s_cmp_lt_i32 s22, 4
	s_cselect_b64 s[26:27], -1, 0
	global_load_dword v205, v[154:155], off offset:64
	global_load_dword v204, v[154:155], off offset:128
	global_load_dword v203, v[154:155], off offset:192
	global_load_dword v202, v[154:155], off offset:512
	global_load_dword v201, v[154:155], off offset:576
	global_load_dword v200, v[154:155], off offset:640
	global_load_dword v199, v[154:155], off offset:704
	s_waitcnt vmcnt(0)
	v_fmamk_f32 v142, v142, 0x39800000, v246
	v_cmp_gt_f32_e32 vcc, s95, v142
	v_mul_f32_e32 v143, 0x4b800000, v142
	s_nop 0
	v_cndmask_b32_e32 v142, v142, v143, vcc
	v_rsq_f32_e32 v142, v142
	s_nop 0
	v_mul_f32_e32 v143, 0x45800000, v142
	v_cndmask_b32_e32 v142, v142, v143, vcc
	v_pk_mul_f32 v[132:133], v[132:133], v[142:143] op_sel_hi:[1,0]
	v_pk_mul_f32 v[130:131], v[130:131], v[142:143] op_sel_hi:[1,0]
	v_pk_mul_f32 v[128:129], v[128:129], v[142:143] op_sel_hi:[1,0]
	v_pk_mul_f32 v[126:127], v[126:127], v[142:143] op_sel_hi:[1,0]
	v_pk_mul_f32 v[124:125], v[124:125], v[142:143] op_sel_hi:[1,0]
	v_pk_mul_f32 v[122:123], v[122:123], v[142:143] op_sel_hi:[1,0]
	v_pk_mul_f32 v[120:121], v[120:121], v[142:143] op_sel_hi:[1,0]
	v_pk_mul_f32 v[118:119], v[118:119], v[142:143] op_sel_hi:[1,0]
	s_waitcnt vmcnt(0)
	v_fmamk_f32 v142, v205, 0x39800000, v246
	v_cmp_gt_f32_e32 vcc, s95, v142
	v_mul_f32_e32 v143, 0x4b800000, v142
	s_nop 0
	v_cndmask_b32_e32 v142, v142, v143, vcc
	v_rsq_f32_e32 v142, v142
	s_nop 0
	v_mul_f32_e32 v143, 0x45800000, v142
	v_cndmask_b32_e32 v142, v142, v143, vcc
	v_pk_mul_f32 v[116:117], v[116:117], v[142:143] op_sel_hi:[1,0]
	v_pk_mul_f32 v[114:115], v[114:115], v[142:143] op_sel_hi:[1,0]
	v_pk_mul_f32 v[112:113], v[112:113], v[142:143] op_sel_hi:[1,0]
	v_pk_mul_f32 v[110:111], v[110:111], v[142:143] op_sel_hi:[1,0]
	v_pk_mul_f32 v[108:109], v[108:109], v[142:143] op_sel_hi:[1,0]
	v_pk_mul_f32 v[106:107], v[106:107], v[142:143] op_sel_hi:[1,0]
	v_pk_mul_f32 v[104:105], v[104:105], v[142:143] op_sel_hi:[1,0]
	v_pk_mul_f32 v[102:103], v[102:103], v[142:143] op_sel_hi:[1,0]
	s_waitcnt vmcnt(0)
	v_fmamk_f32 v142, v204, 0x39800000, v246
	v_cmp_gt_f32_e32 vcc, s95, v142
	v_mul_f32_e32 v143, 0x4b800000, v142
	s_nop 0
	v_cndmask_b32_e32 v142, v142, v143, vcc
	v_rsq_f32_e32 v142, v142
	s_nop 0
	v_mul_f32_e32 v143, 0x45800000, v142
	v_cndmask_b32_e32 v142, v142, v143, vcc
	v_pk_mul_f32 v[150:151], v[94:95], v[142:143] op_sel_hi:[1,0]
	v_pk_mul_f32 v[152:153], v[98:99], v[142:143] op_sel_hi:[1,0]
	v_pk_mul_f32 v[100:101], v[100:101], v[142:143] op_sel_hi:[1,0]
	v_pk_mul_f32 v[92:93], v[92:93], v[142:143] op_sel_hi:[1,0]
	v_pk_mul_f32 v[90:91], v[90:91], v[142:143] op_sel_hi:[1,0]
	v_pk_mul_f32 v[86:87], v[86:87], v[142:143] op_sel_hi:[1,0]
	v_pk_mul_f32 v[96:97], v[96:97], v[142:143] op_sel_hi:[1,0]
	v_pk_mul_f32 v[88:89], v[88:89], v[142:143] op_sel_hi:[1,0]
	s_waitcnt vmcnt(0)
	v_fmamk_f32 v94, v203, 0x39800000, v246
	v_cmp_gt_f32_e32 vcc, s95, v94
	v_mul_f32_e32 v95, 0x4b800000, v94
	s_nop 0
	v_cndmask_b32_e32 v94, v94, v95, vcc
	v_rsq_f32_e32 v94, v94
	s_nop 0
	v_mul_f32_e32 v95, 0x45800000, v94
	v_cndmask_b32_e32 v94, v94, v95, vcc
	v_pk_mul_f32 v[164:165], v[80:81], v[94:95] op_sel_hi:[1,0]
	v_pk_mul_f32 v[80:81], v[74:75], v[94:95] op_sel_hi:[1,0]
	v_pk_mul_f32 v[166:167], v[84:85], v[94:95] op_sel_hi:[1,0]
	v_pk_mul_f32 v[170:171], v[82:83], v[94:95] op_sel_hi:[1,0]
	v_pk_mul_f32 v[168:169], v[78:79], v[94:95] op_sel_hi:[1,0]
	v_pk_mul_f32 v[78:79], v[76:77], v[94:95] op_sel_hi:[1,0]
	v_pk_mul_f32 v[72:73], v[72:73], v[94:95] op_sel_hi:[1,0]
	v_pk_mul_f32 v[70:71], v[70:71], v[94:95] op_sel_hi:[1,0]
	s_waitcnt vmcnt(0)
	v_fmamk_f32 v74, v202, 0x39800000, v246
	v_cmp_gt_f32_e32 vcc, s95, v74
	v_mul_f32_e32 v75, 0x4b800000, v74
	s_nop 0
	v_cndmask_b32_e32 v74, v74, v75, vcc
	v_rsq_f32_e32 v74, v74
	s_nop 0
	v_mul_f32_e32 v75, 0x45800000, v74
	v_cndmask_b32_e32 v98, v74, v75, vcc
	v_pk_mul_f32 v[76:77], v[68:69], v[98:99] op_sel_hi:[1,0]
	v_pk_mul_f32 v[176:177], v[66:67], v[98:99] op_sel_hi:[1,0]
	v_pk_mul_f32 v[74:75], v[64:65], v[98:99] op_sel_hi:[1,0]
	v_pk_mul_f32 v[174:175], v[62:63], v[98:99] op_sel_hi:[1,0]
	v_pk_mul_f32 v[84:85], v[60:61], v[98:99] op_sel_hi:[1,0]
	v_pk_mul_f32 v[94:95], v[58:59], v[98:99] op_sel_hi:[1,0]
	v_pk_mul_f32 v[82:83], v[56:57], v[98:99] op_sel_hi:[1,0]
	v_pk_mul_f32 v[98:99], v[54:55], v[98:99] op_sel_hi:[1,0]
	s_waitcnt vmcnt(0)
	v_fmamk_f32 v54, v201, 0x39800000, v246
	v_cmp_gt_f32_e32 vcc, s95, v54
	v_mul_f32_e32 v55, 0x4b800000, v54
	s_nop 0
	v_cndmask_b32_e32 v54, v54, v55, vcc
	v_rsq_f32_e32 v54, v54
	s_nop 0
	v_mul_f32_e32 v55, 0x45800000, v54
	v_cndmask_b32_e32 v54, v54, v55, vcc
	v_pk_mul_f32 v[146:147], v[38:39], v[54:55] op_sel_hi:[1,0]
	v_pk_mul_f32 v[180:181], v[52:53], v[54:55] op_sel_hi:[1,0]
	v_pk_mul_f32 v[184:185], v[50:51], v[54:55] op_sel_hi:[1,0]
	v_pk_mul_f32 v[144:145], v[44:45], v[54:55] op_sel_hi:[1,0]
	v_pk_mul_f32 v[148:149], v[42:43], v[54:55] op_sel_hi:[1,0]
	v_pk_mul_f32 v[182:183], v[46:47], v[54:55] op_sel_hi:[1,0]
	v_pk_mul_f32 v[178:179], v[48:49], v[54:55] op_sel_hi:[1,0]
	v_pk_mul_f32 v[142:143], v[40:41], v[54:55] op_sel_hi:[1,0]
	s_waitcnt vmcnt(0)
	v_fmamk_f32 v38, v200, 0x39800000, v246
	v_cmp_gt_f32_e32 vcc, s95, v38
	v_mul_f32_e32 v39, 0x4b800000, v38
	s_nop 0
	v_cndmask_b32_e32 v38, v38, v39, vcc
	v_rsq_f32_e32 v38, v38
	s_nop 0
	v_mul_f32_e32 v39, 0x45800000, v38
	v_cndmask_b32_e32 v38, v38, v39, vcc
	v_pk_mul_f32 v[160:161], v[22:23], v[38:39] op_sel_hi:[1,0]
	v_pk_mul_f32 v[188:189], v[36:37], v[38:39] op_sel_hi:[1,0]
	v_pk_mul_f32 v[192:193], v[34:35], v[38:39] op_sel_hi:[1,0]
	v_pk_mul_f32 v[158:159], v[28:29], v[38:39] op_sel_hi:[1,0]
	v_pk_mul_f32 v[162:163], v[26:27], v[38:39] op_sel_hi:[1,0]
	v_pk_mul_f32 v[186:187], v[32:33], v[38:39] op_sel_hi:[1,0]
	v_pk_mul_f32 v[190:191], v[30:31], v[38:39] op_sel_hi:[1,0]
	v_pk_mul_f32 v[156:157], v[24:25], v[38:39] op_sel_hi:[1,0]
	v_mul_f32_e32 v24, v95, v95
	v_mul_f32_e32 v25, v85, v85
	v_mul_f32_e32 v26, v185, v185
	v_mul_f32_e32 v27, v181, v181
	v_mul_f32_e32 v28, v149, v149
	v_mul_f32_e32 v29, v145, v145
	v_mul_f32_e32 v30, v193, v193
	v_mul_f32_e32 v31, v189, v189
	v_mul_f32_e32 v32, v163, v163
	v_mul_f32_e32 v33, v159, v159
	v_fmac_f32_e32 v24, v94, v94
	v_fmac_f32_e32 v25, v84, v84
	v_fmac_f32_e32 v26, v184, v184
	v_fmac_f32_e32 v27, v180, v180
	v_fmac_f32_e32 v28, v148, v148
	v_fmac_f32_e32 v29, v144, v144
	v_fmac_f32_e32 v30, v192, v192
	v_fmac_f32_e32 v31, v188, v188
	v_fmac_f32_e32 v32, v162, v162
	v_fmac_f32_e32 v33, v158, v158
	v_add_f32_e32 v24, v24, v25
	v_mul_f32_e32 v25, v99, v99
	v_add_f32_e32 v26, v26, v27
	v_mul_f32_e32 v27, v183, v183
	v_add_f32_e32 v28, v28, v29
	v_mul_f32_e32 v29, v147, v147
	v_add_f32_e32 v30, v30, v31
	v_mul_f32_e32 v31, v191, v191
	v_add_f32_e32 v32, v32, v33
	v_mul_f32_e32 v33, v161, v161
	v_fmac_f32_e32 v25, v98, v98
	v_fmac_f32_e32 v27, v182, v182
	v_fmac_f32_e32 v29, v146, v146
	v_fmac_f32_e32 v31, v190, v190
	v_fmac_f32_e32 v33, v160, v160
	v_add_f32_e32 v24, v25, v24
	v_mul_f32_e32 v25, v83, v83
	v_add_f32_e32 v26, v27, v26
	v_mul_f32_e32 v27, v179, v179
	v_add_f32_e32 v28, v29, v28
	v_mul_f32_e32 v29, v143, v143
	v_add_f32_e32 v30, v31, v30
	v_mul_f32_e32 v31, v187, v187
	v_add_f32_e32 v32, v33, v32
	v_mul_f32_e32 v33, v157, v157
	v_fmac_f32_e32 v25, v82, v82
	v_fmac_f32_e32 v27, v178, v178
	v_fmac_f32_e32 v29, v142, v142
	v_fmac_f32_e32 v31, v186, v186
	v_fmac_f32_e32 v33, v156, v156
	v_add_f32_e32 v24, v25, v24
	v_add_f32_e32 v26, v27, v26
	v_add_f32_e32 v28, v29, v28
	v_add_f32_e32 v30, v31, v30
	v_add_f32_e32 v32, v33, v32
	ds_swizzle_b32 v25, v24 offset:swizzle(SWAP,16)
	ds_swizzle_b32 v27, v26 offset:swizzle(SWAP,16)
	ds_swizzle_b32 v29, v28 offset:swizzle(SWAP,16)
	ds_swizzle_b32 v31, v30 offset:swizzle(SWAP,16)
	ds_swizzle_b32 v33, v32 offset:swizzle(SWAP,16)
	s_waitcnt lgkmcnt(4)
	v_add_f32_e32 v24, v24, v25
	s_waitcnt lgkmcnt(3)
	v_add_f32_e32 v26, v26, v27
	s_waitcnt lgkmcnt(2)
	v_add_f32_e32 v28, v28, v29
	s_waitcnt lgkmcnt(1)
	v_add_f32_e32 v30, v30, v31
	s_waitcnt lgkmcnt(0)
	v_add_f32_e32 v32, v32, v33
	v_mov_b32_e32 v25, v24
	v_mov_b32_e32 v27, v26
	v_mov_b32_e32 v29, v28
	v_mov_b32_e32 v31, v30
	v_mov_b32_e32 v33, v32
	v_permlane32_swap_b32_e32 v24, v25
	s_waitcnt vmcnt(0)
	v_fmamk_f32 v22, v199, 0x39800000, v246
	v_cmp_gt_f32_e32 vcc, s95, v22
	v_mul_f32_e32 v23, 0x4b800000, v22
	v_permlane32_swap_b32_e32 v26, v27
	v_cndmask_b32_e32 v22, v22, v23, vcc
	v_rsq_f32_e32 v22, v22
	v_permlane32_swap_b32_e32 v28, v29
	v_permlane32_swap_b32_e32 v30, v31
	v_mul_f32_e32 v23, 0x45800000, v22
	v_cndmask_b32_e32 v22, v22, v23, vcc
	v_pk_mul_f32 v[202:203], v[20:21], v[22:23] op_sel_hi:[1,0]
	v_pk_mul_f32 v[204:205], v[18:19], v[22:23] op_sel_hi:[1,0]
	v_pk_mul_f32 v[194:195], v[12:13], v[22:23] op_sel_hi:[1,0]
	v_pk_mul_f32 v[196:197], v[10:11], v[22:23] op_sel_hi:[1,0]
	v_pk_mul_f32 v[206:207], v[16:17], v[22:23] op_sel_hi:[1,0]
	v_pk_mul_f32 v[208:209], v[14:15], v[22:23] op_sel_hi:[1,0]
	v_pk_mul_f32 v[198:199], v[8:9], v[22:23] op_sel_hi:[1,0]
	v_pk_mul_f32 v[200:201], v[6:7], v[22:23] op_sel_hi:[1,0]
	v_mul_f32_e32 v6, v131, v131
	v_mul_f32_e32 v7, v133, v133
	v_mul_f32_e32 v8, v123, v123
	v_mul_f32_e32 v9, v125, v125
	v_mul_f32_e32 v10, v115, v115
	v_mul_f32_e32 v11, v117, v117
	v_mul_f32_e32 v12, v107, v107
	v_mul_f32_e32 v13, v109, v109
	v_mul_f32_e32 v14, v153, v153
	v_mul_f32_e32 v15, v101, v101
	v_mul_f32_e32 v16, v91, v91
	v_mul_f32_e32 v17, v93, v93
	v_mul_f32_e32 v18, v171, v171
	v_mul_f32_e32 v19, v167, v167
	v_mul_f32_e32 v20, v81, v81
	v_mul_f32_e32 v21, v79, v79
	v_mul_f32_e32 v22, v177, v177
	v_mul_f32_e32 v23, v77, v77
	v_mul_f32_e32 v34, v205, v205
	v_mul_f32_e32 v35, v203, v203
	v_mul_f32_e32 v36, v197, v197
	v_mul_f32_e32 v37, v195, v195
	v_fmac_f32_e32 v6, v130, v130
	v_fmac_f32_e32 v7, v132, v132
	v_fmac_f32_e32 v8, v122, v122
	v_fmac_f32_e32 v9, v124, v124
	v_fmac_f32_e32 v10, v114, v114
	v_fmac_f32_e32 v11, v116, v116
	v_fmac_f32_e32 v12, v106, v106
	v_fmac_f32_e32 v13, v108, v108
	v_fmac_f32_e32 v14, v152, v152
	v_fmac_f32_e32 v15, v100, v100
	v_fmac_f32_e32 v16, v90, v90
	v_fmac_f32_e32 v17, v92, v92
	v_fmac_f32_e32 v18, v170, v170
	v_fmac_f32_e32 v19, v166, v166
	v_fmac_f32_e32 v20, v80, v80
	v_fmac_f32_e32 v21, v78, v78
	v_fmac_f32_e32 v22, v176, v176
	v_fmac_f32_e32 v23, v76, v76
	v_fmac_f32_e32 v34, v204, v204
	v_fmac_f32_e32 v35, v202, v202
	v_fmac_f32_e32 v36, v196, v196
	v_fmac_f32_e32 v37, v194, v194
	v_add_f32_e32 v6, v6, v7
	v_mul_f32_e32 v7, v127, v127
	v_add_f32_e32 v8, v8, v9
	v_mul_f32_e32 v9, v119, v119
	v_add_f32_e32 v10, v10, v11
	v_mul_f32_e32 v11, v111, v111
	v_add_f32_e32 v12, v12, v13
	v_mul_f32_e32 v13, v103, v103
	v_add_f32_e32 v14, v14, v15
	v_mul_f32_e32 v15, v151, v151
	v_add_f32_e32 v16, v16, v17
	v_mul_f32_e32 v17, v87, v87
	v_add_f32_e32 v18, v18, v19
	v_mul_f32_e32 v19, v169, v169
	v_add_f32_e32 v20, v20, v21
	v_mul_f32_e32 v21, v71, v71
	v_add_f32_e32 v22, v22, v23
	v_mul_f32_e32 v23, v175, v175
	v_add_f32_e32 v34, v34, v35
	v_mul_f32_e32 v35, v209, v209
	v_add_f32_e32 v36, v36, v37
	v_mul_f32_e32 v37, v201, v201
	v_fmac_f32_e32 v7, v126, v126
	v_fmac_f32_e32 v9, v118, v118
	v_fmac_f32_e32 v11, v110, v110
	v_fmac_f32_e32 v13, v102, v102
	v_fmac_f32_e32 v15, v150, v150
	v_fmac_f32_e32 v17, v86, v86
	v_fmac_f32_e32 v19, v168, v168
	v_fmac_f32_e32 v21, v70, v70
	v_fmac_f32_e32 v23, v174, v174
	v_fmac_f32_e32 v35, v208, v208
	v_fmac_f32_e32 v37, v200, v200
	v_add_f32_e32 v6, v7, v6
	v_mul_f32_e32 v7, v129, v129
	v_add_f32_e32 v8, v9, v8
	v_mul_f32_e32 v9, v121, v121
	v_add_f32_e32 v10, v11, v10
	v_mul_f32_e32 v11, v113, v113
	v_add_f32_e32 v12, v13, v12
	v_mul_f32_e32 v13, v105, v105
	v_add_f32_e32 v14, v15, v14
	v_mul_f32_e32 v15, v97, v97
	v_add_f32_e32 v16, v17, v16
	v_mul_f32_e32 v17, v89, v89
	v_add_f32_e32 v18, v19, v18
	v_mul_f32_e32 v19, v165, v165
	v_add_f32_e32 v20, v21, v20
	v_mul_f32_e32 v21, v73, v73
	v_add_f32_e32 v22, v23, v22
	v_mul_f32_e32 v23, v75, v75
	v_add_f32_e32 v34, v35, v34
	v_mul_f32_e32 v35, v207, v207
	v_add_f32_e32 v36, v37, v36
	v_mul_f32_e32 v37, v199, v199
	v_fmac_f32_e32 v7, v128, v128
	v_fmac_f32_e32 v9, v120, v120
	v_fmac_f32_e32 v11, v112, v112
	v_fmac_f32_e32 v13, v104, v104
	v_fmac_f32_e32 v15, v96, v96
	v_fmac_f32_e32 v17, v88, v88
	v_fmac_f32_e32 v19, v164, v164
	v_fmac_f32_e32 v21, v72, v72
	v_fmac_f32_e32 v23, v74, v74
	v_fmac_f32_e32 v35, v206, v206
	v_fmac_f32_e32 v37, v198, v198
	v_add_f32_e32 v6, v7, v6
	v_add_f32_e32 v8, v9, v8
	v_add_f32_e32 v10, v11, v10
	v_add_f32_e32 v12, v13, v12
	v_add_f32_e32 v14, v15, v14
	v_add_f32_e32 v16, v17, v16
	v_add_f32_e32 v18, v19, v18
	v_add_f32_e32 v20, v21, v20
	v_add_f32_e32 v22, v23, v22
	v_add_f32_e32 v34, v35, v34
	v_add_f32_e32 v36, v37, v36
	ds_swizzle_b32 v7, v6 offset:swizzle(SWAP,16)
	ds_swizzle_b32 v9, v8 offset:swizzle(SWAP,16)
	ds_swizzle_b32 v11, v10 offset:swizzle(SWAP,16)
	ds_swizzle_b32 v13, v12 offset:swizzle(SWAP,16)
	ds_swizzle_b32 v15, v14 offset:swizzle(SWAP,16)
	ds_swizzle_b32 v17, v16 offset:swizzle(SWAP,16)
	ds_swizzle_b32 v19, v18 offset:swizzle(SWAP,16)
	ds_swizzle_b32 v21, v20 offset:swizzle(SWAP,16)
	ds_swizzle_b32 v23, v22 offset:swizzle(SWAP,16)
	ds_swizzle_b32 v35, v34 offset:swizzle(SWAP,16)
	ds_swizzle_b32 v37, v36 offset:swizzle(SWAP,16)
	s_waitcnt lgkmcnt(10)
	v_add_f32_e32 v6, v6, v7
	s_waitcnt lgkmcnt(9)
	v_add_f32_e32 v8, v8, v9
	s_waitcnt lgkmcnt(8)
	v_add_f32_e32 v10, v10, v11
	s_waitcnt lgkmcnt(7)
	v_add_f32_e32 v12, v12, v13
	s_waitcnt lgkmcnt(6)
	v_add_f32_e32 v14, v14, v15
	s_waitcnt lgkmcnt(5)
	v_add_f32_e32 v16, v16, v17
	s_waitcnt lgkmcnt(4)
	v_add_f32_e32 v18, v18, v19
	s_waitcnt lgkmcnt(3)
	v_add_f32_e32 v20, v20, v21
	s_waitcnt lgkmcnt(2)
	v_add_f32_e32 v22, v22, v23
	s_waitcnt lgkmcnt(1)
	v_add_f32_e32 v34, v34, v35
	s_waitcnt lgkmcnt(0)
	v_add_f32_e32 v36, v36, v37
	v_mov_b32_e32 v7, v6
	v_mov_b32_e32 v9, v8
	v_mov_b32_e32 v11, v10
	v_mov_b32_e32 v13, v12
	v_mov_b32_e32 v15, v14
	v_mov_b32_e32 v17, v16
	v_mov_b32_e32 v19, v18
	v_mov_b32_e32 v21, v20
	v_mov_b32_e32 v23, v22
	v_mov_b32_e32 v35, v34
	v_mov_b32_e32 v37, v36
	v_permlane32_swap_b32_e32 v6, v7
	v_permlane32_swap_b32_e32 v8, v9
	v_permlane32_swap_b32_e32 v10, v11
	v_permlane32_swap_b32_e32 v12, v13
	v_permlane32_swap_b32_e32 v14, v15
	v_permlane32_swap_b32_e32 v16, v17
	v_permlane32_swap_b32_e32 v18, v19
	v_permlane32_swap_b32_e32 v20, v21
	v_permlane32_swap_b32_e32 v22, v23
	v_permlane32_swap_b32_e32 v32, v33
	v_permlane32_swap_b32_e32 v34, v35
	v_permlane32_swap_b32_e32 v36, v37
	v_cmp_eq_u32_e32 vcc, 0, v210
	s_and_saveexec_b64 s[30:31], vcc
	s_cbranch_execz .LBB0_349
	s_and_b64 s[52:53], s[28:29], exec
	s_mov_b32 s1, 0x31000
	s_cselect_b32 s1, s1, 0x20800
	s_add_u32 s1, s24, s1
	s_addc_u32 s2, s25, 0
	s_add_u32 s52, s1, s6
	v_add_f32_e32 v8, v8, v9
	v_add_f32_e32 v9, v6, v7
	s_addc_u32 s53, s2, s7
	v_add_f32_e32 v12, v12, v13
	v_add_f32_e32 v10, v10, v11
	v_lshl_add_u64 v[6:7], v[140:141], 2, s[52:53]
	v_add_f32_e32 v8, v9, v8
	v_add_f32_e32 v16, v16, v17
	v_add_f32_e32 v14, v14, v15
	global_atomic_add_f32 v[6:7], v8, off
	v_add_f32_e32 v8, v10, v12
	v_add_f32_e32 v20, v20, v21
	v_add_f32_e32 v18, v18, v19
	global_atomic_add_f32 v[6:7], v8, off offset:64
	v_add_f32_e32 v8, v14, v16
	v_add_f32_e32 v24, v24, v25
	v_add_f32_e32 v22, v22, v23
	global_atomic_add_f32 v[6:7], v8, off offset:128
	v_add_f32_e32 v8, v18, v20
	v_add_f32_e32 v28, v28, v29
	v_add_f32_e32 v26, v26, v27
	global_atomic_add_f32 v[6:7], v8, off offset:192
	v_add_f32_e32 v8, v22, v24
	v_add_f32_e32 v32, v32, v33
	v_add_f32_e32 v30, v30, v31
	global_atomic_add_f32 v[6:7], v8, off offset:512
	v_add_f32_e32 v8, v26, v28
	v_add_f32_e32 v36, v36, v37
	v_add_f32_e32 v34, v34, v35
	global_atomic_add_f32 v[6:7], v8, off offset:576
	v_add_f32_e32 v8, v30, v32
	global_atomic_add_f32 v[6:7], v8, off offset:640
	v_add_f32_e32 v8, v34, v36
	global_atomic_add_f32 v[6:7], v8, off offset:704

.LBB0_454:
	s_add_u32 s66, s62, 0xffffff80
	s_addc_u32 s67, s63, -1
	s_cmp_eq_u32 s64, 12
	s_cselect_b32 s38, s21, s62
	s_cselect_b32 s39, s3, s63
	s_cselect_b32 s41, s23, s61
	s_cselect_b32 s40, s31, s33
	s_add_u32 s34, s38, 0x80
	s_addc_u32 s35, s39, 0
	s_add_u32 s36, s40, 0x80
	s_addc_u32 s37, s41, 0
	s_add_i32 s65, 0, 0x10000
	s_add_i32 s68, 0, 0x14000
	v_add_u32_e32 v152, s65, v1
	v_add_u32_e32 v168, s68, v1
	ds_read_b128 v[140:143], v152
	ds_read_b128 v[144:147], v152 offset:1024
	ds_read_b128 v[148:151], v152 offset:2048
	ds_read_b128 v[152:155], v152 offset:3072
	ds_read_b128 v[156:159], v168
	ds_read_b128 v[160:163], v168 offset:1024
	ds_read_b128 v[164:167], v168 offset:2048
	ds_read_b128 v[168:171], v168 offset:3072
	s_add_u32 s66, s66, 0x40000
	s_addc_u32 s67, s67, 0
	v_lshl_add_u64 v[204:205], s[66:67], 0, v[2:3]
	s_add_i32 m0, s29, 0xc000
	ds_read_b128 v[172:175], v5
	ds_read_b128 v[176:179], v5 offset:1024
	ds_read_b128 v[180:183], v5 offset:2048
	ds_read_b128 v[184:187], v5 offset:3072
	ds_read_b128 v[188:191], v5 offset:4096
	ds_read_b128 v[192:195], v5 offset:5120
	ds_read_b128 v[196:199], v5 offset:6144
	ds_read_b128 v[200:203], v5 offset:7168
	global_load_lds_dwordx4 v[204:205], off
	v_lshl_add_u64 v[204:205], s[66:67], 0, v[136:137]
	s_add_i32 m0, s29, 0xe000
	s_nop 0
	global_load_lds_dwordx4 v[204:205], off
	s_waitcnt vmcnt(8)
	s_waitcnt lgkmcnt(0)
	s_setprio 1
	s_barrier
	v_mfma_f32_16x16x32_bf16 v[130:133], v[140:143], v[172:175], v[130:133]
	v_mfma_f32_16x16x32_bf16 v[126:129], v[148:151], v[172:175], v[126:129]
	v_mfma_f32_16x16x32_bf16 v[114:117], v[140:143], v[180:183], v[114:117]
	v_mfma_f32_16x16x32_bf16 v[110:113], v[148:151], v[180:183], v[110:113]
	v_mfma_f32_16x16x32_bf16 v[98:101], v[140:143], v[188:191], v[98:101]
	v_mfma_f32_16x16x32_bf16 v[94:97], v[148:151], v[188:191], v[94:97]
	v_mfma_f32_16x16x32_bf16 v[82:85], v[140:143], v[196:199], v[82:85]
	v_mfma_f32_16x16x32_bf16 v[78:81], v[148:151], v[196:199], v[78:81]
	v_mfma_f32_16x16x32_bf16 v[130:133], v[144:147], v[176:179], v[130:133]
	v_mfma_f32_16x16x32_bf16 v[126:129], v[152:155], v[176:179], v[126:129]
	v_mfma_f32_16x16x32_bf16 v[114:117], v[144:147], v[184:187], v[114:117]
	v_mfma_f32_16x16x32_bf16 v[110:113], v[152:155], v[184:187], v[110:113]
	v_mfma_f32_16x16x32_bf16 v[98:101], v[144:147], v[192:195], v[98:101]
	v_mfma_f32_16x16x32_bf16 v[94:97], v[152:155], v[192:195], v[94:97]
	v_mfma_f32_16x16x32_bf16 v[82:85], v[144:147], v[200:203], v[82:85]
	v_mfma_f32_16x16x32_bf16 v[78:81], v[152:155], v[200:203], v[78:81]
	s_setprio 0
	s_setprio 1
	v_mfma_f32_16x16x32_bf16 v[122:125], v[156:159], v[172:175], v[122:125]
	v_mfma_f32_16x16x32_bf16 v[118:121], v[164:167], v[172:175], v[118:121]
	v_mfma_f32_16x16x32_bf16 v[106:109], v[156:159], v[180:183], v[106:109]
	v_mfma_f32_16x16x32_bf16 v[102:105], v[164:167], v[180:183], v[102:105]
	v_mfma_f32_16x16x32_bf16 v[90:93], v[156:159], v[188:191], v[90:93]
	v_mfma_f32_16x16x32_bf16 v[86:89], v[164:167], v[188:191], v[86:89]
	v_mfma_f32_16x16x32_bf16 v[74:77], v[156:159], v[196:199], v[74:77]
	v_mfma_f32_16x16x32_bf16 v[70:73], v[164:167], v[196:199], v[70:73]
	v_mfma_f32_16x16x32_bf16 v[122:125], v[160:163], v[176:179], v[122:125]
	v_mfma_f32_16x16x32_bf16 v[118:121], v[168:171], v[176:179], v[118:121]
	v_mfma_f32_16x16x32_bf16 v[106:109], v[160:163], v[184:187], v[106:109]
	v_mfma_f32_16x16x32_bf16 v[102:105], v[168:171], v[184:187], v[102:105]
	v_mfma_f32_16x16x32_bf16 v[90:93], v[160:163], v[192:195], v[90:93]
	v_mfma_f32_16x16x32_bf16 v[86:89], v[168:171], v[192:195], v[86:89]
	v_mfma_f32_16x16x32_bf16 v[74:77], v[160:163], v[200:203], v[74:77]
	v_mfma_f32_16x16x32_bf16 v[70:73], v[168:171], v[200:203], v[70:73]
	s_barrier
	s_setprio 0
	s_add_i32 s65, s65, s46
	v_lshl_add_u64 v[204:205], s[40:41], 0, v[134:135]
	s_mov_b32 m0, s65
	ds_read_b128 v[172:175], v5 offset:16384
	ds_read_b128 v[176:179], v5 offset:17408
	ds_read_b128 v[180:183], v5 offset:18432
	ds_read_b128 v[184:187], v5 offset:19456
	ds_read_b128 v[188:191], v5 offset:20480
	ds_read_b128 v[192:195], v5 offset:21504
	ds_read_b128 v[196:199], v5 offset:22528
	ds_read_b128 v[200:203], v5 offset:23552
	global_load_lds_dwordx4 v[204:205], off
	s_add_i32 m0, s65, 0x2000
	v_lshl_add_u64 v[204:205], s[40:41], 0, v[138:139]
	s_add_u32 s40, s40, 0x40000
	s_addc_u32 s41, s41, 0
	s_add_i32 s65, s68, s46
	global_load_lds_dwordx4 v[204:205], off
	v_lshl_add_u64 v[204:205], s[40:41], 0, v[134:135]
	s_mov_b32 m0, s65
	s_nop 0
	global_load_lds_dwordx4 v[204:205], off
	v_lshl_add_u64 v[204:205], s[40:41], 0, v[138:139]
	s_add_i32 m0, s65, 0x2000
	s_nop 0
	global_load_lds_dwordx4 v[204:205], off
	v_lshl_add_u64 v[204:205], s[38:39], 0, v[2:3]
	s_mov_b32 m0, s29
	s_nop 0
	global_load_lds_dwordx4 v[204:205], off
	v_lshl_add_u64 v[204:205], s[38:39], 0, v[136:137]
	s_mov_b32 m0, s51
	s_nop 0
	global_load_lds_dwordx4 v[204:205], off
	s_waitcnt vmcnt(8)
	s_waitcnt lgkmcnt(0)
	s_setprio 1
	s_barrier
	v_mfma_f32_16x16x32_bf16 v[66:69], v[140:143], v[172:175], v[66:69]
	v_mfma_f32_16x16x32_bf16 v[62:65], v[148:151], v[172:175], v[62:65]
	v_mfma_f32_16x16x32_bf16 v[50:53], v[140:143], v[180:183], v[50:53]
	v_mfma_f32_16x16x32_bf16 v[46:49], v[148:151], v[180:183], v[46:49]
	v_mfma_f32_16x16x32_bf16 v[34:37], v[140:143], v[188:191], v[34:37]
	v_mfma_f32_16x16x32_bf16 v[30:33], v[148:151], v[188:191], v[30:33]
	v_mfma_f32_16x16x32_bf16 v[18:21], v[140:143], v[196:199], v[18:21]
	v_mfma_f32_16x16x32_bf16 v[14:17], v[148:151], v[196:199], v[14:17]
	v_mfma_f32_16x16x32_bf16 v[66:69], v[144:147], v[176:179], v[66:69]
	v_mfma_f32_16x16x32_bf16 v[62:65], v[152:155], v[176:179], v[62:65]
	v_mfma_f32_16x16x32_bf16 v[50:53], v[144:147], v[184:187], v[50:53]
	v_mfma_f32_16x16x32_bf16 v[46:49], v[152:155], v[184:187], v[46:49]
	v_mfma_f32_16x16x32_bf16 v[34:37], v[144:147], v[192:195], v[34:37]
	v_mfma_f32_16x16x32_bf16 v[30:33], v[152:155], v[192:195], v[30:33]
	v_mfma_f32_16x16x32_bf16 v[18:21], v[144:147], v[200:203], v[18:21]
	v_mfma_f32_16x16x32_bf16 v[14:17], v[152:155], v[200:203], v[14:17]
	s_setprio 0
	s_setprio 1
	v_mfma_f32_16x16x32_bf16 v[58:61], v[156:159], v[172:175], v[58:61]
	v_mfma_f32_16x16x32_bf16 v[54:57], v[164:167], v[172:175], v[54:57]
	v_mfma_f32_16x16x32_bf16 v[42:45], v[156:159], v[180:183], v[42:45]
	v_mfma_f32_16x16x32_bf16 v[38:41], v[164:167], v[180:183], v[38:41]
	v_mfma_f32_16x16x32_bf16 v[26:29], v[156:159], v[188:191], v[26:29]
	v_mfma_f32_16x16x32_bf16 v[22:25], v[164:167], v[188:191], v[22:25]
	v_mfma_f32_16x16x32_bf16 v[10:13], v[156:159], v[196:199], v[10:13]
	v_mfma_f32_16x16x32_bf16 v[6:9], v[164:167], v[196:199], v[6:9]
	v_mfma_f32_16x16x32_bf16 v[58:61], v[160:163], v[176:179], v[58:61]
	v_mfma_f32_16x16x32_bf16 v[54:57], v[168:171], v[176:179], v[54:57]
	v_mfma_f32_16x16x32_bf16 v[42:45], v[160:163], v[184:187], v[42:45]
	v_mfma_f32_16x16x32_bf16 v[38:41], v[168:171], v[184:187], v[38:41]
	v_mfma_f32_16x16x32_bf16 v[26:29], v[160:163], v[192:195], v[26:29]
	v_mfma_f32_16x16x32_bf16 v[22:25], v[168:171], v[192:195], v[22:25]
	v_mfma_f32_16x16x32_bf16 v[10:13], v[160:163], v[200:203], v[10:13]
	v_mfma_f32_16x16x32_bf16 v[6:9], v[168:171], v[200:203], v[6:9]
	s_barrier
	s_setprio 0
	s_add_i32 s40, 0, 0x18000
	s_add_i32 s41, 0, 0x1c000
	v_add_u32_e32 v152, s40, v1
	v_add_u32_e32 v168, s41, v1
	ds_read_b128 v[140:143], v152
	ds_read_b128 v[144:147], v152 offset:1024
	ds_read_b128 v[148:151], v152 offset:2048
	ds_read_b128 v[152:155], v152 offset:3072
	ds_read_b128 v[156:159], v168
	ds_read_b128 v[160:163], v168 offset:1024
	ds_read_b128 v[164:167], v168 offset:2048
	ds_read_b128 v[168:171], v168 offset:3072
	s_add_u32 s38, s38, 0x40000
	s_addc_u32 s39, s39, 0
	s_mov_b32 m0, s52
	v_lshl_add_u64 v[204:205], s[38:39], 0, v[2:3]
	ds_read_b128 v[172:175], v5 offset:32768
	ds_read_b128 v[176:179], v5 offset:33792
	ds_read_b128 v[180:183], v5 offset:34816
	ds_read_b128 v[184:187], v5 offset:35840
	ds_read_b128 v[188:191], v5 offset:36864
	ds_read_b128 v[192:195], v5 offset:37888
	ds_read_b128 v[196:199], v5 offset:38912
	ds_read_b128 v[200:203], v5 offset:39936
	global_load_lds_dwordx4 v[204:205], off
	v_lshl_add_u64 v[204:205], s[38:39], 0, v[136:137]
	s_mov_b32 m0, s53
	s_nop 0
	global_load_lds_dwordx4 v[204:205], off
	s_waitcnt vmcnt(8)
	s_waitcnt lgkmcnt(0)
	s_setprio 1
	s_barrier
	v_mfma_f32_16x16x32_bf16 v[130:133], v[140:143], v[172:175], v[130:133]
	v_mfma_f32_16x16x32_bf16 v[126:129], v[148:151], v[172:175], v[126:129]
	v_mfma_f32_16x16x32_bf16 v[114:117], v[140:143], v[180:183], v[114:117]
	v_mfma_f32_16x16x32_bf16 v[110:113], v[148:151], v[180:183], v[110:113]
	v_mfma_f32_16x16x32_bf16 v[98:101], v[140:143], v[188:191], v[98:101]
	v_mfma_f32_16x16x32_bf16 v[94:97], v[148:151], v[188:191], v[94:97]
	v_mfma_f32_16x16x32_bf16 v[82:85], v[140:143], v[196:199], v[82:85]
	v_mfma_f32_16x16x32_bf16 v[78:81], v[148:151], v[196:199], v[78:81]
	v_mfma_f32_16x16x32_bf16 v[130:133], v[144:147], v[176:179], v[130:133]
	v_mfma_f32_16x16x32_bf16 v[126:129], v[152:155], v[176:179], v[126:129]
	v_mfma_f32_16x16x32_bf16 v[114:117], v[144:147], v[184:187], v[114:117]
	v_mfma_f32_16x16x32_bf16 v[110:113], v[152:155], v[184:187], v[110:113]
	v_mfma_f32_16x16x32_bf16 v[98:101], v[144:147], v[192:195], v[98:101]
	v_mfma_f32_16x16x32_bf16 v[94:97], v[152:155], v[192:195], v[94:97]
	v_mfma_f32_16x16x32_bf16 v[82:85], v[144:147], v[200:203], v[82:85]
	v_mfma_f32_16x16x32_bf16 v[78:81], v[152:155], v[200:203], v[78:81]
	s_setprio 0
	s_setprio 1
	v_mfma_f32_16x16x32_bf16 v[122:125], v[156:159], v[172:175], v[122:125]
	v_mfma_f32_16x16x32_bf16 v[118:121], v[164:167], v[172:175], v[118:121]
	v_mfma_f32_16x16x32_bf16 v[106:109], v[156:159], v[180:183], v[106:109]
	v_mfma_f32_16x16x32_bf16 v[102:105], v[164:167], v[180:183], v[102:105]
	v_mfma_f32_16x16x32_bf16 v[90:93], v[156:159], v[188:191], v[90:93]
	v_mfma_f32_16x16x32_bf16 v[86:89], v[164:167], v[188:191], v[86:89]
	v_mfma_f32_16x16x32_bf16 v[74:77], v[156:159], v[196:199], v[74:77]
	v_mfma_f32_16x16x32_bf16 v[70:73], v[164:167], v[196:199], v[70:73]
	v_mfma_f32_16x16x32_bf16 v[122:125], v[160:163], v[176:179], v[122:125]
	v_mfma_f32_16x16x32_bf16 v[118:121], v[168:171], v[176:179], v[118:121]
	v_mfma_f32_16x16x32_bf16 v[106:109], v[160:163], v[184:187], v[106:109]
	v_mfma_f32_16x16x32_bf16 v[102:105], v[168:171], v[184:187], v[102:105]
	v_mfma_f32_16x16x32_bf16 v[90:93], v[160:163], v[192:195], v[90:93]
	v_mfma_f32_16x16x32_bf16 v[86:89], v[168:171], v[192:195], v[86:89]
	v_mfma_f32_16x16x32_bf16 v[74:77], v[160:163], v[200:203], v[74:77]
	v_mfma_f32_16x16x32_bf16 v[70:73], v[168:171], v[200:203], v[70:73]
	s_barrier
	s_setprio 0
	s_add_i32 s38, s40, s46
	v_lshl_add_u64 v[204:205], s[36:37], 0, v[134:135]
	s_mov_b32 m0, s38
	ds_read_b128 v[172:175], v5 offset:49152
	ds_read_b128 v[176:179], v5 offset:50176
	ds_read_b128 v[180:183], v5 offset:51200
	ds_read_b128 v[184:187], v5 offset:52224
	ds_read_b128 v[188:191], v5 offset:53248
	ds_read_b128 v[192:195], v5 offset:54272
	ds_read_b128 v[196:199], v5 offset:55296
	ds_read_b128 v[200:203], v5 offset:56320
	global_load_lds_dwordx4 v[204:205], off
	s_add_i32 m0, s38, 0x2000
	v_lshl_add_u64 v[204:205], s[36:37], 0, v[138:139]
	s_add_u32 s36, s36, 0x40000
	s_addc_u32 s37, s37, 0
	s_add_i32 s38, s41, s46
	global_load_lds_dwordx4 v[204:205], off
	v_lshl_add_u64 v[204:205], s[36:37], 0, v[134:135]
	s_mov_b32 m0, s38
	s_nop 0
	global_load_lds_dwordx4 v[204:205], off
	v_lshl_add_u64 v[204:205], s[36:37], 0, v[138:139]
	s_add_i32 m0, s38, 0x2000
	s_nop 0
	global_load_lds_dwordx4 v[204:205], off
	v_lshl_add_u64 v[204:205], s[34:35], 0, v[2:3]
	s_mov_b32 m0, s56
	s_nop 0
	global_load_lds_dwordx4 v[204:205], off
	v_lshl_add_u64 v[204:205], s[34:35], 0, v[136:137]
	s_mov_b32 m0, s57
	s_nop 0
	global_load_lds_dwordx4 v[204:205], off
	s_waitcnt vmcnt(8)
	s_waitcnt lgkmcnt(0)
	s_setprio 1
	s_barrier
	v_mfma_f32_16x16x32_bf16 v[66:69], v[140:143], v[172:175], v[66:69]
	v_mfma_f32_16x16x32_bf16 v[62:65], v[148:151], v[172:175], v[62:65]
	v_mfma_f32_16x16x32_bf16 v[50:53], v[140:143], v[180:183], v[50:53]
	v_mfma_f32_16x16x32_bf16 v[46:49], v[148:151], v[180:183], v[46:49]
	v_mfma_f32_16x16x32_bf16 v[34:37], v[140:143], v[188:191], v[34:37]
	v_mfma_f32_16x16x32_bf16 v[30:33], v[148:151], v[188:191], v[30:33]
	v_mfma_f32_16x16x32_bf16 v[18:21], v[140:143], v[196:199], v[18:21]
	v_mfma_f32_16x16x32_bf16 v[14:17], v[148:151], v[196:199], v[14:17]
	v_mfma_f32_16x16x32_bf16 v[66:69], v[144:147], v[176:179], v[66:69]
	v_mfma_f32_16x16x32_bf16 v[62:65], v[152:155], v[176:179], v[62:65]
	v_mfma_f32_16x16x32_bf16 v[50:53], v[144:147], v[184:187], v[50:53]
	v_mfma_f32_16x16x32_bf16 v[46:49], v[152:155], v[184:187], v[46:49]
	v_mfma_f32_16x16x32_bf16 v[34:37], v[144:147], v[192:195], v[34:37]
	v_mfma_f32_16x16x32_bf16 v[30:33], v[152:155], v[192:195], v[30:33]
	v_mfma_f32_16x16x32_bf16 v[18:21], v[144:147], v[200:203], v[18:21]
	v_mfma_f32_16x16x32_bf16 v[14:17], v[152:155], v[200:203], v[14:17]
	s_setprio 0
	s_setprio 1
	v_mfma_f32_16x16x32_bf16 v[58:61], v[156:159], v[172:175], v[58:61]
	v_mfma_f32_16x16x32_bf16 v[54:57], v[164:167], v[172:175], v[54:57]
	v_mfma_f32_16x16x32_bf16 v[42:45], v[156:159], v[180:183], v[42:45]
	v_mfma_f32_16x16x32_bf16 v[38:41], v[164:167], v[180:183], v[38:41]
	v_mfma_f32_16x16x32_bf16 v[26:29], v[156:159], v[188:191], v[26:29]
	v_mfma_f32_16x16x32_bf16 v[22:25], v[164:167], v[188:191], v[22:25]
	v_mfma_f32_16x16x32_bf16 v[10:13], v[156:159], v[196:199], v[10:13]
	v_mfma_f32_16x16x32_bf16 v[6:9], v[164:167], v[196:199], v[6:9]
	v_mfma_f32_16x16x32_bf16 v[58:61], v[160:163], v[176:179], v[58:61]
	v_mfma_f32_16x16x32_bf16 v[54:57], v[168:171], v[176:179], v[54:57]
	v_mfma_f32_16x16x32_bf16 v[42:45], v[160:163], v[184:187], v[42:45]
	v_mfma_f32_16x16x32_bf16 v[38:41], v[168:171], v[184:187], v[38:41]
	v_mfma_f32_16x16x32_bf16 v[26:29], v[160:163], v[192:195], v[26:29]
	v_mfma_f32_16x16x32_bf16 v[22:25], v[168:171], v[192:195], v[22:25]
	v_mfma_f32_16x16x32_bf16 v[10:13], v[160:163], v[200:203], v[10:13]
	v_mfma_f32_16x16x32_bf16 v[6:9], v[168:171], v[200:203], v[6:9]
	s_barrier
	s_setprio 0
	s_add_i32 s64, s64, 2
	s_add_u32 s33, s33, 0x100
	s_addc_u32 s61, s61, 0
	s_add_u32 s62, s62, 0x100
	s_addc_u32 s63, s63, 0
	s_cmp_gt_u32 s64, 13
	s_cbranch_scc0 .LBB0_454
	s_and_b64 vcc, exec, s[8:9]
	s_cbranch_vccz .LBB0_457
	s_barrier

.LBB0_480:
	s_add_u32 s58, s54, 0xffffff80
	s_addc_u32 s59, s55, -1
	s_cmp_eq_u32 s56, 4
	s_cselect_b32 s30, s25, s54
	s_cselect_b32 s31, s15, s55
	s_cselect_b32 s35, s17, s53
	s_cselect_b32 s34, s33, s52
	s_add_u32 s26, s30, 0x80
	s_addc_u32 s27, s31, 0
	s_add_u32 s28, s34, 0x80
	s_addc_u32 s29, s35, 0
	s_add_i32 s57, 0, 0x10000
	s_add_i32 s60, 0, 0x14000
	v_add_u32_e32 v152, s57, v1
	v_add_u32_e32 v168, s60, v1
	ds_read_b128 v[140:143], v152
	ds_read_b128 v[144:147], v152 offset:1024
	ds_read_b128 v[148:151], v152 offset:2048
	ds_read_b128 v[152:155], v152 offset:3072
	ds_read_b128 v[156:159], v168
	ds_read_b128 v[160:163], v168 offset:1024
	ds_read_b128 v[164:167], v168 offset:2048
	ds_read_b128 v[168:171], v168 offset:3072
	s_add_u32 s58, s58, 0x20000
	s_addc_u32 s59, s59, 0
	v_lshl_add_u64 v[204:205], s[58:59], 0, v[2:3]
	s_add_i32 m0, s43, 0xc000
	ds_read_b128 v[172:175], v5
	ds_read_b128 v[176:179], v5 offset:1024
	ds_read_b128 v[180:183], v5 offset:2048
	ds_read_b128 v[184:187], v5 offset:3072
	ds_read_b128 v[188:191], v5 offset:4096
	ds_read_b128 v[192:195], v5 offset:5120
	ds_read_b128 v[196:199], v5 offset:6144
	ds_read_b128 v[200:203], v5 offset:7168
	global_load_lds_dwordx4 v[204:205], off
	v_lshl_add_u64 v[204:205], s[58:59], 0, v[136:137]
	s_add_i32 m0, s43, 0xe000
	s_nop 0
	global_load_lds_dwordx4 v[204:205], off
	s_waitcnt vmcnt(8)
	s_waitcnt lgkmcnt(0)
	s_setprio 1
	s_barrier
	v_mfma_f32_16x16x32_bf16 v[130:133], v[140:143], v[172:175], v[130:133]
	v_mfma_f32_16x16x32_bf16 v[126:129], v[148:151], v[172:175], v[126:129]
	v_mfma_f32_16x16x32_bf16 v[114:117], v[140:143], v[180:183], v[114:117]
	v_mfma_f32_16x16x32_bf16 v[110:113], v[148:151], v[180:183], v[110:113]
	v_mfma_f32_16x16x32_bf16 v[98:101], v[140:143], v[188:191], v[98:101]
	v_mfma_f32_16x16x32_bf16 v[94:97], v[148:151], v[188:191], v[94:97]
	v_mfma_f32_16x16x32_bf16 v[82:85], v[140:143], v[196:199], v[82:85]
	v_mfma_f32_16x16x32_bf16 v[78:81], v[148:151], v[196:199], v[78:81]
	v_mfma_f32_16x16x32_bf16 v[130:133], v[144:147], v[176:179], v[130:133]
	v_mfma_f32_16x16x32_bf16 v[126:129], v[152:155], v[176:179], v[126:129]
	v_mfma_f32_16x16x32_bf16 v[114:117], v[144:147], v[184:187], v[114:117]
	v_mfma_f32_16x16x32_bf16 v[110:113], v[152:155], v[184:187], v[110:113]
	v_mfma_f32_16x16x32_bf16 v[98:101], v[144:147], v[192:195], v[98:101]
	v_mfma_f32_16x16x32_bf16 v[94:97], v[152:155], v[192:195], v[94:97]
	v_mfma_f32_16x16x32_bf16 v[82:85], v[144:147], v[200:203], v[82:85]
	v_mfma_f32_16x16x32_bf16 v[78:81], v[152:155], v[200:203], v[78:81]
	s_setprio 0
	s_setprio 1
	v_mfma_f32_16x16x32_bf16 v[122:125], v[156:159], v[172:175], v[122:125]
	v_mfma_f32_16x16x32_bf16 v[118:121], v[164:167], v[172:175], v[118:121]
	v_mfma_f32_16x16x32_bf16 v[106:109], v[156:159], v[180:183], v[106:109]
	v_mfma_f32_16x16x32_bf16 v[102:105], v[164:167], v[180:183], v[102:105]
	v_mfma_f32_16x16x32_bf16 v[90:93], v[156:159], v[188:191], v[90:93]
	v_mfma_f32_16x16x32_bf16 v[86:89], v[164:167], v[188:191], v[86:89]
	v_mfma_f32_16x16x32_bf16 v[74:77], v[156:159], v[196:199], v[74:77]
	v_mfma_f32_16x16x32_bf16 v[70:73], v[164:167], v[196:199], v[70:73]
	v_mfma_f32_16x16x32_bf16 v[122:125], v[160:163], v[176:179], v[122:125]
	v_mfma_f32_16x16x32_bf16 v[118:121], v[168:171], v[176:179], v[118:121]
	v_mfma_f32_16x16x32_bf16 v[106:109], v[160:163], v[184:187], v[106:109]
	v_mfma_f32_16x16x32_bf16 v[102:105], v[168:171], v[184:187], v[102:105]
	v_mfma_f32_16x16x32_bf16 v[90:93], v[160:163], v[192:195], v[90:93]
	v_mfma_f32_16x16x32_bf16 v[86:89], v[168:171], v[192:195], v[86:89]
	v_mfma_f32_16x16x32_bf16 v[74:77], v[160:163], v[200:203], v[74:77]
	v_mfma_f32_16x16x32_bf16 v[70:73], v[168:171], v[200:203], v[70:73]
	s_barrier
	s_setprio 0
	s_add_i32 s57, s57, s42
	v_lshl_add_u64 v[204:205], s[34:35], 0, v[134:135]
	s_mov_b32 m0, s57
	ds_read_b128 v[172:175], v5 offset:16384
	ds_read_b128 v[176:179], v5 offset:17408
	ds_read_b128 v[180:183], v5 offset:18432
	ds_read_b128 v[184:187], v5 offset:19456
	ds_read_b128 v[188:191], v5 offset:20480
	ds_read_b128 v[192:195], v5 offset:21504
	ds_read_b128 v[196:199], v5 offset:22528
	ds_read_b128 v[200:203], v5 offset:23552
	global_load_lds_dwordx4 v[204:205], off
	s_add_i32 m0, s57, 0x2000
	v_lshl_add_u64 v[204:205], s[34:35], 0, v[138:139]
	s_add_u32 s34, s34, 0x20000
	s_addc_u32 s35, s35, 0
	s_add_i32 s57, s60, s42
	global_load_lds_dwordx4 v[204:205], off
	v_lshl_add_u64 v[204:205], s[34:35], 0, v[134:135]
	s_mov_b32 m0, s57
	s_nop 0
	global_load_lds_dwordx4 v[204:205], off
	v_lshl_add_u64 v[204:205], s[34:35], 0, v[138:139]
	s_add_i32 m0, s57, 0x2000
	s_nop 0
	global_load_lds_dwordx4 v[204:205], off
	v_lshl_add_u64 v[204:205], s[30:31], 0, v[2:3]
	s_mov_b32 m0, s43
	s_nop 0
	global_load_lds_dwordx4 v[204:205], off
	v_lshl_add_u64 v[204:205], s[30:31], 0, v[136:137]
	s_mov_b32 m0, s44
	s_nop 0
	global_load_lds_dwordx4 v[204:205], off
	s_waitcnt vmcnt(8)
	s_waitcnt lgkmcnt(0)
	s_setprio 1
	s_barrier
	v_mfma_f32_16x16x32_bf16 v[66:69], v[140:143], v[172:175], v[66:69]
	v_mfma_f32_16x16x32_bf16 v[62:65], v[148:151], v[172:175], v[62:65]
	v_mfma_f32_16x16x32_bf16 v[50:53], v[140:143], v[180:183], v[50:53]
	v_mfma_f32_16x16x32_bf16 v[46:49], v[148:151], v[180:183], v[46:49]
	v_mfma_f32_16x16x32_bf16 v[34:37], v[140:143], v[188:191], v[34:37]
	v_mfma_f32_16x16x32_bf16 v[30:33], v[148:151], v[188:191], v[30:33]
	v_mfma_f32_16x16x32_bf16 v[18:21], v[140:143], v[196:199], v[18:21]
	v_mfma_f32_16x16x32_bf16 v[14:17], v[148:151], v[196:199], v[14:17]
	v_mfma_f32_16x16x32_bf16 v[66:69], v[144:147], v[176:179], v[66:69]
	v_mfma_f32_16x16x32_bf16 v[62:65], v[152:155], v[176:179], v[62:65]
	v_mfma_f32_16x16x32_bf16 v[50:53], v[144:147], v[184:187], v[50:53]
	v_mfma_f32_16x16x32_bf16 v[46:49], v[152:155], v[184:187], v[46:49]
	v_mfma_f32_16x16x32_bf16 v[34:37], v[144:147], v[192:195], v[34:37]
	v_mfma_f32_16x16x32_bf16 v[30:33], v[152:155], v[192:195], v[30:33]
	v_mfma_f32_16x16x32_bf16 v[18:21], v[144:147], v[200:203], v[18:21]
	v_mfma_f32_16x16x32_bf16 v[14:17], v[152:155], v[200:203], v[14:17]
	s_setprio 0
	s_setprio 1
	v_mfma_f32_16x16x32_bf16 v[58:61], v[156:159], v[172:175], v[58:61]
	v_mfma_f32_16x16x32_bf16 v[54:57], v[164:167], v[172:175], v[54:57]
	v_mfma_f32_16x16x32_bf16 v[42:45], v[156:159], v[180:183], v[42:45]
	v_mfma_f32_16x16x32_bf16 v[38:41], v[164:167], v[180:183], v[38:41]
	v_mfma_f32_16x16x32_bf16 v[26:29], v[156:159], v[188:191], v[26:29]
	v_mfma_f32_16x16x32_bf16 v[22:25], v[164:167], v[188:191], v[22:25]
	v_mfma_f32_16x16x32_bf16 v[10:13], v[156:159], v[196:199], v[10:13]
	v_mfma_f32_16x16x32_bf16 v[6:9], v[164:167], v[196:199], v[6:9]
	v_mfma_f32_16x16x32_bf16 v[58:61], v[160:163], v[176:179], v[58:61]
	v_mfma_f32_16x16x32_bf16 v[54:57], v[168:171], v[176:179], v[54:57]
	v_mfma_f32_16x16x32_bf16 v[42:45], v[160:163], v[184:187], v[42:45]
	v_mfma_f32_16x16x32_bf16 v[38:41], v[168:171], v[184:187], v[38:41]
	v_mfma_f32_16x16x32_bf16 v[26:29], v[160:163], v[192:195], v[26:29]
	v_mfma_f32_16x16x32_bf16 v[22:25], v[168:171], v[192:195], v[22:25]
	v_mfma_f32_16x16x32_bf16 v[10:13], v[160:163], v[200:203], v[10:13]
	v_mfma_f32_16x16x32_bf16 v[6:9], v[168:171], v[200:203], v[6:9]
	s_barrier
	s_setprio 0
	s_add_i32 s34, 0, 0x18000
	s_add_i32 s35, 0, 0x1c000
	v_add_u32_e32 v152, s34, v1
	v_add_u32_e32 v168, s35, v1
	ds_read_b128 v[140:143], v152
	ds_read_b128 v[144:147], v152 offset:1024
	ds_read_b128 v[148:151], v152 offset:2048
	ds_read_b128 v[152:155], v152 offset:3072
	ds_read_b128 v[156:159], v168
	ds_read_b128 v[160:163], v168 offset:1024
	ds_read_b128 v[164:167], v168 offset:2048
	ds_read_b128 v[168:171], v168 offset:3072
	s_add_u32 s30, s30, 0x20000
	s_addc_u32 s31, s31, 0
	s_mov_b32 m0, s45
	v_lshl_add_u64 v[204:205], s[30:31], 0, v[2:3]
	ds_read_b128 v[172:175], v5 offset:32768
	ds_read_b128 v[176:179], v5 offset:33792
	ds_read_b128 v[180:183], v5 offset:34816
	ds_read_b128 v[184:187], v5 offset:35840
	ds_read_b128 v[188:191], v5 offset:36864
	ds_read_b128 v[192:195], v5 offset:37888
	ds_read_b128 v[196:199], v5 offset:38912
	ds_read_b128 v[200:203], v5 offset:39936
	global_load_lds_dwordx4 v[204:205], off
	v_lshl_add_u64 v[204:205], s[30:31], 0, v[136:137]
	s_mov_b32 m0, s46
	s_nop 0
	global_load_lds_dwordx4 v[204:205], off
	s_waitcnt vmcnt(8)
	s_waitcnt lgkmcnt(0)
	s_setprio 1
	s_barrier
	v_mfma_f32_16x16x32_bf16 v[130:133], v[140:143], v[172:175], v[130:133]
	v_mfma_f32_16x16x32_bf16 v[126:129], v[148:151], v[172:175], v[126:129]
	v_mfma_f32_16x16x32_bf16 v[114:117], v[140:143], v[180:183], v[114:117]
	v_mfma_f32_16x16x32_bf16 v[110:113], v[148:151], v[180:183], v[110:113]
	v_mfma_f32_16x16x32_bf16 v[98:101], v[140:143], v[188:191], v[98:101]
	v_mfma_f32_16x16x32_bf16 v[94:97], v[148:151], v[188:191], v[94:97]
	v_mfma_f32_16x16x32_bf16 v[82:85], v[140:143], v[196:199], v[82:85]
	v_mfma_f32_16x16x32_bf16 v[78:81], v[148:151], v[196:199], v[78:81]
	v_mfma_f32_16x16x32_bf16 v[130:133], v[144:147], v[176:179], v[130:133]
	v_mfma_f32_16x16x32_bf16 v[126:129], v[152:155], v[176:179], v[126:129]
	v_mfma_f32_16x16x32_bf16 v[114:117], v[144:147], v[184:187], v[114:117]
	v_mfma_f32_16x16x32_bf16 v[110:113], v[152:155], v[184:187], v[110:113]
	v_mfma_f32_16x16x32_bf16 v[98:101], v[144:147], v[192:195], v[98:101]
	v_mfma_f32_16x16x32_bf16 v[94:97], v[152:155], v[192:195], v[94:97]
	v_mfma_f32_16x16x32_bf16 v[82:85], v[144:147], v[200:203], v[82:85]
	v_mfma_f32_16x16x32_bf16 v[78:81], v[152:155], v[200:203], v[78:81]
	s_setprio 0
	s_setprio 1
	v_mfma_f32_16x16x32_bf16 v[122:125], v[156:159], v[172:175], v[122:125]
	v_mfma_f32_16x16x32_bf16 v[118:121], v[164:167], v[172:175], v[118:121]
	v_mfma_f32_16x16x32_bf16 v[106:109], v[156:159], v[180:183], v[106:109]
	v_mfma_f32_16x16x32_bf16 v[102:105], v[164:167], v[180:183], v[102:105]
	v_mfma_f32_16x16x32_bf16 v[90:93], v[156:159], v[188:191], v[90:93]
	v_mfma_f32_16x16x32_bf16 v[86:89], v[164:167], v[188:191], v[86:89]
	v_mfma_f32_16x16x32_bf16 v[74:77], v[156:159], v[196:199], v[74:77]
	v_mfma_f32_16x16x32_bf16 v[70:73], v[164:167], v[196:199], v[70:73]
	v_mfma_f32_16x16x32_bf16 v[122:125], v[160:163], v[176:179], v[122:125]
	v_mfma_f32_16x16x32_bf16 v[118:121], v[168:171], v[176:179], v[118:121]
	v_mfma_f32_16x16x32_bf16 v[106:109], v[160:163], v[184:187], v[106:109]
	v_mfma_f32_16x16x32_bf16 v[102:105], v[168:171], v[184:187], v[102:105]
	v_mfma_f32_16x16x32_bf16 v[90:93], v[160:163], v[192:195], v[90:93]
	v_mfma_f32_16x16x32_bf16 v[86:89], v[168:171], v[192:195], v[86:89]
	v_mfma_f32_16x16x32_bf16 v[74:77], v[160:163], v[200:203], v[74:77]
	v_mfma_f32_16x16x32_bf16 v[70:73], v[168:171], v[200:203], v[70:73]
	s_barrier
	s_setprio 0
	s_add_i32 s30, s34, s42
	v_lshl_add_u64 v[204:205], s[28:29], 0, v[134:135]
	s_mov_b32 m0, s30
	ds_read_b128 v[172:175], v5 offset:49152
	ds_read_b128 v[176:179], v5 offset:50176
	ds_read_b128 v[180:183], v5 offset:51200
	ds_read_b128 v[184:187], v5 offset:52224
	ds_read_b128 v[188:191], v5 offset:53248
	ds_read_b128 v[192:195], v5 offset:54272
	ds_read_b128 v[196:199], v5 offset:55296
	ds_read_b128 v[200:203], v5 offset:56320
	global_load_lds_dwordx4 v[204:205], off
	s_add_i32 m0, s30, 0x2000
	v_lshl_add_u64 v[204:205], s[28:29], 0, v[138:139]
	s_add_u32 s28, s28, 0x20000
	s_addc_u32 s29, s29, 0
	s_add_i32 s30, s35, s42
	global_load_lds_dwordx4 v[204:205], off
	v_lshl_add_u64 v[204:205], s[28:29], 0, v[134:135]
	s_mov_b32 m0, s30
	s_nop 0
	global_load_lds_dwordx4 v[204:205], off
	v_lshl_add_u64 v[204:205], s[28:29], 0, v[138:139]
	s_add_i32 m0, s30, 0x2000
	s_nop 0
	global_load_lds_dwordx4 v[204:205], off
	v_lshl_add_u64 v[204:205], s[26:27], 0, v[2:3]
	s_mov_b32 m0, s49
	s_nop 0
	global_load_lds_dwordx4 v[204:205], off
	v_lshl_add_u64 v[204:205], s[26:27], 0, v[136:137]
	s_mov_b32 m0, s50
	s_nop 0
	global_load_lds_dwordx4 v[204:205], off
	s_waitcnt vmcnt(8)
	s_waitcnt lgkmcnt(0)
	s_setprio 1
	s_barrier
	v_mfma_f32_16x16x32_bf16 v[66:69], v[140:143], v[172:175], v[66:69]
	v_mfma_f32_16x16x32_bf16 v[62:65], v[148:151], v[172:175], v[62:65]
	v_mfma_f32_16x16x32_bf16 v[50:53], v[140:143], v[180:183], v[50:53]
	v_mfma_f32_16x16x32_bf16 v[46:49], v[148:151], v[180:183], v[46:49]
	v_mfma_f32_16x16x32_bf16 v[34:37], v[140:143], v[188:191], v[34:37]
	v_mfma_f32_16x16x32_bf16 v[30:33], v[148:151], v[188:191], v[30:33]
	v_mfma_f32_16x16x32_bf16 v[18:21], v[140:143], v[196:199], v[18:21]
	v_mfma_f32_16x16x32_bf16 v[14:17], v[148:151], v[196:199], v[14:17]
	v_mfma_f32_16x16x32_bf16 v[66:69], v[144:147], v[176:179], v[66:69]
	v_mfma_f32_16x16x32_bf16 v[62:65], v[152:155], v[176:179], v[62:65]
	v_mfma_f32_16x16x32_bf16 v[50:53], v[144:147], v[184:187], v[50:53]
	v_mfma_f32_16x16x32_bf16 v[46:49], v[152:155], v[184:187], v[46:49]
	v_mfma_f32_16x16x32_bf16 v[34:37], v[144:147], v[192:195], v[34:37]
	v_mfma_f32_16x16x32_bf16 v[30:33], v[152:155], v[192:195], v[30:33]
	v_mfma_f32_16x16x32_bf16 v[18:21], v[144:147], v[200:203], v[18:21]
	v_mfma_f32_16x16x32_bf16 v[14:17], v[152:155], v[200:203], v[14:17]
	s_setprio 0
	s_setprio 1
	v_mfma_f32_16x16x32_bf16 v[58:61], v[156:159], v[172:175], v[58:61]
	v_mfma_f32_16x16x32_bf16 v[54:57], v[164:167], v[172:175], v[54:57]
	v_mfma_f32_16x16x32_bf16 v[42:45], v[156:159], v[180:183], v[42:45]
	v_mfma_f32_16x16x32_bf16 v[38:41], v[164:167], v[180:183], v[38:41]
	v_mfma_f32_16x16x32_bf16 v[26:29], v[156:159], v[188:191], v[26:29]
	v_mfma_f32_16x16x32_bf16 v[22:25], v[164:167], v[188:191], v[22:25]
	v_mfma_f32_16x16x32_bf16 v[10:13], v[156:159], v[196:199], v[10:13]
	v_mfma_f32_16x16x32_bf16 v[6:9], v[164:167], v[196:199], v[6:9]
	v_mfma_f32_16x16x32_bf16 v[58:61], v[160:163], v[176:179], v[58:61]
	v_mfma_f32_16x16x32_bf16 v[54:57], v[168:171], v[176:179], v[54:57]
	v_mfma_f32_16x16x32_bf16 v[42:45], v[160:163], v[184:187], v[42:45]
	v_mfma_f32_16x16x32_bf16 v[38:41], v[168:171], v[184:187], v[38:41]
	v_mfma_f32_16x16x32_bf16 v[26:29], v[160:163], v[192:195], v[26:29]
	v_mfma_f32_16x16x32_bf16 v[22:25], v[168:171], v[192:195], v[22:25]
	v_mfma_f32_16x16x32_bf16 v[10:13], v[160:163], v[200:203], v[10:13]
	v_mfma_f32_16x16x32_bf16 v[6:9], v[168:171], v[200:203], v[6:9]
	s_barrier
	s_setprio 0
	s_add_i32 s56, s56, 2
	s_add_u32 s52, s52, 0x100
	s_addc_u32 s53, s53, 0
	s_add_u32 s54, s54, 0x100
	s_addc_u32 s55, s55, 0
	s_cmp_gt_u32 s56, 5
	s_cbranch_scc0 .LBB0_480
	s_and_b64 vcc, exec, s[8:9]
	s_cbranch_vccz .LBB0_483
	s_barrier

.LBB0_536:
	s_add_u32 s48, s45, 0xffffff80
	s_addc_u32 s49, s46, -1
	s_cmp_eq_u32 s47, 4
	s_cselect_b32 s22, s41, s45
	s_cselect_b32 s23, s7, s46
	s_cselect_b32 s25, s9, s44
	s_cselect_b32 s24, s42, s43
	s_add_u32 s18, s22, 0x80
	s_addc_u32 s19, s23, 0
	s_add_u32 s20, s24, 0x80
	s_addc_u32 s21, s25, 0
	s_add_i32 s50, 0, 0x10000
	s_add_i32 s51, 0, 0x14000
	v_add_u32_e32 v152, s50, v1
	v_add_u32_e32 v168, s51, v1
	ds_read_b128 v[140:143], v152
	ds_read_b128 v[144:147], v152 offset:1024
	ds_read_b128 v[148:151], v152 offset:2048
	ds_read_b128 v[152:155], v152 offset:3072
	ds_read_b128 v[156:159], v168
	ds_read_b128 v[160:163], v168 offset:1024
	ds_read_b128 v[164:167], v168 offset:2048
	ds_read_b128 v[168:171], v168 offset:3072
	s_add_u32 s48, s48, 0x20000
	s_addc_u32 s49, s49, 0
	v_lshl_add_u64 v[204:205], s[48:49], 0, v[2:3]
	s_add_i32 m0, s15, 0xc000
	ds_read_b128 v[172:175], v5
	ds_read_b128 v[176:179], v5 offset:1024
	ds_read_b128 v[180:183], v5 offset:2048
	ds_read_b128 v[184:187], v5 offset:3072
	ds_read_b128 v[188:191], v5 offset:4096
	ds_read_b128 v[192:195], v5 offset:5120
	ds_read_b128 v[196:199], v5 offset:6144
	ds_read_b128 v[200:203], v5 offset:7168
	global_load_lds_dwordx4 v[204:205], off
	v_lshl_add_u64 v[204:205], s[48:49], 0, v[136:137]
	s_add_i32 m0, s15, 0xe000
	s_nop 0
	global_load_lds_dwordx4 v[204:205], off
	s_waitcnt vmcnt(8)
	s_waitcnt lgkmcnt(0)
	s_setprio 1
	s_barrier
	v_mfma_f32_16x16x32_bf16 v[130:133], v[140:143], v[172:175], v[130:133]
	v_mfma_f32_16x16x32_bf16 v[126:129], v[148:151], v[172:175], v[126:129]
	v_mfma_f32_16x16x32_bf16 v[122:125], v[140:143], v[180:183], v[122:125]
	v_mfma_f32_16x16x32_bf16 v[114:117], v[148:151], v[180:183], v[114:117]
	v_mfma_f32_16x16x32_bf16 v[106:109], v[140:143], v[188:191], v[106:109]
	v_mfma_f32_16x16x32_bf16 v[98:101], v[148:151], v[188:191], v[98:101]
	v_mfma_f32_16x16x32_bf16 v[90:93], v[140:143], v[196:199], v[90:93]
	v_mfma_f32_16x16x32_bf16 v[82:85], v[148:151], v[196:199], v[82:85]
	v_mfma_f32_16x16x32_bf16 v[130:133], v[144:147], v[176:179], v[130:133]
	v_mfma_f32_16x16x32_bf16 v[126:129], v[152:155], v[176:179], v[126:129]
	v_mfma_f32_16x16x32_bf16 v[122:125], v[144:147], v[184:187], v[122:125]
	v_mfma_f32_16x16x32_bf16 v[114:117], v[152:155], v[184:187], v[114:117]
	v_mfma_f32_16x16x32_bf16 v[106:109], v[144:147], v[192:195], v[106:109]
	v_mfma_f32_16x16x32_bf16 v[98:101], v[152:155], v[192:195], v[98:101]
	v_mfma_f32_16x16x32_bf16 v[90:93], v[144:147], v[200:203], v[90:93]
	v_mfma_f32_16x16x32_bf16 v[82:85], v[152:155], v[200:203], v[82:85]
	s_setprio 0
	s_setprio 1
	v_mfma_f32_16x16x32_bf16 v[118:121], v[156:159], v[172:175], v[118:121]
	v_mfma_f32_16x16x32_bf16 v[110:113], v[164:167], v[172:175], v[110:113]
	v_mfma_f32_16x16x32_bf16 v[102:105], v[156:159], v[180:183], v[102:105]
	v_mfma_f32_16x16x32_bf16 v[94:97], v[164:167], v[180:183], v[94:97]
	v_mfma_f32_16x16x32_bf16 v[86:89], v[156:159], v[188:191], v[86:89]
	v_mfma_f32_16x16x32_bf16 v[78:81], v[164:167], v[188:191], v[78:81]
	v_mfma_f32_16x16x32_bf16 v[74:77], v[156:159], v[196:199], v[74:77]
	v_mfma_f32_16x16x32_bf16 v[70:73], v[164:167], v[196:199], v[70:73]
	v_mfma_f32_16x16x32_bf16 v[118:121], v[160:163], v[176:179], v[118:121]
	v_mfma_f32_16x16x32_bf16 v[110:113], v[168:171], v[176:179], v[110:113]
	v_mfma_f32_16x16x32_bf16 v[102:105], v[160:163], v[184:187], v[102:105]
	v_mfma_f32_16x16x32_bf16 v[94:97], v[168:171], v[184:187], v[94:97]
	v_mfma_f32_16x16x32_bf16 v[86:89], v[160:163], v[192:195], v[86:89]
	v_mfma_f32_16x16x32_bf16 v[78:81], v[168:171], v[192:195], v[78:81]
	v_mfma_f32_16x16x32_bf16 v[74:77], v[160:163], v[200:203], v[74:77]
	v_mfma_f32_16x16x32_bf16 v[70:73], v[168:171], v[200:203], v[70:73]
	s_barrier
	s_setprio 0
	s_add_i32 s48, s50, s29
	v_lshl_add_u64 v[204:205], s[24:25], 0, v[134:135]
	s_mov_b32 m0, s48
	ds_read_b128 v[172:175], v5 offset:16384
	ds_read_b128 v[176:179], v5 offset:17408
	ds_read_b128 v[180:183], v5 offset:18432
	ds_read_b128 v[184:187], v5 offset:19456
	ds_read_b128 v[188:191], v5 offset:20480
	ds_read_b128 v[192:195], v5 offset:21504
	ds_read_b128 v[196:199], v5 offset:22528
	ds_read_b128 v[200:203], v5 offset:23552
	global_load_lds_dwordx4 v[204:205], off
	s_add_i32 m0, s48, 0x2000
	v_lshl_add_u64 v[204:205], s[24:25], 0, v[138:139]
	s_add_u32 s24, s24, 0x20000
	s_addc_u32 s25, s25, 0
	s_add_i32 s48, s51, s29
	global_load_lds_dwordx4 v[204:205], off
	v_lshl_add_u64 v[204:205], s[24:25], 0, v[134:135]
	s_mov_b32 m0, s48
	s_nop 0
	global_load_lds_dwordx4 v[204:205], off
	v_lshl_add_u64 v[204:205], s[24:25], 0, v[138:139]
	s_add_i32 m0, s48, 0x2000
	s_nop 0
	global_load_lds_dwordx4 v[204:205], off
	v_lshl_add_u64 v[204:205], s[22:23], 0, v[2:3]
	s_mov_b32 m0, s15
	s_nop 0
	global_load_lds_dwordx4 v[204:205], off
	v_lshl_add_u64 v[204:205], s[22:23], 0, v[136:137]
	s_mov_b32 m0, s17
	s_nop 0
	global_load_lds_dwordx4 v[204:205], off
	s_waitcnt vmcnt(8)
	s_waitcnt lgkmcnt(0)
	s_setprio 1
	s_barrier
	v_mfma_f32_16x16x32_bf16 v[66:69], v[140:143], v[172:175], v[66:69]
	v_mfma_f32_16x16x32_bf16 v[62:65], v[148:151], v[172:175], v[62:65]
	v_mfma_f32_16x16x32_bf16 v[58:61], v[140:143], v[180:183], v[58:61]
	v_mfma_f32_16x16x32_bf16 v[50:53], v[148:151], v[180:183], v[50:53]
	v_mfma_f32_16x16x32_bf16 v[42:45], v[140:143], v[188:191], v[42:45]
	v_mfma_f32_16x16x32_bf16 v[34:37], v[148:151], v[188:191], v[34:37]
	v_mfma_f32_16x16x32_bf16 v[26:29], v[140:143], v[196:199], v[26:29]
	v_mfma_f32_16x16x32_bf16 v[18:21], v[148:151], v[196:199], v[18:21]
	v_mfma_f32_16x16x32_bf16 v[66:69], v[144:147], v[176:179], v[66:69]
	v_mfma_f32_16x16x32_bf16 v[62:65], v[152:155], v[176:179], v[62:65]
	v_mfma_f32_16x16x32_bf16 v[58:61], v[144:147], v[184:187], v[58:61]
	v_mfma_f32_16x16x32_bf16 v[50:53], v[152:155], v[184:187], v[50:53]
	v_mfma_f32_16x16x32_bf16 v[42:45], v[144:147], v[192:195], v[42:45]
	v_mfma_f32_16x16x32_bf16 v[34:37], v[152:155], v[192:195], v[34:37]
	v_mfma_f32_16x16x32_bf16 v[26:29], v[144:147], v[200:203], v[26:29]
	v_mfma_f32_16x16x32_bf16 v[18:21], v[152:155], v[200:203], v[18:21]
	s_setprio 0
	s_setprio 1
	v_mfma_f32_16x16x32_bf16 v[54:57], v[156:159], v[172:175], v[54:57]
	v_mfma_f32_16x16x32_bf16 v[46:49], v[164:167], v[172:175], v[46:49]
	v_mfma_f32_16x16x32_bf16 v[38:41], v[156:159], v[180:183], v[38:41]
	v_mfma_f32_16x16x32_bf16 v[30:33], v[164:167], v[180:183], v[30:33]
	v_mfma_f32_16x16x32_bf16 v[22:25], v[156:159], v[188:191], v[22:25]
	v_mfma_f32_16x16x32_bf16 v[14:17], v[164:167], v[188:191], v[14:17]
	v_mfma_f32_16x16x32_bf16 v[10:13], v[156:159], v[196:199], v[10:13]
	v_mfma_f32_16x16x32_bf16 v[6:9], v[164:167], v[196:199], v[6:9]
	v_mfma_f32_16x16x32_bf16 v[54:57], v[160:163], v[176:179], v[54:57]
	v_mfma_f32_16x16x32_bf16 v[46:49], v[168:171], v[176:179], v[46:49]
	v_mfma_f32_16x16x32_bf16 v[38:41], v[160:163], v[184:187], v[38:41]
	v_mfma_f32_16x16x32_bf16 v[30:33], v[168:171], v[184:187], v[30:33]
	v_mfma_f32_16x16x32_bf16 v[22:25], v[160:163], v[192:195], v[22:25]
	v_mfma_f32_16x16x32_bf16 v[14:17], v[168:171], v[192:195], v[14:17]
	v_mfma_f32_16x16x32_bf16 v[10:13], v[160:163], v[200:203], v[10:13]
	v_mfma_f32_16x16x32_bf16 v[6:9], v[168:171], v[200:203], v[6:9]
	s_barrier
	s_setprio 0
	s_add_i32 s24, 0, 0x18000
	s_add_i32 s25, 0, 0x1c000
	v_add_u32_e32 v152, s24, v1
	v_add_u32_e32 v168, s25, v1
	ds_read_b128 v[140:143], v152
	ds_read_b128 v[144:147], v152 offset:1024
	ds_read_b128 v[148:151], v152 offset:2048
	ds_read_b128 v[152:155], v152 offset:3072
	ds_read_b128 v[156:159], v168
	ds_read_b128 v[160:163], v168 offset:1024
	ds_read_b128 v[164:167], v168 offset:2048
	ds_read_b128 v[168:171], v168 offset:3072
	s_add_u32 s22, s22, 0x20000
	s_addc_u32 s23, s23, 0
	s_mov_b32 m0, s31
	v_lshl_add_u64 v[204:205], s[22:23], 0, v[2:3]
	ds_read_b128 v[172:175], v5 offset:32768
	ds_read_b128 v[176:179], v5 offset:33792
	ds_read_b128 v[180:183], v5 offset:34816
	ds_read_b128 v[184:187], v5 offset:35840
	ds_read_b128 v[188:191], v5 offset:36864
	ds_read_b128 v[192:195], v5 offset:37888
	ds_read_b128 v[196:199], v5 offset:38912
	ds_read_b128 v[200:203], v5 offset:39936
	global_load_lds_dwordx4 v[204:205], off
	v_lshl_add_u64 v[204:205], s[22:23], 0, v[136:137]
	s_mov_b32 m0, s33
	s_nop 0
	global_load_lds_dwordx4 v[204:205], off
	s_waitcnt vmcnt(8)
	s_waitcnt lgkmcnt(0)
	s_setprio 1
	s_barrier
	v_mfma_f32_16x16x32_bf16 v[130:133], v[140:143], v[172:175], v[130:133]
	v_mfma_f32_16x16x32_bf16 v[126:129], v[148:151], v[172:175], v[126:129]
	v_mfma_f32_16x16x32_bf16 v[122:125], v[140:143], v[180:183], v[122:125]
	v_mfma_f32_16x16x32_bf16 v[114:117], v[148:151], v[180:183], v[114:117]
	v_mfma_f32_16x16x32_bf16 v[106:109], v[140:143], v[188:191], v[106:109]
	v_mfma_f32_16x16x32_bf16 v[98:101], v[148:151], v[188:191], v[98:101]
	v_mfma_f32_16x16x32_bf16 v[90:93], v[140:143], v[196:199], v[90:93]
	v_mfma_f32_16x16x32_bf16 v[82:85], v[148:151], v[196:199], v[82:85]
	v_mfma_f32_16x16x32_bf16 v[130:133], v[144:147], v[176:179], v[130:133]
	v_mfma_f32_16x16x32_bf16 v[126:129], v[152:155], v[176:179], v[126:129]
	v_mfma_f32_16x16x32_bf16 v[122:125], v[144:147], v[184:187], v[122:125]
	v_mfma_f32_16x16x32_bf16 v[114:117], v[152:155], v[184:187], v[114:117]
	v_mfma_f32_16x16x32_bf16 v[106:109], v[144:147], v[192:195], v[106:109]
	v_mfma_f32_16x16x32_bf16 v[98:101], v[152:155], v[192:195], v[98:101]
	v_mfma_f32_16x16x32_bf16 v[90:93], v[144:147], v[200:203], v[90:93]
	v_mfma_f32_16x16x32_bf16 v[82:85], v[152:155], v[200:203], v[82:85]
	s_setprio 0
	s_setprio 1
	v_mfma_f32_16x16x32_bf16 v[118:121], v[156:159], v[172:175], v[118:121]
	v_mfma_f32_16x16x32_bf16 v[110:113], v[164:167], v[172:175], v[110:113]
	v_mfma_f32_16x16x32_bf16 v[102:105], v[156:159], v[180:183], v[102:105]
	v_mfma_f32_16x16x32_bf16 v[94:97], v[164:167], v[180:183], v[94:97]
	v_mfma_f32_16x16x32_bf16 v[86:89], v[156:159], v[188:191], v[86:89]
	v_mfma_f32_16x16x32_bf16 v[78:81], v[164:167], v[188:191], v[78:81]
	v_mfma_f32_16x16x32_bf16 v[74:77], v[156:159], v[196:199], v[74:77]
	v_mfma_f32_16x16x32_bf16 v[70:73], v[164:167], v[196:199], v[70:73]
	v_mfma_f32_16x16x32_bf16 v[118:121], v[160:163], v[176:179], v[118:121]
	v_mfma_f32_16x16x32_bf16 v[110:113], v[168:171], v[176:179], v[110:113]
	v_mfma_f32_16x16x32_bf16 v[102:105], v[160:163], v[184:187], v[102:105]
	v_mfma_f32_16x16x32_bf16 v[94:97], v[168:171], v[184:187], v[94:97]
	v_mfma_f32_16x16x32_bf16 v[86:89], v[160:163], v[192:195], v[86:89]
	v_mfma_f32_16x16x32_bf16 v[78:81], v[168:171], v[192:195], v[78:81]
	v_mfma_f32_16x16x32_bf16 v[74:77], v[160:163], v[200:203], v[74:77]
	v_mfma_f32_16x16x32_bf16 v[70:73], v[168:171], v[200:203], v[70:73]
	s_barrier
	s_setprio 0
	s_add_i32 s22, s24, s29
	v_lshl_add_u64 v[204:205], s[20:21], 0, v[134:135]
	s_mov_b32 m0, s22
	ds_read_b128 v[172:175], v5 offset:49152
	ds_read_b128 v[176:179], v5 offset:50176
	ds_read_b128 v[180:183], v5 offset:51200
	ds_read_b128 v[184:187], v5 offset:52224
	ds_read_b128 v[188:191], v5 offset:53248
	ds_read_b128 v[192:195], v5 offset:54272
	ds_read_b128 v[196:199], v5 offset:55296
	ds_read_b128 v[200:203], v5 offset:56320
	global_load_lds_dwordx4 v[204:205], off
	s_add_i32 m0, s22, 0x2000
	v_lshl_add_u64 v[204:205], s[20:21], 0, v[138:139]
	s_add_u32 s20, s20, 0x20000
	s_addc_u32 s21, s21, 0
	s_add_i32 s22, s25, s29
	global_load_lds_dwordx4 v[204:205], off
	v_lshl_add_u64 v[204:205], s[20:21], 0, v[134:135]
	s_mov_b32 m0, s22
	s_nop 0
	global_load_lds_dwordx4 v[204:205], off
	v_lshl_add_u64 v[204:205], s[20:21], 0, v[138:139]
	s_add_i32 m0, s22, 0x2000
	s_nop 0
	global_load_lds_dwordx4 v[204:205], off
	v_lshl_add_u64 v[204:205], s[18:19], 0, v[2:3]
	s_mov_b32 m0, s38
	s_nop 0
	global_load_lds_dwordx4 v[204:205], off
	v_lshl_add_u64 v[204:205], s[18:19], 0, v[136:137]
	s_mov_b32 m0, s39
	s_nop 0
	global_load_lds_dwordx4 v[204:205], off
	s_waitcnt vmcnt(8)
	s_waitcnt lgkmcnt(0)
	s_setprio 1
	s_barrier
	v_mfma_f32_16x16x32_bf16 v[66:69], v[140:143], v[172:175], v[66:69]
	v_mfma_f32_16x16x32_bf16 v[62:65], v[148:151], v[172:175], v[62:65]
	v_mfma_f32_16x16x32_bf16 v[58:61], v[140:143], v[180:183], v[58:61]
	v_mfma_f32_16x16x32_bf16 v[50:53], v[148:151], v[180:183], v[50:53]
	v_mfma_f32_16x16x32_bf16 v[42:45], v[140:143], v[188:191], v[42:45]
	v_mfma_f32_16x16x32_bf16 v[34:37], v[148:151], v[188:191], v[34:37]
	v_mfma_f32_16x16x32_bf16 v[26:29], v[140:143], v[196:199], v[26:29]
	v_mfma_f32_16x16x32_bf16 v[18:21], v[148:151], v[196:199], v[18:21]
	v_mfma_f32_16x16x32_bf16 v[66:69], v[144:147], v[176:179], v[66:69]
	v_mfma_f32_16x16x32_bf16 v[62:65], v[152:155], v[176:179], v[62:65]
	v_mfma_f32_16x16x32_bf16 v[58:61], v[144:147], v[184:187], v[58:61]
	v_mfma_f32_16x16x32_bf16 v[50:53], v[152:155], v[184:187], v[50:53]
	v_mfma_f32_16x16x32_bf16 v[42:45], v[144:147], v[192:195], v[42:45]
	v_mfma_f32_16x16x32_bf16 v[34:37], v[152:155], v[192:195], v[34:37]
	v_mfma_f32_16x16x32_bf16 v[26:29], v[144:147], v[200:203], v[26:29]
	v_mfma_f32_16x16x32_bf16 v[18:21], v[152:155], v[200:203], v[18:21]
	s_setprio 0
	s_setprio 1
	v_mfma_f32_16x16x32_bf16 v[54:57], v[156:159], v[172:175], v[54:57]
	v_mfma_f32_16x16x32_bf16 v[46:49], v[164:167], v[172:175], v[46:49]
	v_mfma_f32_16x16x32_bf16 v[38:41], v[156:159], v[180:183], v[38:41]
	v_mfma_f32_16x16x32_bf16 v[30:33], v[164:167], v[180:183], v[30:33]
	v_mfma_f32_16x16x32_bf16 v[22:25], v[156:159], v[188:191], v[22:25]
	v_mfma_f32_16x16x32_bf16 v[14:17], v[164:167], v[188:191], v[14:17]
	v_mfma_f32_16x16x32_bf16 v[10:13], v[156:159], v[196:199], v[10:13]
	v_mfma_f32_16x16x32_bf16 v[6:9], v[164:167], v[196:199], v[6:9]
	v_mfma_f32_16x16x32_bf16 v[54:57], v[160:163], v[176:179], v[54:57]
	v_mfma_f32_16x16x32_bf16 v[46:49], v[168:171], v[176:179], v[46:49]
	v_mfma_f32_16x16x32_bf16 v[38:41], v[160:163], v[184:187], v[38:41]
	v_mfma_f32_16x16x32_bf16 v[30:33], v[168:171], v[184:187], v[30:33]
	v_mfma_f32_16x16x32_bf16 v[22:25], v[160:163], v[192:195], v[22:25]
	v_mfma_f32_16x16x32_bf16 v[14:17], v[168:171], v[192:195], v[14:17]
	v_mfma_f32_16x16x32_bf16 v[10:13], v[160:163], v[200:203], v[10:13]
	v_mfma_f32_16x16x32_bf16 v[6:9], v[168:171], v[200:203], v[6:9]
	s_barrier
	s_setprio 0
	s_add_i32 s47, s47, 2
	s_add_u32 s43, s43, 0x100
	s_addc_u32 s44, s44, 0
	s_add_u32 s45, s45, 0x100
	s_addc_u32 s46, s46, 0
	s_cmp_gt_u32 s47, 5
	s_cbranch_scc0 .LBB0_536
	s_lshl_b32 s20, s16, 8
	v_mov_b32_e32 v140, v0
	s_mov_b64 s[18:19], s[84:85]
	s_lshl_b32 s7, s14, 8
	s_ashr_i32 s21, s20, 31
	s_add_i32 s7, s7, s34
	s_lshl_b64 s[20:21], s[20:21], 1
	v_and_b32_e32 v142, 15, v140
	s_add_u32 s18, s18, s20
	v_or_b32_e32 v146, s7, v142
	v_lshrrev_b32_e32 v140, 1, v140
	s_addc_u32 s19, s19, s21
	s_ashr_i32 s9, s7, 11
	v_mov_b32_e32 v143, s7
	s_movk_i32 s7, 0x7cf
	v_and_or_b32 v140, v140, 24, s35
	s_mulk_i32 s9, 0x810
	v_bitop3_b32 v142, v142, s7, v143 bitop3:0xc8
	v_lshlrev_b32_e32 v140, 1, v140
	v_mov_b32_e32 v141, v4
	v_add_u32_e32 v142, s9, v142
	v_lshl_add_u64 v[140:141], s[18:19], 0, v[140:141]
	s_mov_b64 s[18:19], 0x2c900000
	v_ashrrev_i32_e32 v143, 31, v142
	v_lshl_add_u64 v[140:141], v[140:141], 0, s[18:19]
	v_lshlrev_b64 v[144:145], 13, v[142:143]
	v_lshl_add_u64 v[144:145], v[140:141], 0, v[144:145]
	v_cvt_pk_bf16_f32 v130, v130, v131
	v_cvt_pk_bf16_f32 v131, v132, v133
	v_cvt_pk_bf16_f32 v132, v126, v127
	v_cvt_pk_bf16_f32 v133, v128, v129
	global_store_dwordx4 v[144:145], v[130:133], off nt
	v_cvt_pk_bf16_f32 v118, v118, v119
	v_cvt_pk_bf16_f32 v119, v120, v121
	v_cvt_pk_bf16_f32 v120, v110, v111
	v_add_u32_e32 v110, 16, v142
	v_ashrrev_i32_e32 v111, 31, v110
	v_lshlrev_b64 v[110:111], 13, v[110:111]
	v_cvt_pk_bf16_f32 v121, v112, v113
	global_store_dwordx4 v[144:145], v[118:121], off offset:256 nt
	s_movk_i32 s7, 0x810
	s_and_b64 vcc, exec, s[0:1]
	v_lshl_add_u64 v[118:119], v[140:141], 0, v[110:111]
	v_cvt_pk_bf16_f32 v110, v122, v123
	v_cvt_pk_bf16_f32 v111, v124, v125
	v_cvt_pk_bf16_f32 v112, v114, v115
	v_cvt_pk_bf16_f32 v113, v116, v117
	global_store_dwordx4 v[118:119], v[110:113], off nt
	v_cvt_pk_bf16_f32 v102, v102, v103
	v_cvt_pk_bf16_f32 v103, v104, v105
	v_cvt_pk_bf16_f32 v104, v94, v95
	v_add_u32_e32 v94, 32, v142
	v_ashrrev_i32_e32 v95, 31, v94
	v_lshlrev_b64 v[94:95], 13, v[94:95]
	v_cvt_pk_bf16_f32 v105, v96, v97
	global_store_dwordx4 v[118:119], v[102:105], off offset:256 nt
	s_mov_b32 s16, s8
	s_mov_b32 s14, s6
	v_lshl_add_u64 v[102:103], v[140:141], 0, v[94:95]
	v_cvt_pk_bf16_f32 v94, v106, v107
	v_cvt_pk_bf16_f32 v95, v108, v109
	v_cvt_pk_bf16_f32 v96, v98, v99
	v_cvt_pk_bf16_f32 v97, v100, v101
	global_store_dwordx4 v[102:103], v[94:97], off nt
	v_cvt_pk_bf16_f32 v86, v86, v87
	v_cvt_pk_bf16_f32 v87, v88, v89
	v_cvt_pk_bf16_f32 v88, v78, v79
	v_add_u32_e32 v78, 48, v142
	v_ashrrev_i32_e32 v79, 31, v78
	v_lshlrev_b64 v[78:79], 13, v[78:79]
	v_cvt_pk_bf16_f32 v89, v80, v81
	global_store_dwordx4 v[102:103], v[86:89], off offset:256 nt
	s_mov_b64 s[20:21], s[10:11]
	s_mov_b64 s[18:19], s[12:13]
	v_lshl_add_u64 v[86:87], v[140:141], 0, v[78:79]
	v_cvt_pk_bf16_f32 v78, v90, v91
	v_cvt_pk_bf16_f32 v79, v92, v93
	v_cvt_pk_bf16_f32 v80, v82, v83
	v_cvt_pk_bf16_f32 v81, v84, v85
	global_store_dwordx4 v[86:87], v[78:81], off nt
	v_cvt_pk_bf16_f32 v74, v74, v75
	v_cvt_pk_bf16_f32 v75, v76, v77
	v_cvt_pk_bf16_f32 v76, v70, v71
	v_add_u32_e32 v70, 0x80, v146
	v_ashrrev_i32_e32 v71, 11, v70
	v_and_b32_e32 v70, 0x7cf, v70
	v_mad_i32_i24 v70, v71, s7, v70
	v_ashrrev_i32_e32 v71, 31, v70
	v_cvt_pk_bf16_f32 v77, v72, v73
	v_lshlrev_b64 v[72:73], 13, v[70:71]
	global_store_dwordx4 v[86:87], v[74:77], off offset:256 nt
	v_lshl_add_u64 v[72:73], v[140:141], 0, v[72:73]
	v_cvt_pk_bf16_f32 v66, v66, v67
	v_cvt_pk_bf16_f32 v67, v68, v69
	v_cvt_pk_bf16_f32 v68, v62, v63
	v_cvt_pk_bf16_f32 v69, v64, v65
	global_store_dwordx4 v[72:73], v[66:69], off nt
	v_cvt_pk_bf16_f32 v54, v54, v55
	v_cvt_pk_bf16_f32 v55, v56, v57
	v_cvt_pk_bf16_f32 v56, v46, v47
	v_add_u32_e32 v46, 16, v70
	v_ashrrev_i32_e32 v47, 31, v46
	v_lshlrev_b64 v[46:47], 13, v[46:47]
	v_cvt_pk_bf16_f32 v57, v48, v49
	global_store_dwordx4 v[72:73], v[54:57], off offset:256 nt
	s_mov_b32 s51, 0x40c000
	s_mov_b32 s47, 0x120000
	v_lshl_add_u64 v[54:55], v[140:141], 0, v[46:47]
	v_cvt_pk_bf16_f32 v46, v58, v59
	v_cvt_pk_bf16_f32 v47, v60, v61
	v_cvt_pk_bf16_f32 v48, v50, v51
	v_cvt_pk_bf16_f32 v49, v52, v53
	global_store_dwordx4 v[54:55], v[46:49], off nt
	v_cvt_pk_bf16_f32 v38, v38, v39
	v_cvt_pk_bf16_f32 v39, v40, v41
	v_cvt_pk_bf16_f32 v40, v30, v31
	v_add_u32_e32 v30, 32, v70
	v_ashrrev_i32_e32 v31, 31, v30
	v_lshlrev_b64 v[30:31], 13, v[30:31]
	v_cvt_pk_bf16_f32 v41, v32, v33
	global_store_dwordx4 v[54:55], v[38:41], off offset:256 nt
	s_mov_b64 s[48:49], 0x7ffff
	s_nop 0
	v_lshl_add_u64 v[38:39], v[140:141], 0, v[30:31]
	v_cvt_pk_bf16_f32 v30, v42, v43
	v_cvt_pk_bf16_f32 v31, v44, v45
	v_cvt_pk_bf16_f32 v32, v34, v35
	v_cvt_pk_bf16_f32 v33, v36, v37
	global_store_dwordx4 v[38:39], v[30:33], off nt
	v_cvt_pk_bf16_f32 v22, v22, v23
	v_cvt_pk_bf16_f32 v23, v24, v25
	v_cvt_pk_bf16_f32 v24, v14, v15
	v_add_u32_e32 v14, 48, v70
	v_ashrrev_i32_e32 v15, 31, v14
	v_lshlrev_b64 v[14:15], 13, v[14:15]
	v_cvt_pk_bf16_f32 v25, v16, v17
	global_store_dwordx4 v[38:39], v[22:25], off offset:256 nt
	s_nop 1
	v_lshl_add_u64 v[22:23], v[140:141], 0, v[14:15]
	v_cvt_pk_bf16_f32 v14, v26, v27
	v_cvt_pk_bf16_f32 v15, v28, v29
	v_cvt_pk_bf16_f32 v16, v18, v19
	v_cvt_pk_bf16_f32 v17, v20, v21
	global_store_dwordx4 v[22:23], v[14:17], off nt
	v_cvt_pk_bf16_f32 v10, v10, v11
	v_cvt_pk_bf16_f32 v11, v12, v13
	v_cvt_pk_bf16_f32 v12, v6, v7
	v_cvt_pk_bf16_f32 v13, v8, v9
	global_store_dwordx4 v[22:23], v[10:13], off offset:256 nt
	s_cbranch_vccz .LBB0_529
	s_waitcnt vmcnt(0)
	s_cmpk_gt_u32 s28, 0xff
	s_cbranch_scc1 .LBB0_540
	s_barrier

.LBB0_924:
	s_add_u32 s48, s45, 0xffffff80
	s_addc_u32 s49, s46, -1
	s_cmp_eq_u32 s47, 60
	s_cselect_b32 s22, s9, s45
	s_cselect_b32 s23, s7, s46
	s_cselect_b32 s25, s11, s44
	s_cselect_b32 s24, s13, s33
	s_add_u32 s18, s22, 0x80
	s_addc_u32 s19, s23, 0
	s_add_u32 s20, s24, 0x80
	s_addc_u32 s21, s25, 0
	s_add_i32 s50, 0, 0x10000
	s_add_i32 s51, 0, 0x14000
	v_add_u32_e32 v90, s50, v1
	v_add_u32_e32 v162, s51, v1
	ds_read_b128 v[78:81], v90
	ds_read_b128 v[82:85], v90 offset:1024
	ds_read_b128 v[86:89], v90 offset:2048
	ds_read_b128 v[90:93], v90 offset:3072
	ds_read_b128 v[142:145], v162
	ds_read_b128 v[146:149], v162 offset:1024
	ds_read_b128 v[158:161], v162 offset:2048
	ds_read_b128 v[162:165], v162 offset:3072
	s_add_u32 s48, s48, 0x100000
	s_addc_u32 s49, s49, 0
	v_lshl_add_u64 v[198:199], s[48:49], 0, v[2:3]
	s_add_i32 m0, s35, 0xc000
	ds_read_b128 v[166:169], v5
	ds_read_b128 v[170:173], v5 offset:1024
	ds_read_b128 v[174:177], v5 offset:2048
	ds_read_b128 v[178:181], v5 offset:3072
	ds_read_b128 v[182:185], v5 offset:4096
	ds_read_b128 v[186:189], v5 offset:5120
	ds_read_b128 v[190:193], v5 offset:6144
	ds_read_b128 v[194:197], v5 offset:7168
	global_load_lds_dwordx4 v[198:199], off
	v_lshl_add_u64 v[198:199], s[48:49], 0, v[218:219]
	s_add_i32 m0, s35, 0xe000
	s_nop 0
	global_load_lds_dwordx4 v[198:199], off
	s_waitcnt vmcnt(8)
	s_waitcnt lgkmcnt(0)
	s_setprio 1
	s_barrier
	v_mfma_f32_16x16x32_bf16 v[154:157], v[78:81], v[166:169], v[154:157]
	v_mfma_f32_16x16x32_bf16 v[150:153], v[86:89], v[166:169], v[150:153]
	v_mfma_f32_16x16x32_bf16 v[134:137], v[78:81], v[174:177], v[134:137]
	v_mfma_f32_16x16x32_bf16 v[126:129], v[86:89], v[174:177], v[126:129]
	v_mfma_f32_16x16x32_bf16 v[118:121], v[78:81], v[182:185], v[118:121]
	v_mfma_f32_16x16x32_bf16 v[110:113], v[86:89], v[182:185], v[110:113]
	v_mfma_f32_16x16x32_bf16 v[102:105], v[78:81], v[190:193], v[102:105]
	v_mfma_f32_16x16x32_bf16 v[94:97], v[86:89], v[190:193], v[94:97]
	v_mfma_f32_16x16x32_bf16 v[154:157], v[82:85], v[170:173], v[154:157]
	v_mfma_f32_16x16x32_bf16 v[150:153], v[90:93], v[170:173], v[150:153]
	v_mfma_f32_16x16x32_bf16 v[134:137], v[82:85], v[178:181], v[134:137]
	v_mfma_f32_16x16x32_bf16 v[126:129], v[90:93], v[178:181], v[126:129]
	v_mfma_f32_16x16x32_bf16 v[118:121], v[82:85], v[186:189], v[118:121]
	v_mfma_f32_16x16x32_bf16 v[110:113], v[90:93], v[186:189], v[110:113]
	v_mfma_f32_16x16x32_bf16 v[102:105], v[82:85], v[194:197], v[102:105]
	v_mfma_f32_16x16x32_bf16 v[94:97], v[90:93], v[194:197], v[94:97]
	s_setprio 0
	s_setprio 1
	v_mfma_f32_16x16x32_bf16 v[138:141], v[142:145], v[166:169], v[138:141]
	v_mfma_f32_16x16x32_bf16 v[130:133], v[158:161], v[166:169], v[130:133]
	v_mfma_f32_16x16x32_bf16 v[122:125], v[142:145], v[174:177], v[122:125]
	v_mfma_f32_16x16x32_bf16 v[114:117], v[158:161], v[174:177], v[114:117]
	v_mfma_f32_16x16x32_bf16 v[106:109], v[142:145], v[182:185], v[106:109]
	v_mfma_f32_16x16x32_bf16 v[98:101], v[158:161], v[182:185], v[98:101]
	v_mfma_f32_16x16x32_bf16 v[74:77], v[142:145], v[190:193], v[74:77]
	v_mfma_f32_16x16x32_bf16 v[70:73], v[158:161], v[190:193], v[70:73]
	v_mfma_f32_16x16x32_bf16 v[138:141], v[146:149], v[170:173], v[138:141]
	v_mfma_f32_16x16x32_bf16 v[130:133], v[162:165], v[170:173], v[130:133]
	v_mfma_f32_16x16x32_bf16 v[122:125], v[146:149], v[178:181], v[122:125]
	v_mfma_f32_16x16x32_bf16 v[114:117], v[162:165], v[178:181], v[114:117]
	v_mfma_f32_16x16x32_bf16 v[106:109], v[146:149], v[186:189], v[106:109]
	v_mfma_f32_16x16x32_bf16 v[98:101], v[162:165], v[186:189], v[98:101]
	v_mfma_f32_16x16x32_bf16 v[74:77], v[146:149], v[194:197], v[74:77]
	v_mfma_f32_16x16x32_bf16 v[70:73], v[162:165], v[194:197], v[70:73]
	s_barrier
	s_setprio 0
	s_add_i32 s48, s50, s29
	v_lshl_add_u64 v[198:199], s[24:25], 0, v[216:217]
	s_mov_b32 m0, s48
	ds_read_b128 v[166:169], v5 offset:16384
	ds_read_b128 v[170:173], v5 offset:17408
	ds_read_b128 v[174:177], v5 offset:18432
	ds_read_b128 v[178:181], v5 offset:19456
	ds_read_b128 v[182:185], v5 offset:20480
	ds_read_b128 v[186:189], v5 offset:21504
	ds_read_b128 v[190:193], v5 offset:22528
	ds_read_b128 v[194:197], v5 offset:23552
	global_load_lds_dwordx4 v[198:199], off
	s_add_i32 m0, s48, 0x2000
	v_lshl_add_u64 v[198:199], s[24:25], 0, v[220:221]
	s_add_u32 s24, s24, 0x100000
	s_addc_u32 s25, s25, 0
	s_add_i32 s48, s51, s29
	global_load_lds_dwordx4 v[198:199], off
	v_lshl_add_u64 v[198:199], s[24:25], 0, v[216:217]
	s_mov_b32 m0, s48
	s_nop 0
	global_load_lds_dwordx4 v[198:199], off
	v_lshl_add_u64 v[198:199], s[24:25], 0, v[220:221]
	s_add_i32 m0, s48, 0x2000
	s_nop 0
	global_load_lds_dwordx4 v[198:199], off
	v_lshl_add_u64 v[198:199], s[22:23], 0, v[2:3]
	s_mov_b32 m0, s35
	s_nop 0
	global_load_lds_dwordx4 v[198:199], off
	v_lshl_add_u64 v[198:199], s[22:23], 0, v[218:219]
	s_mov_b32 m0, s36
	s_nop 0
	global_load_lds_dwordx4 v[198:199], off
	s_waitcnt vmcnt(8)
	s_waitcnt lgkmcnt(0)
	s_setprio 1
	s_barrier
	v_mfma_f32_16x16x32_bf16 v[66:69], v[78:81], v[166:169], v[66:69]
	v_mfma_f32_16x16x32_bf16 v[62:65], v[86:89], v[166:169], v[62:65]
	v_mfma_f32_16x16x32_bf16 v[54:57], v[78:81], v[174:177], v[54:57]
	v_mfma_f32_16x16x32_bf16 v[46:49], v[86:89], v[174:177], v[46:49]
	v_mfma_f32_16x16x32_bf16 v[38:41], v[78:81], v[182:185], v[38:41]
	v_mfma_f32_16x16x32_bf16 v[30:33], v[86:89], v[182:185], v[30:33]
	v_mfma_f32_16x16x32_bf16 v[22:25], v[78:81], v[190:193], v[22:25]
	v_mfma_f32_16x16x32_bf16 v[14:17], v[86:89], v[190:193], v[14:17]
	v_mfma_f32_16x16x32_bf16 v[66:69], v[82:85], v[170:173], v[66:69]
	v_mfma_f32_16x16x32_bf16 v[62:65], v[90:93], v[170:173], v[62:65]
	v_mfma_f32_16x16x32_bf16 v[54:57], v[82:85], v[178:181], v[54:57]
	v_mfma_f32_16x16x32_bf16 v[46:49], v[90:93], v[178:181], v[46:49]
	v_mfma_f32_16x16x32_bf16 v[38:41], v[82:85], v[186:189], v[38:41]
	v_mfma_f32_16x16x32_bf16 v[30:33], v[90:93], v[186:189], v[30:33]
	v_mfma_f32_16x16x32_bf16 v[22:25], v[82:85], v[194:197], v[22:25]
	v_mfma_f32_16x16x32_bf16 v[14:17], v[90:93], v[194:197], v[14:17]
	s_setprio 0
	s_setprio 1
	v_mfma_f32_16x16x32_bf16 v[58:61], v[142:145], v[166:169], v[58:61]
	v_mfma_f32_16x16x32_bf16 v[50:53], v[158:161], v[166:169], v[50:53]
	v_mfma_f32_16x16x32_bf16 v[42:45], v[142:145], v[174:177], v[42:45]
	v_mfma_f32_16x16x32_bf16 v[34:37], v[158:161], v[174:177], v[34:37]
	v_mfma_f32_16x16x32_bf16 v[26:29], v[142:145], v[182:185], v[26:29]
	v_mfma_f32_16x16x32_bf16 v[18:21], v[158:161], v[182:185], v[18:21]
	v_mfma_f32_16x16x32_bf16 v[10:13], v[142:145], v[190:193], v[10:13]
	v_mfma_f32_16x16x32_bf16 v[6:9], v[158:161], v[190:193], v[6:9]
	v_mfma_f32_16x16x32_bf16 v[58:61], v[146:149], v[170:173], v[58:61]
	v_mfma_f32_16x16x32_bf16 v[50:53], v[162:165], v[170:173], v[50:53]
	v_mfma_f32_16x16x32_bf16 v[42:45], v[146:149], v[178:181], v[42:45]
	v_mfma_f32_16x16x32_bf16 v[34:37], v[162:165], v[178:181], v[34:37]
	v_mfma_f32_16x16x32_bf16 v[26:29], v[146:149], v[186:189], v[26:29]
	v_mfma_f32_16x16x32_bf16 v[18:21], v[162:165], v[186:189], v[18:21]
	v_mfma_f32_16x16x32_bf16 v[10:13], v[146:149], v[194:197], v[10:13]
	v_mfma_f32_16x16x32_bf16 v[6:9], v[162:165], v[194:197], v[6:9]
	s_barrier
	s_setprio 0
	s_add_i32 s24, 0, 0x18000
	s_add_i32 s25, 0, 0x1c000
	v_add_u32_e32 v90, s24, v1
	v_add_u32_e32 v162, s25, v1
	ds_read_b128 v[78:81], v90
	ds_read_b128 v[82:85], v90 offset:1024
	ds_read_b128 v[86:89], v90 offset:2048
	ds_read_b128 v[90:93], v90 offset:3072
	ds_read_b128 v[142:145], v162
	ds_read_b128 v[146:149], v162 offset:1024
	ds_read_b128 v[158:161], v162 offset:2048
	ds_read_b128 v[162:165], v162 offset:3072
	s_add_u32 s22, s22, 0x100000
	s_addc_u32 s23, s23, 0
	s_mov_b32 m0, s37
	v_lshl_add_u64 v[198:199], s[22:23], 0, v[2:3]
	ds_read_b128 v[166:169], v5 offset:32768
	ds_read_b128 v[170:173], v5 offset:33792
	ds_read_b128 v[174:177], v5 offset:34816
	ds_read_b128 v[178:181], v5 offset:35840
	ds_read_b128 v[182:185], v5 offset:36864
	ds_read_b128 v[186:189], v5 offset:37888
	ds_read_b128 v[190:193], v5 offset:38912
	ds_read_b128 v[194:197], v5 offset:39936
	global_load_lds_dwordx4 v[198:199], off
	v_lshl_add_u64 v[198:199], s[22:23], 0, v[218:219]
	s_mov_b32 m0, s38
	s_nop 0
	global_load_lds_dwordx4 v[198:199], off
	s_waitcnt vmcnt(8)
	s_waitcnt lgkmcnt(0)
	s_setprio 1
	s_barrier
	v_mfma_f32_16x16x32_bf16 v[154:157], v[78:81], v[166:169], v[154:157]
	v_mfma_f32_16x16x32_bf16 v[150:153], v[86:89], v[166:169], v[150:153]
	v_mfma_f32_16x16x32_bf16 v[134:137], v[78:81], v[174:177], v[134:137]
	v_mfma_f32_16x16x32_bf16 v[126:129], v[86:89], v[174:177], v[126:129]
	v_mfma_f32_16x16x32_bf16 v[118:121], v[78:81], v[182:185], v[118:121]
	v_mfma_f32_16x16x32_bf16 v[110:113], v[86:89], v[182:185], v[110:113]
	v_mfma_f32_16x16x32_bf16 v[102:105], v[78:81], v[190:193], v[102:105]
	v_mfma_f32_16x16x32_bf16 v[94:97], v[86:89], v[190:193], v[94:97]
	v_mfma_f32_16x16x32_bf16 v[154:157], v[82:85], v[170:173], v[154:157]
	v_mfma_f32_16x16x32_bf16 v[150:153], v[90:93], v[170:173], v[150:153]
	v_mfma_f32_16x16x32_bf16 v[134:137], v[82:85], v[178:181], v[134:137]
	v_mfma_f32_16x16x32_bf16 v[126:129], v[90:93], v[178:181], v[126:129]
	v_mfma_f32_16x16x32_bf16 v[118:121], v[82:85], v[186:189], v[118:121]
	v_mfma_f32_16x16x32_bf16 v[110:113], v[90:93], v[186:189], v[110:113]
	v_mfma_f32_16x16x32_bf16 v[102:105], v[82:85], v[194:197], v[102:105]
	v_mfma_f32_16x16x32_bf16 v[94:97], v[90:93], v[194:197], v[94:97]
	s_setprio 0
	s_setprio 1
	v_mfma_f32_16x16x32_bf16 v[138:141], v[142:145], v[166:169], v[138:141]
	v_mfma_f32_16x16x32_bf16 v[130:133], v[158:161], v[166:169], v[130:133]
	v_mfma_f32_16x16x32_bf16 v[122:125], v[142:145], v[174:177], v[122:125]
	v_mfma_f32_16x16x32_bf16 v[114:117], v[158:161], v[174:177], v[114:117]
	v_mfma_f32_16x16x32_bf16 v[106:109], v[142:145], v[182:185], v[106:109]
	v_mfma_f32_16x16x32_bf16 v[98:101], v[158:161], v[182:185], v[98:101]
	v_mfma_f32_16x16x32_bf16 v[74:77], v[142:145], v[190:193], v[74:77]
	v_mfma_f32_16x16x32_bf16 v[70:73], v[158:161], v[190:193], v[70:73]
	v_mfma_f32_16x16x32_bf16 v[138:141], v[146:149], v[170:173], v[138:141]
	v_mfma_f32_16x16x32_bf16 v[130:133], v[162:165], v[170:173], v[130:133]
	v_mfma_f32_16x16x32_bf16 v[122:125], v[146:149], v[178:181], v[122:125]
	v_mfma_f32_16x16x32_bf16 v[114:117], v[162:165], v[178:181], v[114:117]
	v_mfma_f32_16x16x32_bf16 v[106:109], v[146:149], v[186:189], v[106:109]
	v_mfma_f32_16x16x32_bf16 v[98:101], v[162:165], v[186:189], v[98:101]
	v_mfma_f32_16x16x32_bf16 v[74:77], v[146:149], v[194:197], v[74:77]
	v_mfma_f32_16x16x32_bf16 v[70:73], v[162:165], v[194:197], v[70:73]
	s_barrier
	s_setprio 0
	s_add_i32 s22, s24, s29
	v_lshl_add_u64 v[198:199], s[20:21], 0, v[216:217]
	s_mov_b32 m0, s22
	ds_read_b128 v[166:169], v5 offset:49152
	ds_read_b128 v[170:173], v5 offset:50176
	ds_read_b128 v[174:177], v5 offset:51200
	ds_read_b128 v[178:181], v5 offset:52224
	ds_read_b128 v[182:185], v5 offset:53248
	ds_read_b128 v[186:189], v5 offset:54272
	ds_read_b128 v[190:193], v5 offset:55296
	ds_read_b128 v[194:197], v5 offset:56320
	global_load_lds_dwordx4 v[198:199], off
	s_add_i32 m0, s22, 0x2000
	v_lshl_add_u64 v[198:199], s[20:21], 0, v[220:221]
	s_add_u32 s20, s20, 0x100000
	s_addc_u32 s21, s21, 0
	s_add_i32 s22, s25, s29
	global_load_lds_dwordx4 v[198:199], off
	v_lshl_add_u64 v[198:199], s[20:21], 0, v[216:217]
	s_mov_b32 m0, s22
	s_nop 0
	global_load_lds_dwordx4 v[198:199], off
	v_lshl_add_u64 v[198:199], s[20:21], 0, v[220:221]
	s_add_i32 m0, s22, 0x2000
	s_nop 0
	global_load_lds_dwordx4 v[198:199], off
	v_lshl_add_u64 v[198:199], s[18:19], 0, v[2:3]
	s_mov_b32 m0, s41
	s_nop 0
	global_load_lds_dwordx4 v[198:199], off
	v_lshl_add_u64 v[198:199], s[18:19], 0, v[218:219]
	s_mov_b32 m0, s42
	s_nop 0
	global_load_lds_dwordx4 v[198:199], off
	s_waitcnt vmcnt(8)
	s_waitcnt lgkmcnt(0)
	s_setprio 1
	s_barrier
	v_mfma_f32_16x16x32_bf16 v[66:69], v[78:81], v[166:169], v[66:69]
	v_mfma_f32_16x16x32_bf16 v[62:65], v[86:89], v[166:169], v[62:65]
	v_mfma_f32_16x16x32_bf16 v[54:57], v[78:81], v[174:177], v[54:57]
	v_mfma_f32_16x16x32_bf16 v[46:49], v[86:89], v[174:177], v[46:49]
	v_mfma_f32_16x16x32_bf16 v[38:41], v[78:81], v[182:185], v[38:41]
	v_mfma_f32_16x16x32_bf16 v[30:33], v[86:89], v[182:185], v[30:33]
	v_mfma_f32_16x16x32_bf16 v[22:25], v[78:81], v[190:193], v[22:25]
	v_mfma_f32_16x16x32_bf16 v[14:17], v[86:89], v[190:193], v[14:17]
	v_mfma_f32_16x16x32_bf16 v[66:69], v[82:85], v[170:173], v[66:69]
	v_mfma_f32_16x16x32_bf16 v[62:65], v[90:93], v[170:173], v[62:65]
	v_mfma_f32_16x16x32_bf16 v[54:57], v[82:85], v[178:181], v[54:57]
	v_mfma_f32_16x16x32_bf16 v[46:49], v[90:93], v[178:181], v[46:49]
	v_mfma_f32_16x16x32_bf16 v[38:41], v[82:85], v[186:189], v[38:41]
	v_mfma_f32_16x16x32_bf16 v[30:33], v[90:93], v[186:189], v[30:33]
	v_mfma_f32_16x16x32_bf16 v[22:25], v[82:85], v[194:197], v[22:25]
	v_mfma_f32_16x16x32_bf16 v[14:17], v[90:93], v[194:197], v[14:17]
	s_setprio 0
	s_setprio 1
	v_mfma_f32_16x16x32_bf16 v[58:61], v[142:145], v[166:169], v[58:61]
	v_mfma_f32_16x16x32_bf16 v[50:53], v[158:161], v[166:169], v[50:53]
	v_mfma_f32_16x16x32_bf16 v[42:45], v[142:145], v[174:177], v[42:45]
	v_mfma_f32_16x16x32_bf16 v[34:37], v[158:161], v[174:177], v[34:37]
	v_mfma_f32_16x16x32_bf16 v[26:29], v[142:145], v[182:185], v[26:29]
	v_mfma_f32_16x16x32_bf16 v[18:21], v[158:161], v[182:185], v[18:21]
	v_mfma_f32_16x16x32_bf16 v[10:13], v[142:145], v[190:193], v[10:13]
	v_mfma_f32_16x16x32_bf16 v[6:9], v[158:161], v[190:193], v[6:9]
	v_mfma_f32_16x16x32_bf16 v[58:61], v[146:149], v[170:173], v[58:61]
	v_mfma_f32_16x16x32_bf16 v[50:53], v[162:165], v[170:173], v[50:53]
	v_mfma_f32_16x16x32_bf16 v[42:45], v[146:149], v[178:181], v[42:45]
	v_mfma_f32_16x16x32_bf16 v[34:37], v[162:165], v[178:181], v[34:37]
	v_mfma_f32_16x16x32_bf16 v[26:29], v[146:149], v[186:189], v[26:29]
	v_mfma_f32_16x16x32_bf16 v[18:21], v[162:165], v[186:189], v[18:21]
	v_mfma_f32_16x16x32_bf16 v[10:13], v[146:149], v[194:197], v[10:13]
	v_mfma_f32_16x16x32_bf16 v[6:9], v[162:165], v[194:197], v[6:9]
	s_barrier
	s_setprio 0
	s_add_i32 s47, s47, 2
	s_add_u32 s33, s33, 0x100
	s_addc_u32 s44, s44, 0
	s_add_u32 s45, s45, 0x100
	s_addc_u32 s46, s46, 0
	s_cmp_gt_u32 s47, 61
	s_cbranch_scc0 .LBB0_924
	v_mov_b32_e32 v142, v0
	s_mov_b64 s[20:21], s[84:85]
	s_add_u32 s7, s20, 0x4179c000
	v_readlane_b32 s18, v254, 26
	s_addc_u32 s9, s21, 0
	v_readlane_b32 s19, v254, 27
	v_readlane_b32 s44, v253, 35
	s_and_b64 s[18:19], s[18:19], exec
	v_readlane_b32 s45, v253, 36
	v_bfe_u32 v144, v142, 4, 2
	s_cselect_b32 s23, s9, s45
	s_cselect_b32 s22, s7, s44
	s_cselect_b32 s19, s83, s9
	s_cselect_b32 s18, s82, s7
	s_lshl_b32 s7, s8, 8
	s_lshl_b32 s6, s6, 8
	v_lshl_or_b32 v78, v144, 3, s7
	s_add_i32 s6, s6, s39
	v_or_b32_e32 v226, s40, v78
	v_ashrrev_i32_e32 v227, 31, v226
	v_readlane_b32 s8, v254, 9
	v_and_or_b32 v230, v142, 15, s6
	v_lshlrev_b64 v[244:245], 2, v[226:227]
	v_readlane_b32 s9, v254, 10
	v_lshl_add_u64 v[142:143], v[226:227], 1, s[20:21]
	s_mov_b64 s[6:7], 0x10f80000
	v_ashrrev_i32_e32 v231, 31, v230
	v_or_b32_e32 v240, 16, v230
	v_lshl_add_u64 v[82:83], s[8:9], 0, v[244:245]
	v_lshl_add_u64 v[228:229], s[22:23], 0, v[244:245]
	v_lshl_add_u64 v[224:225], v[142:143], 0, s[6:7]
	v_lshl_add_u64 v[142:143], v[230:231], 2, s[20:21]
	s_mov_b64 s[8:9], 0x18400
	v_lshlrev_b64 v[248:249], 14, v[230:231]
	v_ashrrev_i32_e32 v241, 31, v240
	v_or_b32_e32 v236, 32, v230
	v_or_b32_e32 v232, 48, v230
	v_lshl_add_u64 v[222:223], v[142:143], 0, s[8:9]
	v_lshl_add_u64 v[142:143], v[228:229], 0, v[248:249]
	v_lshlrev_b64 v[242:243], 14, v[240:241]
	v_ashrrev_i32_e32 v237, 31, v236
	v_ashrrev_i32_e32 v233, 31, v232
	global_load_dwordx4 v[86:89], v[82:83], off offset:16
	global_load_dwordx4 v[90:93], v[82:83], off
	global_load_dwordx4 v[78:81], v[82:83], off offset:528
	s_nop 0
	global_load_dwordx4 v[82:85], v[82:83], off offset:512
	s_nop 0
	global_load_dwordx4 v[206:209], v[142:143], off offset:16
	global_load_dwordx4 v[210:213], v[142:143], off
	global_load_dwordx4 v[198:201], v[142:143], off offset:528
	global_load_dwordx4 v[202:205], v[142:143], off offset:512
	v_lshl_add_u64 v[142:143], v[228:229], 0, v[242:243]
	v_lshlrev_b64 v[238:239], 14, v[236:237]
	v_lshlrev_b64 v[234:235], 14, v[232:233]
	global_load_dwordx4 v[190:193], v[142:143], off offset:16
	global_load_dwordx4 v[194:197], v[142:143], off
	global_load_dwordx4 v[182:185], v[142:143], off offset:528
	global_load_dwordx4 v[186:189], v[142:143], off offset:512
	v_lshl_add_u64 v[142:143], v[228:229], 0, v[238:239]
	v_lshl_add_u64 v[146:147], v[228:229], 0, v[234:235]
	v_cmp_eq_u32_e64 s[6:7], 0, v144
	global_load_dwordx4 v[174:177], v[142:143], off offset:16
	global_load_dwordx4 v[178:181], v[142:143], off
	global_load_dwordx4 v[166:169], v[142:143], off offset:528
	global_load_dwordx4 v[170:173], v[142:143], off offset:512
	global_load_dwordx4 v[158:161], v[146:147], off offset:16
	global_load_dwordx4 v[162:165], v[146:147], off
	s_nop 0
	global_load_dwordx4 v[142:145], v[146:147], off offset:528
	s_nop 0
	global_load_dwordx4 v[146:149], v[146:147], off offset:512
	v_lshl_add_u64 v[248:249], s[18:19], 0, v[248:249]
	v_lshl_add_u64 v[244:245], v[248:249], 0, v[244:245]
	s_mov_b64 s[20:21], -1
	s_andn2_b64 vcc, exec, s[60:61]
	v_readlane_b32 s46, v253, 37
	v_readlane_b32 s47, v253, 38
	v_readlane_b32 s48, v253, 39
	v_readlane_b32 s49, v253, 40
	v_readlane_b32 s50, v253, 41
	v_readlane_b32 s51, v253, 42
	v_readlane_b32 s52, v253, 43
	v_readlane_b32 s53, v253, 44
	v_readlane_b32 s54, v253, 45
	v_readlane_b32 s55, v253, 46
	v_readlane_b32 s56, v253, 47
	v_readlane_b32 s57, v253, 48
	v_readlane_b32 s58, v253, 49
	v_readlane_b32 s59, v253, 50
	s_waitcnt vmcnt(0)
	v_pk_add_f32 v[206:207], v[150:151], v[206:207]
	v_cndmask_b32_e64 v150, 0, 1, s[60:61]
	v_pk_add_f32 v[212:213], v[156:157], v[212:213]
	v_pk_add_f32 v[210:211], v[154:155], v[210:211]
	v_pk_add_f32 v[208:209], v[152:153], v[208:209]
	v_cmp_ne_u32_e64 s[8:9], 1, v150
	v_pk_add_f32 v[150:151], v[138:139], v[202:203]
	v_pk_add_f32 v[154:155], v[130:131], v[198:199]
	global_store_dwordx4 v[244:245], v[210:213], off
	global_store_dwordx4 v[244:245], v[206:209], off offset:16
	s_cbranch_vccnz .LBB0_929
	v_mul_f32_e32 v138, v211, v211
	v_mul_f32_e32 v139, v213, v213
	v_fmac_f32_e32 v138, v210, v210
	v_fmac_f32_e32 v139, v212, v212
	v_add_f32_e32 v138, v138, v139
	v_mul_f32_e32 v139, v207, v207
	v_fmac_f32_e32 v139, v206, v206
	v_add_f32_e32 v138, v138, v139
	v_mul_f32_e32 v139, v209, v209
	v_lshlrev_b64 v[130:131], 12, v[230:231]
	v_fmac_f32_e32 v139, v208, v208
	v_pk_mul_f32 v[152:153], v[90:91], v[210:211]
	v_pk_mul_f32 v[156:157], v[88:89], v[208:209]
	v_lshl_add_u64 v[130:131], v[130:131], 1, v[224:225]
	v_add_f32_e32 v231, v139, v138
	v_pk_mul_f32 v[138:139], v[92:93], v[212:213]
	v_pk_mul_f32 v[198:199], v[86:87], v[206:207]
	v_cvt_pk_bf16_f32 v206, v152, v153
	v_cvt_pk_bf16_f32 v207, v138, v139
	v_pk_add_f32 v[152:153], v[140:141], v[204:205]
	v_cvt_pk_bf16_f32 v208, v198, v199
	v_cvt_pk_bf16_f32 v209, v156, v157
	v_pk_add_f32 v[156:157], v[132:133], v[200:201]
	global_store_dwordx4 v[130:131], v[206:209], off
	global_store_dwordx4 v[244:245], v[150:153], off offset:512
	global_store_dwordx4 v[244:245], v[154:157], off offset:528
	v_pk_mul_f32 v[202:203], v[80:81], v[156:157]
	v_pk_mul_f32 v[138:139], v[84:85], v[152:153]
	v_mul_f32_e32 v157, v157, v157
	v_fmac_f32_e32 v157, v156, v156
	v_mul_f32_e32 v156, v151, v151
	v_mul_f32_e32 v153, v153, v153
	v_fmac_f32_e32 v156, v150, v150
	v_fmac_f32_e32 v153, v152, v152
	v_add_f32_e32 v152, v156, v153
	v_mul_f32_e32 v153, v155, v155
	v_fmac_f32_e32 v153, v154, v154
	v_add_f32_e32 v152, v152, v153
	v_add_f32_e32 v152, v157, v152
	v_add_f32_e32 v152, v231, v152
	ds_swizzle_b32 v153, v152 offset:swizzle(SWAP,16)
	v_pk_mul_f32 v[208:209], v[78:79], v[154:155]
	v_pk_mul_f32 v[198:199], v[82:83], v[150:151]
	s_nop 0
	v_cvt_pk_bf16_f32 v206, v198, v199
	v_cvt_pk_bf16_f32 v207, v138, v139
	v_cvt_pk_bf16_f32 v208, v208, v209
	v_cvt_pk_bf16_f32 v209, v202, v203
	global_store_dwordx4 v[130:131], v[206:209], off offset:256
	s_waitcnt lgkmcnt(0)
	v_add_f32_e32 v130, v152, v153
	v_mov_b32_e32 v131, v130
	s_nop 1
	v_permlane32_swap_b32_e32 v130, v131
	s_and_saveexec_b64 s[20:21], s[6:7]
	s_cbranch_execz .LBB0_928
	v_add_f32_e32 v130, v130, v131
	global_atomic_add_f32 v[222:223], v130, off
